# gelu epilogue instruction selection: two successive constant multiplies folded into one (258 sites)
# baseline (speedup 1.0000x reference)
; DI void s5_sample_unit(const Params& p, int u, const float* uss, bf16_t* z, int lane) {
;     ...
;     for (int t = 0; t < 4; ++t) {
;         const float* ur = uss + (size_t)(b * 4 + t) * 512 + g * 16;
;         float bur = 0.f, bui = 0.f;
; #pragma unroll
;         for (int i = 0; i < 16; ++i) { const float uv = ur[i]; const float br = bre[i], bi = bim[i]; bur += (fr_ * br - fi_ * bi) * uv; bui += (fr_ * bi + fi_ * br) * uv; }
;         const float n_r = lbr * hr - lbi * hi + bur, n_i = lbr * hi + lbi * hr + bui; hr = n_r; hi = n_i;
;         float yv = 0.f;
; #pragma unroll
;         for (int i = 0; i < 16; ++i) { float a = cre[i * 64] * hr - cim[i * 64] * hi; a = wave_sum(a); if (lane == i) yv = a; }
.LBB0_365:
	v_readlane_b32 s74, v254, 0
	v_readlane_b32 s75, v254, 1
	s_load_dwordx2 s[74:75], s[74:75], 0xd8
	s_waitcnt vmcnt(32) lgkmcnt(0)
	v_pk_mul_f32 v[120:121], v[24:25], v[36:37] op_sel:[0,1] op_sel_hi:[1,0]
	s_waitcnt lgkmcnt(0)
	s_add_u32 s74, s74, s72
	s_addc_u32 s75, s75, s73
	global_load_dwordx4 v[104:107], v71, s[74:75]
	s_add_u32 s84, s74, 0x3c00000
	s_addc_u32 s85, s75, 0
	global_load_dwordx4 v[108:111], v70, s[84:85] offset:16
	global_load_dwordx4 v[112:115], v70, s[84:85] offset:32
	global_load_dwordx4 v[116:119], v70, s[84:85] offset:48
	v_pk_fma_f32 v[122:123], v[26:27], v[36:37], v[120:121] neg_lo:[0,0,1] neg_hi:[0,0,1]
	v_pk_fma_f32 v[36:37], v[26:27], v[36:37], v[120:121]
	s_waitcnt vmcnt(3)
	v_mov_b32_e32 v120, v107
	v_mov_b32_e32 v123, v37
	v_pk_fma_f32 v[36:37], v[32:33], v[104:105], 0 op_sel_hi:[1,0,0]
	s_waitcnt vmcnt(2)
	v_mov_b32_e32 v124, v111
	v_pk_fma_f32 v[36:37], v[34:35], v[104:105], v[36:37] op_sel:[0,1,0]
	s_waitcnt vmcnt(1)
	v_mov_b32_e32 v126, v115
	v_pk_fma_f32 v[36:37], v[38:39], v[106:107], v[36:37] op_sel_hi:[1,0,1]
	s_waitcnt vmcnt(0)
	v_mov_b32_e32 v128, v119
	v_pk_fma_f32 v[36:37], v[40:41], v[120:121], v[36:37] op_sel_hi:[1,0,1]
	s_nop 0
	v_pk_fma_f32 v[36:37], v[42:43], v[108:109], v[36:37] op_sel_hi:[1,0,1]
	s_nop 0
	v_pk_fma_f32 v[36:37], v[4:5], v[108:109], v[36:37] op_sel:[0,1,0]
	s_nop 0
	v_pk_fma_f32 v[36:37], v[0:1], v[110:111], v[36:37] op_sel_hi:[1,0,1]
	s_nop 0
	v_pk_fma_f32 v[36:37], v[2:3], v[124:125], v[36:37] op_sel_hi:[1,0,1]
	s_nop 0
	v_pk_fma_f32 v[36:37], v[6:7], v[112:113], v[36:37] op_sel_hi:[1,0,1]
	s_nop 0
	v_pk_fma_f32 v[36:37], v[44:45], v[112:113], v[36:37] op_sel:[0,1,0]
	s_nop 0
	v_pk_fma_f32 v[36:37], v[46:47], v[114:115], v[36:37] op_sel_hi:[1,0,1]
	s_nop 0
	v_pk_fma_f32 v[36:37], v[48:49], v[126:127], v[36:37] op_sel_hi:[1,0,1]
	s_nop 0
	v_pk_fma_f32 v[36:37], v[50:51], v[116:117], v[36:37] op_sel_hi:[1,0,1]
	s_nop 0
	v_pk_fma_f32 v[36:37], v[52:53], v[116:117], v[36:37] op_sel:[0,1,0]
	s_nop 0
	v_pk_fma_f32 v[36:37], v[54:55], v[118:119], v[36:37] op_sel_hi:[1,0,1]
	s_nop 0
	v_pk_fma_f32 v[36:37], v[56:57], v[128:129], v[36:37] op_sel_hi:[1,0,1]
	s_nop 0
	v_pk_add_f32 v[36:37], v[122:123], v[36:37]
	s_nop 0
	v_mul_f32_e32 v110, v86, v37
	v_mul_f32_e32 v111, v87, v37
	v_mul_f32_e32 v112, v96, v37
	v_fma_f32 v110, v78, v36, -v110
	v_fma_f32 v111, v79, v36, -v111
	v_fma_f32 v118, v88, v36, -v112
	v_mul_f32_e32 v113, v97, v37
	ds_bpermute_b32 v120, v62, v110
	ds_bpermute_b32 v121, v62, v111
	ds_bpermute_b32 v122, v62, v118
	v_fma_f32 v119, v89, v36, -v113
	ds_bpermute_b32 v123, v62, v119
	s_waitcnt lgkmcnt(3)
	v_add_f32_e32 v110, v110, v120
	s_waitcnt lgkmcnt(2)
	v_add_f32_e32 v120, v111, v121
	s_waitcnt lgkmcnt(1)
	v_add_f32_e32 v118, v118, v122
	ds_bpermute_b32 v121, v63, v120
	ds_bpermute_b32 v122, v63, v118
	s_waitcnt lgkmcnt(2)
	v_add_f32_e32 v119, v119, v123
	ds_bpermute_b32 v123, v63, v119
	v_mul_f32_e32 v104, v80, v37
	s_waitcnt lgkmcnt(2)
	v_add_f32_e32 v120, v120, v121
	s_waitcnt lgkmcnt(1)
	v_add_f32_e32 v118, v118, v122
	ds_bpermute_b32 v121, v66, v120
	ds_bpermute_b32 v122, v66, v118
	s_waitcnt lgkmcnt(2)
	v_add_f32_e32 v119, v119, v123
	ds_bpermute_b32 v123, v66, v119
	v_mul_f32_e32 v105, v81, v37
	s_waitcnt lgkmcnt(2)
	v_add_f32_e32 v120, v120, v121
	s_waitcnt lgkmcnt(1)
	v_add_f32_e32 v118, v118, v122
	ds_bpermute_b32 v121, v67, v120
	ds_bpermute_b32 v122, v67, v118
	s_waitcnt lgkmcnt(2)
	v_add_f32_e32 v119, v119, v123
	ds_bpermute_b32 v123, v67, v119
	v_mul_f32_e32 v106, v82, v37
	s_waitcnt lgkmcnt(2)
	v_add_f32_e32 v120, v120, v121
	s_waitcnt lgkmcnt(1)
	v_add_f32_e32 v122, v118, v122
	ds_bpermute_b32 v121, v68, v120
	ds_bpermute_b32 v124, v68, v122
	s_waitcnt lgkmcnt(2)
	v_add_f32_e32 v123, v119, v123
	ds_bpermute_b32 v125, v68, v123
	v_mul_f32_e32 v107, v83, v37
	v_mul_f32_e32 v108, v84, v37
	v_mul_f32_e32 v109, v85, v37
	s_waitcnt lgkmcnt(2)
	v_add_f32_e32 v118, v120, v121
	s_waitcnt lgkmcnt(1)
	v_add_f32_e32 v120, v122, v124
	v_mul_f32_e32 v124, v98, v37
	v_mul_f32_e32 v126, v99, v37
	v_mul_f32_e32 v128, v100, v37
	v_mul_f32_e32 v130, v101, v37
	v_mul_f32_e32 v132, v102, v37
	v_mul_f32_e32 v134, v103, v37
	v_fma_f32 v104, v21, v36, -v104
	v_fma_f32 v105, v23, v36, -v105
	v_fma_f32 v106, v74, v36, -v106
	v_fma_f32 v107, v75, v36, -v107
	v_fma_f32 v108, v76, v36, -v108
	v_fma_f32 v109, v77, v36, -v109
	v_fma_f32 v124, v90, v36, -v124
	v_fma_f32 v126, v91, v36, -v126
	v_fma_f32 v128, v92, v36, -v128
	v_fma_f32 v130, v93, v36, -v130
	v_fma_f32 v132, v94, v36, -v132
	v_fma_f32 v134, v95, v36, -v134
	ds_bpermute_b32 v112, v62, v104
	ds_bpermute_b32 v113, v62, v105
	ds_bpermute_b32 v114, v62, v106
	ds_bpermute_b32 v115, v62, v107
	ds_bpermute_b32 v116, v62, v108
	ds_bpermute_b32 v117, v62, v109
	s_waitcnt lgkmcnt(6)
	v_add_f32_e32 v122, v123, v125
	ds_bpermute_b32 v125, v62, v124
	ds_bpermute_b32 v127, v62, v126
	ds_bpermute_b32 v129, v62, v128
	ds_bpermute_b32 v131, v62, v130
	ds_bpermute_b32 v133, v62, v132
	ds_bpermute_b32 v135, v62, v134
	s_waitcnt lgkmcnt(11)
	v_add_f32_e32 v104, v104, v112
	s_waitcnt lgkmcnt(10)
	v_add_f32_e32 v105, v105, v113
	s_waitcnt lgkmcnt(9)
	v_add_f32_e32 v106, v106, v114
	s_waitcnt lgkmcnt(8)
	v_add_f32_e32 v107, v107, v115
	s_waitcnt lgkmcnt(7)
	v_add_f32_e32 v108, v108, v116
	s_waitcnt lgkmcnt(6)
	v_add_f32_e32 v109, v109, v117
	s_waitcnt lgkmcnt(5)
	v_add_f32_e32 v124, v124, v125
	s_waitcnt lgkmcnt(4)
	v_add_f32_e32 v126, v126, v127
	s_waitcnt lgkmcnt(3)
	v_add_f32_e32 v128, v128, v129
	s_waitcnt lgkmcnt(2)
	v_add_f32_e32 v130, v130, v131
	s_waitcnt lgkmcnt(1)
	v_add_f32_e32 v132, v132, v133
	s_waitcnt lgkmcnt(0)
; DI void s5_sample_unit(const Params& p, int u, const float* uss, bf16_t* z, int lane) {
;     ...
;         for (int i = 0; i < 16; ++i) { float a = cre[i * 64] * hr - cim[i * 64] * hi; a = wave_sum(a); if (lane == i) yv = a; }
	v_add_f32_e32 v134, v134, v135
	ds_bpermute_b32 v111, v63, v104
	ds_bpermute_b32 v112, v63, v105
	ds_bpermute_b32 v113, v63, v106
	ds_bpermute_b32 v114, v63, v107
	ds_bpermute_b32 v115, v63, v108
	ds_bpermute_b32 v116, v63, v109
	ds_bpermute_b32 v117, v63, v110
	ds_bpermute_b32 v125, v63, v124
	ds_bpermute_b32 v127, v63, v126
	ds_bpermute_b32 v129, v63, v128
	ds_bpermute_b32 v131, v63, v130
	ds_bpermute_b32 v133, v63, v132
	ds_bpermute_b32 v135, v63, v134
	s_waitcnt lgkmcnt(12)
	v_add_f32_e32 v104, v104, v111
	s_waitcnt lgkmcnt(11)
	v_add_f32_e32 v105, v105, v112
	s_waitcnt lgkmcnt(10)
	v_add_f32_e32 v106, v106, v113
	s_waitcnt lgkmcnt(9)
	v_add_f32_e32 v107, v107, v114
	s_waitcnt lgkmcnt(8)
	v_add_f32_e32 v108, v108, v115
	s_waitcnt lgkmcnt(7)
	v_add_f32_e32 v109, v109, v116
	s_waitcnt lgkmcnt(6)
	v_add_f32_e32 v110, v110, v117
	s_waitcnt lgkmcnt(5)
	v_add_f32_e32 v124, v124, v125
	s_waitcnt lgkmcnt(4)
	v_add_f32_e32 v126, v126, v127
	s_waitcnt lgkmcnt(3)
	v_add_f32_e32 v128, v128, v129
	s_waitcnt lgkmcnt(2)
	v_add_f32_e32 v130, v130, v131
	s_waitcnt lgkmcnt(1)
	v_add_f32_e32 v132, v132, v133
	s_waitcnt lgkmcnt(0)
	v_add_f32_e32 v134, v134, v135
	ds_bpermute_b32 v111, v66, v104
	ds_bpermute_b32 v112, v66, v105
	ds_bpermute_b32 v113, v66, v106
	ds_bpermute_b32 v114, v66, v107
	ds_bpermute_b32 v115, v66, v108
	ds_bpermute_b32 v116, v66, v109
	ds_bpermute_b32 v117, v66, v110
	ds_bpermute_b32 v125, v66, v124
	ds_bpermute_b32 v127, v66, v126
	ds_bpermute_b32 v129, v66, v128
	ds_bpermute_b32 v131, v66, v130
	ds_bpermute_b32 v133, v66, v132
	ds_bpermute_b32 v135, v66, v134
	s_waitcnt lgkmcnt(12)
	v_add_f32_e32 v104, v104, v111
	s_waitcnt lgkmcnt(11)
	v_add_f32_e32 v105, v105, v112
	s_waitcnt lgkmcnt(10)
	v_add_f32_e32 v106, v106, v113
	s_waitcnt lgkmcnt(9)
	v_add_f32_e32 v107, v107, v114
	s_waitcnt lgkmcnt(8)
	v_add_f32_e32 v108, v108, v115
	s_waitcnt lgkmcnt(7)
	v_add_f32_e32 v109, v109, v116
	s_waitcnt lgkmcnt(6)
	v_add_f32_e32 v110, v110, v117
	s_waitcnt lgkmcnt(5)
	v_add_f32_e32 v124, v124, v125
	s_waitcnt lgkmcnt(4)
	v_add_f32_e32 v126, v126, v127
	s_waitcnt lgkmcnt(3)
	v_add_f32_e32 v128, v128, v129
	s_waitcnt lgkmcnt(2)
	v_add_f32_e32 v130, v130, v131
	s_waitcnt lgkmcnt(1)
	v_add_f32_e32 v132, v132, v133
	s_waitcnt lgkmcnt(0)
	v_add_f32_e32 v134, v134, v135
	ds_bpermute_b32 v111, v67, v104
	ds_bpermute_b32 v112, v67, v105
	ds_bpermute_b32 v113, v67, v106
	ds_bpermute_b32 v114, v67, v107
	ds_bpermute_b32 v115, v67, v108
	ds_bpermute_b32 v116, v67, v109
	ds_bpermute_b32 v117, v67, v110
	ds_bpermute_b32 v125, v67, v124
	ds_bpermute_b32 v127, v67, v126
	ds_bpermute_b32 v129, v67, v128
	ds_bpermute_b32 v131, v67, v130
	ds_bpermute_b32 v133, v67, v132
	ds_bpermute_b32 v135, v67, v134
	s_waitcnt lgkmcnt(12)
	v_add_f32_e32 v104, v104, v111
	s_waitcnt lgkmcnt(11)
	v_add_f32_e32 v105, v105, v112
	s_waitcnt lgkmcnt(10)
	v_add_f32_e32 v106, v106, v113
	s_waitcnt lgkmcnt(9)
	v_add_f32_e32 v107, v107, v114
	s_waitcnt lgkmcnt(8)
	v_add_f32_e32 v108, v108, v115
	s_waitcnt lgkmcnt(7)
	v_add_f32_e32 v111, v109, v116
	s_waitcnt lgkmcnt(6)
	v_add_f32_e32 v110, v110, v117
	s_waitcnt lgkmcnt(5)
	v_add_f32_e32 v124, v124, v125
	s_waitcnt lgkmcnt(4)
	v_add_f32_e32 v126, v126, v127
	s_waitcnt lgkmcnt(3)
	v_add_f32_e32 v128, v128, v129
	s_waitcnt lgkmcnt(2)
	v_add_f32_e32 v130, v130, v131
	s_waitcnt lgkmcnt(1)
	v_add_f32_e32 v132, v132, v133
	s_waitcnt lgkmcnt(0)
	v_add_f32_e32 v134, v134, v135
	ds_bpermute_b32 v109, v68, v104
	ds_bpermute_b32 v112, v68, v105
	ds_bpermute_b32 v113, v68, v106
	ds_bpermute_b32 v114, v68, v107
	ds_bpermute_b32 v115, v68, v108
	ds_bpermute_b32 v116, v68, v111
	ds_bpermute_b32 v117, v68, v110
	ds_bpermute_b32 v125, v68, v124
	ds_bpermute_b32 v127, v68, v126
	ds_bpermute_b32 v129, v68, v128
	ds_bpermute_b32 v131, v68, v130
	ds_bpermute_b32 v133, v68, v132
	ds_bpermute_b32 v135, v68, v134
	s_waitcnt lgkmcnt(12)
	v_add_f32_e32 v104, v104, v109
	s_waitcnt lgkmcnt(11)
	v_add_f32_e32 v105, v105, v112
	s_waitcnt lgkmcnt(10)
	v_add_f32_e32 v106, v106, v113
	s_waitcnt lgkmcnt(9)
	v_add_f32_e32 v107, v107, v114
	s_waitcnt lgkmcnt(8)
	v_add_f32_e32 v109, v108, v115
	s_waitcnt lgkmcnt(7)
	v_add_f32_e32 v111, v111, v116
	s_waitcnt lgkmcnt(6)
	v_add_f32_e32 v113, v110, v117
	s_waitcnt lgkmcnt(5)
	v_add_f32_e32 v124, v124, v125
	s_waitcnt lgkmcnt(4)
	v_add_f32_e32 v126, v126, v127
	s_waitcnt lgkmcnt(3)
	v_add_f32_e32 v128, v128, v129
	s_waitcnt lgkmcnt(2)
	v_add_f32_e32 v130, v130, v131
	s_waitcnt lgkmcnt(1)
	v_add_f32_e32 v132, v132, v133
	s_waitcnt lgkmcnt(0)
	v_add_f32_e32 v134, v134, v135
	ds_bpermute_b32 v108, v69, v104
	ds_bpermute_b32 v110, v69, v105
	ds_bpermute_b32 v112, v69, v106
	ds_bpermute_b32 v114, v69, v107
	ds_bpermute_b32 v115, v69, v109
	ds_bpermute_b32 v116, v69, v111
	ds_bpermute_b32 v117, v69, v113
	ds_bpermute_b32 v119, v69, v118
	ds_bpermute_b32 v121, v69, v120
	ds_bpermute_b32 v123, v69, v122
	ds_bpermute_b32 v125, v69, v124
	ds_bpermute_b32 v127, v69, v126
	ds_bpermute_b32 v129, v69, v128
	ds_bpermute_b32 v131, v69, v130
	ds_bpermute_b32 v133, v69, v132
	ds_bpermute_b32 v135, v69, v134
	s_and_saveexec_b64 s[74:75], s[6:7]
	s_cbranch_execz .LBB0_364
; DI float gelu_tanh(float y) { const float u = 0.7978845608028654f * (y + 0.044715f * y * y * y); return y * __builtin_amdgcn_rcpf(1.0f + __builtin_amdgcn_exp2f(-2.0f * 1.4426950408889634f * u)); }
; DI void s5_sample_unit(const Params& p, int u, const float* uss, bf16_t* z, int lane) {
;     ...
;         for (int i = 0; i < 16; ++i) { float a = cre[i * 64] * hr - cim[i * 64] * hi; a = wave_sum(a); if (lane == i) yv = a; }
;         if (lane < 16) { const float y = yv + p.in[17][g * 16 + lane] * ur[lane]; z[(size_t)(NP + b * 4 + t) * 512 + g * 16 + lane] = (bf16_t)(pk2(gelu_tanh(y), 0.f) & 0xffffu); }
	v_readlane_b32 s84, v254, 0
	v_readlane_b32 s85, v254, 1
	s_load_dwordx2 s[84:85], s[84:85], 0xd8
	global_load_dword v138, v[30:31], off
	s_waitcnt lgkmcnt(0)
	v_add_f32_e32 v104, v104, v108
	v_add_f32_e32 v105, v105, v110
	v_cndmask_b32_e64 v104, 0, v104, s[40:41]
	v_lshl_add_u64 v[136:137], s[84:85], 0, v[60:61]
	global_load_dword v136, v[136:137], off
	v_add_f32_e32 v106, v106, v112
	v_cndmask_b32_e64 v104, v104, v105, s[38:39]
	v_add_f32_e32 v107, v107, v114
	v_cndmask_b32_e64 v104, v104, v106, s[36:37]
	v_add_f32_e32 v109, v109, v115
	v_cndmask_b32_e64 v104, v104, v107, s[34:35]
	v_add_f32_e32 v111, v111, v116
	v_cndmask_b32_e64 v104, v104, v109, s[30:31]
	v_add_f32_e32 v113, v113, v117
	v_cndmask_b32_e64 v104, v104, v111, s[28:29]
	v_add_f32_e32 v118, v118, v119
	v_cndmask_b32_e64 v104, v104, v113, s[26:27]
	v_add_f32_e32 v120, v120, v121
	v_cndmask_b32_e64 v104, v104, v118, s[24:25]
	v_add_f32_e32 v122, v122, v123
	v_cndmask_b32_e64 v104, v104, v120, s[22:23]
	v_add_f32_e32 v124, v124, v125
	v_cndmask_b32_e64 v104, v104, v122, s[20:21]
	v_add_f32_e32 v126, v126, v127
	v_cndmask_b32_e64 v104, v104, v124, s[18:19]
	v_add_f32_e32 v128, v128, v129
	v_cndmask_b32_e64 v104, v104, v126, s[16:17]
	v_add_f32_e32 v130, v130, v131
	v_cndmask_b32_e64 v104, v104, v128, s[14:15]
	v_add_f32_e32 v132, v132, v133
	v_cndmask_b32_e64 v104, v104, v130, s[12:13]
	v_add_f32_e32 v134, v134, v135
	v_cndmask_b32_e64 v104, v104, v132, s[10:11]
	v_cndmask_b32_e64 v104, v104, v134, s[8:9]
	s_waitcnt vmcnt(0)
	v_fmac_f32_e32 v104, v138, v136
	v_mul_f32_e32 v105, 0x3d372713, v104
	v_mul_f32_e32 v105, v104, v105
	v_fma_f32 v105, v104, v105, v104
	v_mul_f32_e32 v105, 0xc0135761, v105
	v_exp_f32_e32 v105, v105
	s_nop 0
	v_add_f32_e32 v105, 1.0, v105
	v_rcp_f32_e32 v105, v105
	s_nop 0
	v_mul_f32_e32 v104, v104, v105
	v_cvt_pk_bf16_f32 v106, v104, s0
	v_lshl_add_u64 v[104:105], s[84:85], 0, v[58:59]
	global_store_short v[104:105], v106, off
	s_branch .LBB0_364

; DI void s5_sample_unit(const Params& p, int u, const float* uss, bf16_t* z, int lane) {
;     ...
;     for (int t = 0; t < 4; ++t) {
;         const float* ur = uss + (size_t)(b * 4 + t) * 512 + g * 16;
;         float bur = 0.f, bui = 0.f;
; #pragma unroll
;         for (int i = 0; i < 16; ++i) { const float uv = ur[i]; const float br = bre[i], bi = bim[i]; bur += (fr_ * br - fi_ * bi) * uv; bui += (fr_ * bi + fi_ * br) * uv; }
;         const float n_r = lbr * hr - lbi * hi + bur, n_i = lbr * hi + lbi * hr + bui; hr = n_r; hi = n_i;
;         float yv = 0.f;
; #pragma unroll
;         for (int i = 0; i < 16; ++i) { float a = cre[i * 64] * hr - cim[i * 64] * hi; a = wave_sum(a); if (lane == i) yv = a; }
.LBB0_380:
	s_waitcnt lgkmcnt(0)
	s_add_u32 s48, s90, s40
	s_addc_u32 s49, s91, s41
	global_load_dwordx4 v[88:91], v65, s[48:49]
	s_add_u32 s50, s48, 0x3c00000
	s_addc_u32 s51, s49, 0
	global_load_dwordx4 v[92:95], v1, s[50:51] offset:16
	global_load_dwordx4 v[96:99], v1, s[50:51] offset:32
	global_load_dwordx4 v[100:103], v1, s[50:51] offset:48
	s_waitcnt vmcnt(36)
	v_pk_mul_f32 v[104:105], v[2:3], v[16:17] op_sel:[0,1] op_sel_hi:[1,0]
	s_waitcnt vmcnt(2)
	v_mov_b32_e32 v108, v95
	v_pk_fma_f32 v[106:107], v[4:5], v[16:17], v[104:105] neg_lo:[0,0,1] neg_hi:[0,0,1]
	v_pk_fma_f32 v[16:17], v[4:5], v[16:17], v[104:105]
	v_mov_b32_e32 v104, v91
	v_mov_b32_e32 v107, v17
	v_pk_fma_f32 v[16:17], v[10:11], v[88:89], 0 op_sel_hi:[1,0,0]
	s_waitcnt vmcnt(1)
	v_mov_b32_e32 v110, v99
	v_pk_fma_f32 v[16:17], v[12:13], v[88:89], v[16:17] op_sel:[0,1,0]
	s_waitcnt vmcnt(0)
	v_mov_b32_e32 v112, v103
	v_pk_fma_f32 v[16:17], v[14:15], v[90:91], v[16:17] op_sel_hi:[1,0,1]
	s_nop 0
	v_pk_fma_f32 v[16:17], v[18:19], v[104:105], v[16:17] op_sel_hi:[1,0,1]
	s_nop 0
	v_pk_fma_f32 v[16:17], v[20:21], v[92:93], v[16:17] op_sel_hi:[1,0,1]
	s_nop 0
	v_pk_fma_f32 v[16:17], v[22:23], v[92:93], v[16:17] op_sel:[0,1,0]
	s_nop 0
	v_pk_fma_f32 v[16:17], v[24:25], v[94:95], v[16:17] op_sel_hi:[1,0,1]
	s_nop 0
	v_pk_fma_f32 v[16:17], v[26:27], v[108:109], v[16:17] op_sel_hi:[1,0,1]
	s_nop 0
	v_pk_fma_f32 v[16:17], v[28:29], v[96:97], v[16:17] op_sel_hi:[1,0,1]
	s_nop 0
	v_pk_fma_f32 v[16:17], v[30:31], v[96:97], v[16:17] op_sel:[0,1,0]
	s_nop 0
	v_pk_fma_f32 v[16:17], v[32:33], v[98:99], v[16:17] op_sel_hi:[1,0,1]
	s_nop 0
	v_pk_fma_f32 v[16:17], v[34:35], v[110:111], v[16:17] op_sel_hi:[1,0,1]
	s_nop 0
	v_pk_fma_f32 v[16:17], v[36:37], v[100:101], v[16:17] op_sel_hi:[1,0,1]
	s_nop 0
	v_pk_fma_f32 v[16:17], v[38:39], v[100:101], v[16:17] op_sel:[0,1,0]
	s_nop 0
	v_pk_fma_f32 v[16:17], v[40:41], v[102:103], v[16:17] op_sel_hi:[1,0,1]
	s_nop 0
	v_pk_fma_f32 v[16:17], v[42:43], v[112:113], v[16:17] op_sel_hi:[1,0,1]
	s_nop 0
	v_pk_add_f32 v[16:17], v[106:107], v[16:17]
	s_nop 0
	v_mul_f32_e32 v93, v69, v17
	v_mul_f32_e32 v94, v70, v17
	v_mul_f32_e32 v95, v79, v17
	v_fma_f32 v93, v59, v16, -v93
	v_fma_f32 v94, v60, v16, -v94
	v_fma_f32 v101, v71, v16, -v95
	v_mul_f32_e32 v96, v80, v17
	ds_bpermute_b32 v103, v0, v93
	ds_bpermute_b32 v104, v0, v94
	ds_bpermute_b32 v105, v0, v101
	v_fma_f32 v102, v72, v16, -v96
	ds_bpermute_b32 v106, v0, v102
	s_waitcnt lgkmcnt(3)
	v_add_f32_e32 v93, v93, v103
	s_waitcnt lgkmcnt(2)
	v_add_f32_e32 v103, v94, v104
	s_waitcnt lgkmcnt(1)
	v_add_f32_e32 v101, v101, v105
	ds_bpermute_b32 v104, v48, v103
	ds_bpermute_b32 v105, v48, v101
	s_waitcnt lgkmcnt(2)
	v_add_f32_e32 v102, v102, v106
	ds_bpermute_b32 v106, v48, v102
	v_mul_f32_e32 v87, v61, v17
	s_waitcnt lgkmcnt(2)
	v_add_f32_e32 v103, v103, v104
	s_waitcnt lgkmcnt(1)
	v_add_f32_e32 v101, v101, v105
	ds_bpermute_b32 v104, v49, v103
	ds_bpermute_b32 v105, v49, v101
	s_waitcnt lgkmcnt(2)
	v_add_f32_e32 v102, v102, v106
	ds_bpermute_b32 v106, v49, v102
	v_mul_f32_e32 v88, v62, v17
	s_waitcnt lgkmcnt(2)
	v_add_f32_e32 v103, v103, v104
	s_waitcnt lgkmcnt(1)
	v_add_f32_e32 v101, v101, v105
	ds_bpermute_b32 v104, v50, v103
	ds_bpermute_b32 v105, v50, v101
	s_waitcnt lgkmcnt(2)
	v_add_f32_e32 v102, v102, v106
	ds_bpermute_b32 v106, v50, v102
	v_mul_f32_e32 v89, v63, v17
	s_waitcnt lgkmcnt(2)
	v_add_f32_e32 v103, v103, v104
	s_waitcnt lgkmcnt(1)
	v_add_f32_e32 v105, v101, v105
	ds_bpermute_b32 v104, v51, v103
	ds_bpermute_b32 v107, v51, v105
	s_waitcnt lgkmcnt(2)
	v_add_f32_e32 v106, v102, v106
	ds_bpermute_b32 v108, v51, v106
	v_mul_f32_e32 v90, v66, v17
	v_mul_f32_e32 v91, v67, v17
	v_mul_f32_e32 v92, v68, v17
	s_waitcnt lgkmcnt(2)
	v_add_f32_e32 v101, v103, v104
	s_waitcnt lgkmcnt(1)
	v_add_f32_e32 v103, v105, v107
	v_mul_f32_e32 v107, v81, v17
	v_mul_f32_e32 v109, v82, v17
	v_mul_f32_e32 v111, v83, v17
	v_mul_f32_e32 v113, v84, v17
	v_mul_f32_e32 v115, v85, v17
	v_mul_f32_e32 v117, v86, v17
	v_fma_f32 v87, v53, v16, -v87
	v_fma_f32 v88, v54, v16, -v88
	v_fma_f32 v89, v55, v16, -v89
	v_fma_f32 v90, v56, v16, -v90
	v_fma_f32 v91, v57, v16, -v91
	v_fma_f32 v92, v58, v16, -v92
	v_fma_f32 v107, v73, v16, -v107
	v_fma_f32 v109, v74, v16, -v109
	v_fma_f32 v111, v75, v16, -v111
	v_fma_f32 v113, v76, v16, -v113
	v_fma_f32 v115, v77, v16, -v115
	v_fma_f32 v117, v78, v16, -v117
	ds_bpermute_b32 v95, v0, v87
	ds_bpermute_b32 v96, v0, v88
	ds_bpermute_b32 v97, v0, v89
	ds_bpermute_b32 v98, v0, v90
	ds_bpermute_b32 v99, v0, v91
	ds_bpermute_b32 v100, v0, v92
	s_waitcnt lgkmcnt(6)
	v_add_f32_e32 v105, v106, v108
	ds_bpermute_b32 v108, v0, v107
	ds_bpermute_b32 v110, v0, v109
	ds_bpermute_b32 v112, v0, v111
	ds_bpermute_b32 v114, v0, v113
	ds_bpermute_b32 v116, v0, v115
	ds_bpermute_b32 v118, v0, v117
	s_waitcnt lgkmcnt(11)
	v_add_f32_e32 v87, v87, v95
	s_waitcnt lgkmcnt(10)
	v_add_f32_e32 v88, v88, v96
	s_waitcnt lgkmcnt(9)
	v_add_f32_e32 v89, v89, v97
	s_waitcnt lgkmcnt(8)
	v_add_f32_e32 v90, v90, v98
	s_waitcnt lgkmcnt(7)
	v_add_f32_e32 v91, v91, v99
	s_waitcnt lgkmcnt(6)
	v_add_f32_e32 v92, v92, v100
	s_waitcnt lgkmcnt(5)
	v_add_f32_e32 v107, v107, v108
	s_waitcnt lgkmcnt(4)
	v_add_f32_e32 v109, v109, v110
	s_waitcnt lgkmcnt(3)
	v_add_f32_e32 v111, v111, v112
	s_waitcnt lgkmcnt(2)
	v_add_f32_e32 v113, v113, v114
	s_waitcnt lgkmcnt(1)
	v_add_f32_e32 v115, v115, v116
	s_waitcnt lgkmcnt(0)
; DI void s5_sample_unit(const Params& p, int u, const float* uss, bf16_t* z, int lane) {
;     ...
;         for (int i = 0; i < 16; ++i) { float a = cre[i * 64] * hr - cim[i * 64] * hi; a = wave_sum(a); if (lane == i) yv = a; }
	v_add_f32_e32 v117, v117, v118
	ds_bpermute_b32 v94, v48, v87
	ds_bpermute_b32 v95, v48, v88
	ds_bpermute_b32 v96, v48, v89
	ds_bpermute_b32 v97, v48, v90
	ds_bpermute_b32 v98, v48, v91
	ds_bpermute_b32 v99, v48, v92
	ds_bpermute_b32 v100, v48, v93
	ds_bpermute_b32 v108, v48, v107
	ds_bpermute_b32 v110, v48, v109
	ds_bpermute_b32 v112, v48, v111
	ds_bpermute_b32 v114, v48, v113
	ds_bpermute_b32 v116, v48, v115
	ds_bpermute_b32 v118, v48, v117
	s_waitcnt lgkmcnt(12)
	v_add_f32_e32 v87, v87, v94
	s_waitcnt lgkmcnt(11)
	v_add_f32_e32 v88, v88, v95
	s_waitcnt lgkmcnt(10)
	v_add_f32_e32 v89, v89, v96
	s_waitcnt lgkmcnt(9)
	v_add_f32_e32 v90, v90, v97
	s_waitcnt lgkmcnt(8)
	v_add_f32_e32 v91, v91, v98
	s_waitcnt lgkmcnt(7)
	v_add_f32_e32 v92, v92, v99
	s_waitcnt lgkmcnt(6)
	v_add_f32_e32 v93, v93, v100
	s_waitcnt lgkmcnt(5)
	v_add_f32_e32 v107, v107, v108
	s_waitcnt lgkmcnt(4)
	v_add_f32_e32 v109, v109, v110
	s_waitcnt lgkmcnt(3)
	v_add_f32_e32 v111, v111, v112
	s_waitcnt lgkmcnt(2)
	v_add_f32_e32 v113, v113, v114
	s_waitcnt lgkmcnt(1)
	v_add_f32_e32 v115, v115, v116
	s_waitcnt lgkmcnt(0)
	v_add_f32_e32 v117, v117, v118
	ds_bpermute_b32 v94, v49, v87
	ds_bpermute_b32 v95, v49, v88
	ds_bpermute_b32 v96, v49, v89
	ds_bpermute_b32 v97, v49, v90
	ds_bpermute_b32 v98, v49, v91
	ds_bpermute_b32 v99, v49, v92
	ds_bpermute_b32 v100, v49, v93
	ds_bpermute_b32 v108, v49, v107
	ds_bpermute_b32 v110, v49, v109
	ds_bpermute_b32 v112, v49, v111
	ds_bpermute_b32 v114, v49, v113
	ds_bpermute_b32 v116, v49, v115
	ds_bpermute_b32 v118, v49, v117
	s_waitcnt lgkmcnt(12)
	v_add_f32_e32 v87, v87, v94
	s_waitcnt lgkmcnt(11)
	v_add_f32_e32 v88, v88, v95
	s_waitcnt lgkmcnt(10)
	v_add_f32_e32 v89, v89, v96
	s_waitcnt lgkmcnt(9)
	v_add_f32_e32 v90, v90, v97
	s_waitcnt lgkmcnt(8)
	v_add_f32_e32 v91, v91, v98
	s_waitcnt lgkmcnt(7)
	v_add_f32_e32 v92, v92, v99
	s_waitcnt lgkmcnt(6)
	v_add_f32_e32 v93, v93, v100
	s_waitcnt lgkmcnt(5)
	v_add_f32_e32 v107, v107, v108
	s_waitcnt lgkmcnt(4)
	v_add_f32_e32 v109, v109, v110
	s_waitcnt lgkmcnt(3)
	v_add_f32_e32 v111, v111, v112
	s_waitcnt lgkmcnt(2)
	v_add_f32_e32 v113, v113, v114
	s_waitcnt lgkmcnt(1)
	v_add_f32_e32 v115, v115, v116
	s_waitcnt lgkmcnt(0)
	v_add_f32_e32 v117, v117, v118
	ds_bpermute_b32 v94, v50, v87
	ds_bpermute_b32 v95, v50, v88
	ds_bpermute_b32 v96, v50, v89
	ds_bpermute_b32 v97, v50, v90
	ds_bpermute_b32 v98, v50, v91
	ds_bpermute_b32 v99, v50, v92
	ds_bpermute_b32 v100, v50, v93
	ds_bpermute_b32 v108, v50, v107
	ds_bpermute_b32 v110, v50, v109
	ds_bpermute_b32 v112, v50, v111
	ds_bpermute_b32 v114, v50, v113
	ds_bpermute_b32 v116, v50, v115
	ds_bpermute_b32 v118, v50, v117
	s_waitcnt lgkmcnt(12)
	v_add_f32_e32 v87, v87, v94
	s_waitcnt lgkmcnt(11)
	v_add_f32_e32 v88, v88, v95
	s_waitcnt lgkmcnt(10)
	v_add_f32_e32 v89, v89, v96
	s_waitcnt lgkmcnt(9)
	v_add_f32_e32 v90, v90, v97
	s_waitcnt lgkmcnt(8)
	v_add_f32_e32 v91, v91, v98
	s_waitcnt lgkmcnt(7)
	v_add_f32_e32 v94, v92, v99
	s_waitcnt lgkmcnt(6)
	v_add_f32_e32 v93, v93, v100
	s_waitcnt lgkmcnt(5)
	v_add_f32_e32 v107, v107, v108
	s_waitcnt lgkmcnt(4)
	v_add_f32_e32 v109, v109, v110
	s_waitcnt lgkmcnt(3)
	v_add_f32_e32 v111, v111, v112
	s_waitcnt lgkmcnt(2)
	v_add_f32_e32 v113, v113, v114
	s_waitcnt lgkmcnt(1)
	v_add_f32_e32 v115, v115, v116
	s_waitcnt lgkmcnt(0)
	v_add_f32_e32 v117, v117, v118
	ds_bpermute_b32 v92, v51, v87
	ds_bpermute_b32 v95, v51, v88
	ds_bpermute_b32 v96, v51, v89
	ds_bpermute_b32 v97, v51, v90
	ds_bpermute_b32 v98, v51, v91
	ds_bpermute_b32 v99, v51, v94
	ds_bpermute_b32 v100, v51, v93
	ds_bpermute_b32 v108, v51, v107
	ds_bpermute_b32 v110, v51, v109
	ds_bpermute_b32 v112, v51, v111
	ds_bpermute_b32 v114, v51, v113
	ds_bpermute_b32 v116, v51, v115
	ds_bpermute_b32 v118, v51, v117
	s_waitcnt lgkmcnt(12)
	v_add_f32_e32 v87, v87, v92
	s_waitcnt lgkmcnt(11)
	v_add_f32_e32 v88, v88, v95
	s_waitcnt lgkmcnt(10)
	v_add_f32_e32 v89, v89, v96
	s_waitcnt lgkmcnt(9)
	v_add_f32_e32 v90, v90, v97
	s_waitcnt lgkmcnt(8)
	v_add_f32_e32 v92, v91, v98
	s_waitcnt lgkmcnt(7)
	v_add_f32_e32 v94, v94, v99
	s_waitcnt lgkmcnt(6)
	v_add_f32_e32 v96, v93, v100
	s_waitcnt lgkmcnt(5)
	v_add_f32_e32 v107, v107, v108
	s_waitcnt lgkmcnt(4)
	v_add_f32_e32 v109, v109, v110
	s_waitcnt lgkmcnt(3)
	v_add_f32_e32 v111, v111, v112
	s_waitcnt lgkmcnt(2)
	v_add_f32_e32 v113, v113, v114
	s_waitcnt lgkmcnt(1)
	v_add_f32_e32 v115, v115, v116
	s_waitcnt lgkmcnt(0)
	v_add_f32_e32 v117, v117, v118
	ds_bpermute_b32 v91, v52, v87
	ds_bpermute_b32 v93, v52, v88
	ds_bpermute_b32 v95, v52, v89
	ds_bpermute_b32 v97, v52, v90
	ds_bpermute_b32 v98, v52, v92
	ds_bpermute_b32 v99, v52, v94
	ds_bpermute_b32 v100, v52, v96
	ds_bpermute_b32 v102, v52, v101
	ds_bpermute_b32 v104, v52, v103
	ds_bpermute_b32 v106, v52, v105
	ds_bpermute_b32 v108, v52, v107
	ds_bpermute_b32 v110, v52, v109
	ds_bpermute_b32 v112, v52, v111
	ds_bpermute_b32 v114, v52, v113
	ds_bpermute_b32 v116, v52, v115
	ds_bpermute_b32 v118, v52, v117
	s_and_saveexec_b64 s[48:49], vcc
	s_cbranch_execz .LBB0_379
; DI float gelu_tanh(float y) { const float u = 0.7978845608028654f * (y + 0.044715f * y * y * y); return y * __builtin_amdgcn_rcpf(1.0f + __builtin_amdgcn_exp2f(-2.0f * 1.4426950408889634f * u)); }
; DI void s5_sample_unit(const Params& p, int u, const float* uss, bf16_t* z, int lane) {
;     ...
;         for (int i = 0; i < 16; ++i) { float a = cre[i * 64] * hr - cim[i * 64] * hi; a = wave_sum(a); if (lane == i) yv = a; }
;         if (lane < 16) { const float y = yv + p.in[17][g * 16 + lane] * ur[lane]; z[(size_t)(NP + b * 4 + t) * 512 + g * 16 + lane] = (bf16_t)(pk2(gelu_tanh(y), 0.f) & 0xffffu); }
	v_lshl_add_u64 v[120:121], s[90:91], 0, v[46:47]
	global_load_dword v119, v[8:9], off
	s_waitcnt lgkmcnt(14)
	v_add_f32_e32 v87, v87, v91
	global_load_dword v120, v[120:121], off
	v_add_f32_e32 v88, v88, v93
	v_cndmask_b32_e64 v87, 0, v87, s[38:39]
	s_waitcnt lgkmcnt(13)
	v_add_f32_e32 v89, v89, v95
	v_cndmask_b32_e64 v87, v87, v88, s[36:37]
	s_waitcnt lgkmcnt(12)
	v_add_f32_e32 v90, v90, v97
	v_cndmask_b32_e64 v87, v87, v89, s[34:35]
	s_waitcnt lgkmcnt(11)
	v_add_f32_e32 v92, v92, v98
	v_cndmask_b32_e64 v87, v87, v90, s[30:31]
	s_waitcnt lgkmcnt(10)
	v_add_f32_e32 v94, v94, v99
	v_cndmask_b32_e64 v87, v87, v92, s[28:29]
	s_waitcnt lgkmcnt(9)
	v_add_f32_e32 v96, v96, v100
	v_cndmask_b32_e64 v87, v87, v94, s[26:27]
	s_waitcnt lgkmcnt(8)
	v_add_f32_e32 v101, v101, v102
	v_cndmask_b32_e64 v87, v87, v96, s[24:25]
	s_waitcnt lgkmcnt(7)
	v_add_f32_e32 v103, v103, v104
	v_cndmask_b32_e64 v87, v87, v101, s[22:23]
	s_waitcnt lgkmcnt(6)
	v_add_f32_e32 v105, v105, v106
	v_cndmask_b32_e64 v87, v87, v103, s[20:21]
	s_waitcnt lgkmcnt(5)
	v_add_f32_e32 v107, v107, v108
	v_cndmask_b32_e64 v87, v87, v105, s[18:19]
	s_waitcnt lgkmcnt(4)
	v_add_f32_e32 v109, v109, v110
	v_cndmask_b32_e64 v87, v87, v107, s[16:17]
	s_waitcnt lgkmcnt(3)
	v_add_f32_e32 v111, v111, v112
	v_cndmask_b32_e64 v87, v87, v109, s[14:15]
	s_waitcnt lgkmcnt(2)
	v_add_f32_e32 v113, v113, v114
	v_cndmask_b32_e64 v87, v87, v111, s[12:13]
	s_waitcnt lgkmcnt(1)
	v_add_f32_e32 v115, v115, v116
	v_cndmask_b32_e64 v87, v87, v113, s[10:11]
	s_waitcnt lgkmcnt(0)
	v_add_f32_e32 v117, v117, v118
	v_cndmask_b32_e64 v87, v87, v115, s[8:9]
	v_cndmask_b32_e64 v87, v87, v117, s[6:7]
	s_waitcnt vmcnt(0)
	v_fmac_f32_e32 v87, v119, v120
	v_mul_f32_e32 v88, 0x3d372713, v87
	v_mul_f32_e32 v88, v87, v88
	v_fma_f32 v88, v87, v88, v87
	v_mul_f32_e32 v88, 0xc0135761, v88
	v_exp_f32_e32 v88, v88
	s_nop 0
	v_add_f32_e32 v88, 1.0, v88
	v_rcp_f32_e32 v88, v88
	s_nop 0
	v_mul_f32_e32 v87, v87, v88
	v_cvt_pk_bf16_f32 v87, v87, s0
	v_lshl_add_u64 v[88:89], s[90:91], 0, v[44:45]
	global_store_short v[88:89], v87, off
	s_branch .LBB0_379

; DI float bflo(unsigned w) { return __uint_as_float(w << 16); }
; DI float bfhi(unsigned w) { return __uint_as_float(w & 0xffff0000u); }
; DI float gelu_tanh(float y) { const float u = 0.7978845608028654f * (y + 0.044715f * y * y * y); return y * __builtin_amdgcn_rcpf(1.0f + __builtin_amdgcn_exp2f(-2.0f * 1.4426950408889634f * u)); }
; #define EPI_ROWS(...) _Pragma("unroll") for (int ai = 0; ai < 2; ++ai) _Pragma("unroll") for (int m = 0; m < 4; ++m) { const int rr = ai * 128 + wr * 64 + m * 16 + fr; __VA_ARGS__ }
; #define EPI_COLS8(...) _Pragma("unroll") for (int bj = 0; bj < 2; ++bj) { const int cc = bj * 128 + wc * 32 + 8 * fq; const f32x4 v0 = acc[ai][bj][m][0], v1 = acc[ai][bj][m][1]; __VA_ARGS__ }
;     DI void operator()(const Acc& acc, int wr, int wc, int fr, int fq) const {
;         EPI_ROWS(const int chunk = row0 + rr; const bf16_t* ap = Ap + ((size_t)g * 2048 + chunk) * 384 + 128;
;             EPI_COLS8(const int r = cc >> 4, i = cc & 15; const u32x4 uw = *(const u32x4*)(ap + cc); const f32x4 d0 = *(const f32x4*)(dskip + g * 16 + i), d1 = *(const f32x4*)(dskip + g * 16 + i + 4);
;                 const float y0 = v0[0] + d0[0] * bflo(uw.x), y1 = v0[1] + d0[1] * bfhi(uw.x), y2 = v0[2] + d0[2] * bflo(uw.y), y3 = v0[3] + d0[3] * bfhi(uw.y);
;                 const float y4 = v1[0] + d1[0] * bflo(uw.z), y5 = v1[1] + d1[1] * bfhi(uw.z), y6 = v1[2] + d1[2] * bflo(uw.w), y7 = v1[3] + d1[3] * bfhi(uw.w);
;                 u32x4 w; w.x = pk2(gelu_tanh(y0), gelu_tanh(y1)); w.y = pk2(gelu_tanh(y2), gelu_tanh(y3)); w.z = pk2(gelu_tanh(y4), gelu_tanh(y5)); w.w = pk2(gelu_tanh(y6), gelu_tanh(y7));
;                 *(u32x4*)(z + ((size_t)chunk * 16 + r) * 512 + g * 16 + i) = w;))
.LBB0_763:
	v_add_u32_e32 v140, s2, v144
	s_ashr_i32 s1, s0, 31
	s_lshl_b64 s[40:41], s[0:1], 11
	v_ashrrev_i32_e32 v141, 31, v140
	v_lshl_add_u64 v[152:153], s[40:41], 0, v[140:141]
	v_mov_b64_e32 v[142:143], s[22:23]
	v_mad_u64_u32 v[154:155], s[38:39], v152, s46, v[142:143]
	s_lshl_b32 s38, s0, 4
	s_ashr_i32 s39, s38, 31
	v_mad_i32_i24 v155, v153, s46, v155
	s_lshl_b64 s[0:1], s[38:39], 2
	v_lshl_add_u64 v[166:167], v[154:155], 0, v[138:139]
	s_add_u32 s0, s20, s0
	global_load_dwordx4 v[154:157], v[166:167], off offset:256
	s_addc_u32 s1, s21, s1
	v_lshlrev_b32_e32 v152, 2, v130
	global_load_dwordx4 v[158:161], v152, s[0:1]
	global_load_dwordx4 v[162:165], v152, s[0:1] offset:16
	v_lshlrev_b64 v[168:169], 14, v[140:141]
	s_lshl_b64 s[38:39], s[38:39], 1
	s_andn2_b64 vcc, exec, s[36:37]
	s_waitcnt vmcnt(0)
	v_lshlrev_b32_e32 v170, 16, v154
	v_and_b32_e32 v171, 0xffff0000, v154
	v_lshlrev_b32_e32 v154, 16, v155
	v_and_b32_e32 v155, 0xffff0000, v155
	v_lshlrev_b32_e32 v172, 16, v156
	v_and_b32_e32 v173, 0xffff0000, v156
	v_lshlrev_b32_e32 v156, 16, v157
	v_and_b32_e32 v157, 0xffff0000, v157
	v_pk_fma_f32 v[124:125], v[158:159], v[170:171], v[124:125]
	v_pk_fma_f32 v[126:127], v[160:161], v[154:155], v[126:127]
	v_pk_fma_f32 v[120:121], v[162:163], v[172:173], v[120:121]
	v_pk_fma_f32 v[122:123], v[164:165], v[156:157], v[122:123]
	v_mul_f32_e32 v132, 0x3d372713, v124
	v_mul_f32_e32 v141, 0x3d372713, v125
	v_mul_f32_e32 v154, 0x3d372713, v127
	v_mul_f32_e32 v155, 0x3d372713, v120
	v_mul_f32_e32 v156, 0x3d372713, v121
	v_mul_f32_e32 v157, 0x3d372713, v122
	v_mul_f32_e32 v158, 0x3d372713, v123
	v_mul_f32_e32 v132, v124, v132
	v_mul_f32_e32 v141, v125, v141
	v_mul_f32_e32 v154, v127, v154
	v_mul_f32_e32 v155, v120, v155
	v_mul_f32_e32 v156, v121, v156
	v_mul_f32_e32 v153, 0x3d372713, v126
	v_mul_f32_e32 v157, v122, v157
	v_mul_f32_e32 v158, v123, v158
	v_fma_f32 v132, v124, v132, v124
	v_fma_f32 v141, v125, v141, v125
	v_fma_f32 v154, v127, v154, v127
	v_fma_f32 v155, v120, v155, v120
	v_fma_f32 v156, v121, v156, v121
	v_mul_f32_e32 v153, v126, v153
	v_fma_f32 v157, v122, v157, v122
	v_fma_f32 v158, v123, v158, v123
	v_mul_f32_e32 v132, 0xc0135761, v132
	v_mul_f32_e32 v141, 0xc0135761, v141
	v_mul_f32_e32 v154, 0xc0135761, v154
	v_mul_f32_e32 v155, 0xc0135761, v155
	v_mul_f32_e32 v156, 0xc0135761, v156
	v_fma_f32 v153, v126, v153, v126
	v_mul_f32_e32 v157, 0xc0135761, v157
	v_mul_f32_e32 v158, 0xc0135761, v158
	v_mul_f32_e32 v153, 0xc0135761, v153
	v_exp_f32_e32 v132, v132
	v_exp_f32_e32 v141, v141
	v_exp_f32_e32 v154, v154
	v_exp_f32_e32 v155, v155
	v_exp_f32_e32 v156, v156
	v_exp_f32_e32 v157, v157
	v_exp_f32_e32 v158, v158
	v_exp_f32_e32 v153, v153
	v_add_f32_e32 v132, 1.0, v132
	v_add_f32_e32 v141, 1.0, v141
	v_add_f32_e32 v159, 1.0, v154
	v_add_f32_e32 v160, 1.0, v155
	v_add_f32_e32 v161, 1.0, v156
	v_add_f32_e32 v162, 1.0, v157
	v_add_f32_e32 v163, 1.0, v158
	v_rcp_f32_e32 v154, v132
	v_rcp_f32_e32 v155, v141
	v_rcp_f32_e32 v157, v159
	v_rcp_f32_e32 v158, v160
	v_rcp_f32_e32 v159, v161
	v_add_f32_e32 v153, 1.0, v153
	v_rcp_f32_e32 v156, v153
	v_rcp_f32_e32 v160, v162
	v_rcp_f32_e32 v161, v163
	v_pk_mul_f32 v[124:125], v[124:125], v[154:155]
	v_pk_mul_f32 v[154:155], v[120:121], v[158:159]
	v_lshl_add_u64 v[158:159], s[26:27], 0, v[168:169]
	v_cvt_pk_bf16_f32 v120, v124, v125
	v_lshl_add_u64 v[124:125], v[158:159], 0, v[134:135]
	v_pk_mul_f32 v[126:127], v[126:127], v[156:157]
	v_pk_mul_f32 v[156:157], v[122:123], v[160:161]
	v_lshl_add_u64 v[124:125], v[124:125], 0, s[38:39]
	v_lshlrev_b32_e32 v132, 1, v130
	v_cvt_pk_bf16_f32 v121, v126, v127
	v_cvt_pk_bf16_f32 v122, v154, v155
	v_cvt_pk_bf16_f32 v123, v156, v157
	v_lshl_add_u64 v[124:125], v[124:125], 0, v[132:133]
	global_store_dwordx4 v[124:125], v[120:123], off
	global_load_dwordx4 v[120:123], v[166:167], off offset:512
	s_nop 0
	global_load_dwordx4 v[124:127], v152, s[0:1]
	global_load_dwordx4 v[154:157], v152, s[0:1] offset:16
	v_lshl_add_u64 v[158:159], v[158:159], 0, v[136:137]
	v_add_u32_e32 v160, s2, v147
	v_lshl_add_u64 v[158:159], v[158:159], 0, s[38:39]
	v_ashrrev_i32_e32 v161, 31, v160
	v_lshl_add_u64 v[158:159], v[158:159], 0, v[132:133]
	s_waitcnt vmcnt(2)
	v_lshlrev_b32_e32 v162, 16, v120
	v_and_b32_e32 v163, 0xffff0000, v120
	v_lshlrev_b32_e32 v120, 16, v121
	v_and_b32_e32 v121, 0xffff0000, v121
	v_lshlrev_b32_e32 v164, 16, v122
	v_and_b32_e32 v165, 0xffff0000, v122
	v_lshlrev_b32_e32 v122, 16, v123
	v_and_b32_e32 v123, 0xffff0000, v123
	s_waitcnt vmcnt(1)
	v_pk_fma_f32 v[112:113], v[124:125], v[162:163], v[112:113]
	v_pk_fma_f32 v[114:115], v[126:127], v[120:121], v[114:115]
	s_waitcnt vmcnt(0)
; DI float bflo(unsigned w) { return __uint_as_float(w << 16); }
; DI float bfhi(unsigned w) { return __uint_as_float(w & 0xffff0000u); }
; DI float gelu_tanh(float y) { const float u = 0.7978845608028654f * (y + 0.044715f * y * y * y); return y * __builtin_amdgcn_rcpf(1.0f + __builtin_amdgcn_exp2f(-2.0f * 1.4426950408889634f * u)); }
; #define EPI_ROWS(...) _Pragma("unroll") for (int ai = 0; ai < 2; ++ai) _Pragma("unroll") for (int m = 0; m < 4; ++m) { const int rr = ai * 128 + wr * 64 + m * 16 + fr; __VA_ARGS__ }
; #define EPI_COLS8(...) _Pragma("unroll") for (int bj = 0; bj < 2; ++bj) { const int cc = bj * 128 + wc * 32 + 8 * fq; const f32x4 v0 = acc[ai][bj][m][0], v1 = acc[ai][bj][m][1]; __VA_ARGS__ }
;     DI void operator()(const Acc& acc, int wr, int wc, int fr, int fq) const {
;         EPI_ROWS(const int chunk = row0 + rr; const bf16_t* ap = Ap + ((size_t)g * 2048 + chunk) * 384 + 128;
;             EPI_COLS8(const int r = cc >> 4, i = cc & 15; const u32x4 uw = *(const u32x4*)(ap + cc); const f32x4 d0 = *(const f32x4*)(dskip + g * 16 + i), d1 = *(const f32x4*)(dskip + g * 16 + i + 4);
;                 const float y0 = v0[0] + d0[0] * bflo(uw.x), y1 = v0[1] + d0[1] * bfhi(uw.x), y2 = v0[2] + d0[2] * bflo(uw.y), y3 = v0[3] + d0[3] * bfhi(uw.y);
;                 const float y4 = v1[0] + d1[0] * bflo(uw.z), y5 = v1[1] + d1[1] * bfhi(uw.z), y6 = v1[2] + d1[2] * bflo(uw.w), y7 = v1[3] + d1[3] * bfhi(uw.w);
;                 u32x4 w; w.x = pk2(gelu_tanh(y0), gelu_tanh(y1)); w.y = pk2(gelu_tanh(y2), gelu_tanh(y3)); w.z = pk2(gelu_tanh(y4), gelu_tanh(y5)); w.w = pk2(gelu_tanh(y6), gelu_tanh(y7));
;                 *(u32x4*)(z + ((size_t)chunk * 16 + r) * 512 + g * 16 + i) = w;))
	v_pk_fma_f32 v[116:117], v[154:155], v[164:165], v[116:117]
	v_pk_fma_f32 v[118:119], v[156:157], v[122:123], v[118:119]
	v_mul_f32_e32 v120, 0x3d372713, v112
	v_mul_f32_e32 v121, 0x3d372713, v113
	v_mul_f32_e32 v122, 0x3d372713, v114
	v_mul_f32_e32 v123, 0x3d372713, v115
	v_mul_f32_e32 v124, 0x3d372713, v116
	v_mul_f32_e32 v125, 0x3d372713, v117
	v_mul_f32_e32 v126, 0x3d372713, v118
	v_mul_f32_e32 v127, 0x3d372713, v119
	v_mul_f32_e32 v120, v112, v120
	v_mul_f32_e32 v121, v113, v121
	v_mul_f32_e32 v122, v114, v122
	v_mul_f32_e32 v123, v115, v123
	v_mul_f32_e32 v124, v116, v124
	v_mul_f32_e32 v125, v117, v125
	v_mul_f32_e32 v126, v118, v126
	v_mul_f32_e32 v127, v119, v127
	v_fma_f32 v120, v112, v120, v112
	v_fma_f32 v121, v113, v121, v113
	v_fma_f32 v122, v114, v122, v114
	v_fma_f32 v123, v115, v123, v115
	v_fma_f32 v124, v116, v124, v116
	v_fma_f32 v125, v117, v125, v117
	v_fma_f32 v126, v118, v126, v118
	v_fma_f32 v127, v119, v127, v119
	v_mul_f32_e32 v120, 0xc0135761, v120
	v_mul_f32_e32 v121, 0xc0135761, v121
	v_mul_f32_e32 v122, 0xc0135761, v122
	v_mul_f32_e32 v123, 0xc0135761, v123
	v_mul_f32_e32 v124, 0xc0135761, v124
	v_mul_f32_e32 v125, 0xc0135761, v125
	v_mul_f32_e32 v126, 0xc0135761, v126
	v_mul_f32_e32 v127, 0xc0135761, v127
	v_exp_f32_e32 v120, v120
	v_exp_f32_e32 v121, v121
	v_exp_f32_e32 v122, v122
	v_exp_f32_e32 v123, v123
	v_exp_f32_e32 v124, v124
	v_exp_f32_e32 v125, v125
	v_exp_f32_e32 v126, v126
	v_exp_f32_e32 v127, v127
	v_add_f32_e32 v120, 1.0, v120
	v_add_f32_e32 v121, 1.0, v121
	v_add_f32_e32 v122, 1.0, v122
	v_add_f32_e32 v123, 1.0, v123
	v_add_f32_e32 v124, 1.0, v124
	v_add_f32_e32 v125, 1.0, v125
	v_add_f32_e32 v126, 1.0, v126
	v_add_f32_e32 v127, 1.0, v127
	v_rcp_f32_e32 v120, v120
	v_rcp_f32_e32 v121, v121
	v_rcp_f32_e32 v122, v122
	v_rcp_f32_e32 v123, v123
	v_rcp_f32_e32 v124, v124
	v_rcp_f32_e32 v125, v125
	v_rcp_f32_e32 v126, v126
	v_rcp_f32_e32 v127, v127
	v_pk_mul_f32 v[112:113], v[112:113], v[120:121]
	v_pk_mul_f32 v[114:115], v[114:115], v[122:123]
	v_pk_mul_f32 v[116:117], v[116:117], v[124:125]
	v_pk_mul_f32 v[118:119], v[118:119], v[126:127]
	v_cvt_pk_bf16_f32 v112, v112, v113
	v_cvt_pk_bf16_f32 v113, v114, v115
	v_cvt_pk_bf16_f32 v114, v116, v117
	v_cvt_pk_bf16_f32 v115, v118, v119
	global_store_dwordx4 v[158:159], v[112:115], off
	v_lshlrev_b64 v[126:127], 14, v[160:161]
	v_lshl_add_u64 v[126:127], s[26:27], 0, v[126:127]
	v_lshl_add_u64 v[112:113], s[40:41], 0, v[160:161]
	v_mad_u64_u32 v[114:115], s[66:67], v112, s46, v[142:143]
	v_mad_i32_i24 v115, v113, s46, v115
	v_lshl_add_u64 v[124:125], v[114:115], 0, v[138:139]
	global_load_dwordx4 v[112:115], v[124:125], off offset:256
	global_load_dwordx4 v[116:119], v152, s[0:1]
	global_load_dwordx4 v[120:123], v152, s[0:1] offset:16
	v_lshl_add_u64 v[154:155], v[126:127], 0, v[134:135]
	v_lshl_add_u64 v[154:155], v[154:155], 0, s[38:39]
	v_lshl_add_u64 v[154:155], v[154:155], 0, v[132:133]
	s_waitcnt vmcnt(2)
	v_lshlrev_b32_e32 v156, 16, v112
	v_and_b32_e32 v157, 0xffff0000, v112
	v_lshlrev_b32_e32 v112, 16, v113
	v_and_b32_e32 v113, 0xffff0000, v113
	v_lshlrev_b32_e32 v158, 16, v114
	v_and_b32_e32 v159, 0xffff0000, v114
	v_lshlrev_b32_e32 v114, 16, v115
	v_and_b32_e32 v115, 0xffff0000, v115
	s_waitcnt vmcnt(1)
	v_pk_fma_f32 v[104:105], v[116:117], v[156:157], v[104:105]
	v_pk_fma_f32 v[106:107], v[118:119], v[112:113], v[106:107]
	s_waitcnt vmcnt(0)
	v_pk_fma_f32 v[108:109], v[120:121], v[158:159], v[108:109]
	v_pk_fma_f32 v[110:111], v[122:123], v[114:115], v[110:111]
	v_mul_f32_e32 v112, 0x3d372713, v104
	v_mul_f32_e32 v113, 0x3d372713, v105
	v_mul_f32_e32 v114, 0x3d372713, v106
	v_mul_f32_e32 v115, 0x3d372713, v107
	v_mul_f32_e32 v116, 0x3d372713, v108
	v_mul_f32_e32 v117, 0x3d372713, v109
	v_mul_f32_e32 v118, 0x3d372713, v110
	v_mul_f32_e32 v119, 0x3d372713, v111
	v_mul_f32_e32 v112, v104, v112
	v_mul_f32_e32 v113, v105, v113
	v_mul_f32_e32 v114, v106, v114
	v_mul_f32_e32 v115, v107, v115
	v_mul_f32_e32 v116, v108, v116
	v_mul_f32_e32 v117, v109, v117
	v_mul_f32_e32 v118, v110, v118
	v_mul_f32_e32 v119, v111, v119
	v_fma_f32 v112, v104, v112, v104
	v_fma_f32 v113, v105, v113, v105
	v_fma_f32 v114, v106, v114, v106
	v_fma_f32 v115, v107, v115, v107
	v_fma_f32 v116, v108, v116, v108
	v_fma_f32 v117, v109, v117, v109
	v_fma_f32 v118, v110, v118, v110
	v_fma_f32 v119, v111, v119, v111
	v_mul_f32_e32 v112, 0xc0135761, v112
	v_mul_f32_e32 v113, 0xc0135761, v113
	v_mul_f32_e32 v114, 0xc0135761, v114
	v_mul_f32_e32 v115, 0xc0135761, v115
	v_mul_f32_e32 v116, 0xc0135761, v116
	v_mul_f32_e32 v117, 0xc0135761, v117
	v_mul_f32_e32 v118, 0xc0135761, v118
	v_mul_f32_e32 v119, 0xc0135761, v119
	v_exp_f32_e32 v112, v112
	v_exp_f32_e32 v113, v113
	v_exp_f32_e32 v114, v114
	v_exp_f32_e32 v115, v115
	v_exp_f32_e32 v116, v116
	v_exp_f32_e32 v117, v117
	v_exp_f32_e32 v118, v118
	v_exp_f32_e32 v119, v119
	v_add_f32_e32 v112, 1.0, v112
	v_add_f32_e32 v113, 1.0, v113
	v_add_f32_e32 v114, 1.0, v114
	v_add_f32_e32 v115, 1.0, v115
	v_add_f32_e32 v116, 1.0, v116
	v_add_f32_e32 v117, 1.0, v117
	v_add_f32_e32 v118, 1.0, v118
	v_add_f32_e32 v119, 1.0, v119
	v_rcp_f32_e32 v112, v112
	v_rcp_f32_e32 v113, v113
	v_rcp_f32_e32 v114, v114
	v_rcp_f32_e32 v115, v115
	v_rcp_f32_e32 v116, v116
	v_rcp_f32_e32 v117, v117
	v_rcp_f32_e32 v118, v118
	v_rcp_f32_e32 v119, v119
	v_pk_mul_f32 v[104:105], v[104:105], v[112:113]
	v_pk_mul_f32 v[106:107], v[106:107], v[114:115]
	v_pk_mul_f32 v[108:109], v[108:109], v[116:117]
	v_pk_mul_f32 v[110:111], v[110:111], v[118:119]
	v_cvt_pk_bf16_f32 v104, v104, v105
	v_cvt_pk_bf16_f32 v105, v106, v107
	v_cvt_pk_bf16_f32 v106, v108, v109
	v_cvt_pk_bf16_f32 v107, v110, v111
	global_store_dwordx4 v[154:155], v[104:107], off
	global_load_dwordx4 v[106:109], v[124:125], off offset:512
	s_nop 0
	global_load_dwordx4 v[110:113], v152, s[0:1]
	global_load_dwordx4 v[114:117], v152, s[0:1] offset:16
	v_add_u32_e32 v118, s2, v148
	v_ashrrev_i32_e32 v119, 31, v118
	v_lshl_add_u64 v[104:105], s[40:41], 0, v[118:119]
	v_mad_u64_u32 v[120:121], s[66:67], v104, s46, v[142:143]
	v_lshl_add_u64 v[122:123], v[126:127], 0, v[136:137]
	v_mad_i32_i24 v121, v105, s46, v121
	v_lshl_add_u64 v[122:123], v[122:123], 0, s[38:39]
	v_lshl_add_u64 v[104:105], v[120:121], 0, v[138:139]
	v_lshl_add_u64 v[120:121], v[122:123], 0, v[132:133]
	s_waitcnt vmcnt(2)
; DI float bflo(unsigned w) { return __uint_as_float(w << 16); }
; DI float bfhi(unsigned w) { return __uint_as_float(w & 0xffff0000u); }
; DI float gelu_tanh(float y) { const float u = 0.7978845608028654f * (y + 0.044715f * y * y * y); return y * __builtin_amdgcn_rcpf(1.0f + __builtin_amdgcn_exp2f(-2.0f * 1.4426950408889634f * u)); }
; #define EPI_ROWS(...) _Pragma("unroll") for (int ai = 0; ai < 2; ++ai) _Pragma("unroll") for (int m = 0; m < 4; ++m) { const int rr = ai * 128 + wr * 64 + m * 16 + fr; __VA_ARGS__ }
; #define EPI_COLS8(...) _Pragma("unroll") for (int bj = 0; bj < 2; ++bj) { const int cc = bj * 128 + wc * 32 + 8 * fq; const f32x4 v0 = acc[ai][bj][m][0], v1 = acc[ai][bj][m][1]; __VA_ARGS__ }
;     DI void operator()(const Acc& acc, int wr, int wc, int fr, int fq) const {
;         EPI_ROWS(const int chunk = row0 + rr; const bf16_t* ap = Ap + ((size_t)g * 2048 + chunk) * 384 + 128;
;             EPI_COLS8(const int r = cc >> 4, i = cc & 15; const u32x4 uw = *(const u32x4*)(ap + cc); const f32x4 d0 = *(const f32x4*)(dskip + g * 16 + i), d1 = *(const f32x4*)(dskip + g * 16 + i + 4);
;                 const float y0 = v0[0] + d0[0] * bflo(uw.x), y1 = v0[1] + d0[1] * bfhi(uw.x), y2 = v0[2] + d0[2] * bflo(uw.y), y3 = v0[3] + d0[3] * bfhi(uw.y);
;                 const float y4 = v1[0] + d1[0] * bflo(uw.z), y5 = v1[1] + d1[1] * bfhi(uw.z), y6 = v1[2] + d1[2] * bflo(uw.w), y7 = v1[3] + d1[3] * bfhi(uw.w);
;                 u32x4 w; w.x = pk2(gelu_tanh(y0), gelu_tanh(y1)); w.y = pk2(gelu_tanh(y2), gelu_tanh(y3)); w.z = pk2(gelu_tanh(y4), gelu_tanh(y5)); w.w = pk2(gelu_tanh(y6), gelu_tanh(y7));
;                 *(u32x4*)(z + ((size_t)chunk * 16 + r) * 512 + g * 16 + i) = w;))
	v_lshlrev_b32_e32 v122, 16, v106
	v_and_b32_e32 v123, 0xffff0000, v106
	v_lshlrev_b32_e32 v106, 16, v107
	v_and_b32_e32 v107, 0xffff0000, v107
	v_lshlrev_b32_e32 v124, 16, v108
	v_and_b32_e32 v125, 0xffff0000, v108
	v_lshlrev_b32_e32 v108, 16, v109
	v_and_b32_e32 v109, 0xffff0000, v109
	s_waitcnt vmcnt(1)
	v_pk_fma_f32 v[96:97], v[110:111], v[122:123], v[96:97]
	v_pk_fma_f32 v[98:99], v[112:113], v[106:107], v[98:99]
	s_waitcnt vmcnt(0)
	v_pk_fma_f32 v[100:101], v[114:115], v[124:125], v[100:101]
	v_pk_fma_f32 v[102:103], v[116:117], v[108:109], v[102:103]
	v_mul_f32_e32 v106, 0x3d372713, v96
	v_mul_f32_e32 v107, 0x3d372713, v97
	v_mul_f32_e32 v108, 0x3d372713, v98
	v_mul_f32_e32 v109, 0x3d372713, v99
	v_mul_f32_e32 v110, 0x3d372713, v100
	v_mul_f32_e32 v111, 0x3d372713, v101
	v_mul_f32_e32 v112, 0x3d372713, v102
	v_mul_f32_e32 v113, 0x3d372713, v103
	v_mul_f32_e32 v106, v96, v106
	v_mul_f32_e32 v107, v97, v107
	v_mul_f32_e32 v108, v98, v108
	v_mul_f32_e32 v109, v99, v109
	v_mul_f32_e32 v110, v100, v110
	v_mul_f32_e32 v111, v101, v111
	v_mul_f32_e32 v112, v102, v112
	v_mul_f32_e32 v113, v103, v113
	v_fma_f32 v106, v96, v106, v96
	v_fma_f32 v107, v97, v107, v97
	v_fma_f32 v108, v98, v108, v98
	v_fma_f32 v109, v99, v109, v99
	v_fma_f32 v110, v100, v110, v100
	v_fma_f32 v111, v101, v111, v101
	v_fma_f32 v112, v102, v112, v102
	v_fma_f32 v113, v103, v113, v103
	v_mul_f32_e32 v106, 0xc0135761, v106
	v_mul_f32_e32 v107, 0xc0135761, v107
	v_mul_f32_e32 v108, 0xc0135761, v108
	v_mul_f32_e32 v109, 0xc0135761, v109
	v_mul_f32_e32 v110, 0xc0135761, v110
	v_mul_f32_e32 v111, 0xc0135761, v111
	v_mul_f32_e32 v112, 0xc0135761, v112
	v_mul_f32_e32 v113, 0xc0135761, v113
	v_exp_f32_e32 v106, v106
	v_exp_f32_e32 v107, v107
	v_exp_f32_e32 v108, v108
	v_exp_f32_e32 v109, v109
	v_exp_f32_e32 v110, v110
	v_exp_f32_e32 v111, v111
	v_exp_f32_e32 v112, v112
	v_exp_f32_e32 v113, v113
	v_add_f32_e32 v106, 1.0, v106
	v_add_f32_e32 v107, 1.0, v107
	v_add_f32_e32 v108, 1.0, v108
	v_add_f32_e32 v109, 1.0, v109
	v_add_f32_e32 v110, 1.0, v110
	v_add_f32_e32 v111, 1.0, v111
	v_add_f32_e32 v112, 1.0, v112
	v_add_f32_e32 v113, 1.0, v113
	v_rcp_f32_e32 v106, v106
	v_rcp_f32_e32 v107, v107
	v_rcp_f32_e32 v108, v108
	v_rcp_f32_e32 v109, v109
	v_rcp_f32_e32 v110, v110
	v_rcp_f32_e32 v111, v111
	v_rcp_f32_e32 v112, v112
	v_rcp_f32_e32 v113, v113
	v_pk_mul_f32 v[96:97], v[96:97], v[106:107]
	v_pk_mul_f32 v[98:99], v[98:99], v[108:109]
	v_pk_mul_f32 v[100:101], v[100:101], v[110:111]
	v_pk_mul_f32 v[102:103], v[102:103], v[112:113]
	v_cvt_pk_bf16_f32 v96, v96, v97
	v_cvt_pk_bf16_f32 v97, v98, v99
	v_cvt_pk_bf16_f32 v98, v100, v101
	v_cvt_pk_bf16_f32 v99, v102, v103
	global_store_dwordx4 v[120:121], v[96:99], off
	global_load_dwordx4 v[96:99], v[104:105], off offset:256
	s_nop 0
	global_load_dwordx4 v[100:103], v152, s[0:1]
	global_load_dwordx4 v[106:109], v152, s[0:1] offset:16
	v_lshlrev_b64 v[110:111], 14, v[118:119]
	v_lshl_add_u64 v[110:111], s[26:27], 0, v[110:111]
	v_lshl_add_u64 v[112:113], v[110:111], 0, v[134:135]
	v_lshl_add_u64 v[112:113], v[112:113], 0, s[38:39]
	v_lshl_add_u64 v[112:113], v[112:113], 0, v[132:133]
	s_waitcnt vmcnt(2)
	v_lshlrev_b32_e32 v114, 16, v96
	v_and_b32_e32 v115, 0xffff0000, v96
	v_lshlrev_b32_e32 v96, 16, v97
	v_and_b32_e32 v97, 0xffff0000, v97
	v_lshlrev_b32_e32 v116, 16, v98
	v_and_b32_e32 v117, 0xffff0000, v98
	v_lshlrev_b32_e32 v98, 16, v99
	v_and_b32_e32 v99, 0xffff0000, v99
	s_waitcnt vmcnt(1)
	v_pk_fma_f32 v[88:89], v[100:101], v[114:115], v[88:89]
	v_pk_fma_f32 v[90:91], v[102:103], v[96:97], v[90:91]
	s_waitcnt vmcnt(0)
	v_pk_fma_f32 v[92:93], v[106:107], v[116:117], v[92:93]
	v_pk_fma_f32 v[94:95], v[108:109], v[98:99], v[94:95]
	v_mul_f32_e32 v96, 0x3d372713, v88
	v_mul_f32_e32 v97, 0x3d372713, v89
	v_mul_f32_e32 v98, 0x3d372713, v90
	v_mul_f32_e32 v99, 0x3d372713, v91
	v_mul_f32_e32 v100, 0x3d372713, v92
	v_mul_f32_e32 v101, 0x3d372713, v93
	v_mul_f32_e32 v102, 0x3d372713, v94
	v_mul_f32_e32 v103, 0x3d372713, v95
	v_mul_f32_e32 v96, v88, v96
	v_mul_f32_e32 v97, v89, v97
	v_mul_f32_e32 v98, v90, v98
	v_mul_f32_e32 v99, v91, v99
	v_mul_f32_e32 v100, v92, v100
	v_mul_f32_e32 v101, v93, v101
	v_mul_f32_e32 v102, v94, v102
	v_mul_f32_e32 v103, v95, v103
	v_fma_f32 v96, v88, v96, v88
	v_fma_f32 v97, v89, v97, v89
	v_fma_f32 v98, v90, v98, v90
	v_fma_f32 v99, v91, v99, v91
	v_fma_f32 v100, v92, v100, v92
	v_fma_f32 v101, v93, v101, v93
	v_fma_f32 v102, v94, v102, v94
	v_fma_f32 v103, v95, v103, v95
	v_mul_f32_e32 v96, 0xc0135761, v96
	v_mul_f32_e32 v97, 0xc0135761, v97
	v_mul_f32_e32 v98, 0xc0135761, v98
	v_mul_f32_e32 v99, 0xc0135761, v99
	v_mul_f32_e32 v100, 0xc0135761, v100
	v_mul_f32_e32 v101, 0xc0135761, v101
	v_mul_f32_e32 v102, 0xc0135761, v102
	v_mul_f32_e32 v103, 0xc0135761, v103
	v_exp_f32_e32 v96, v96
	v_exp_f32_e32 v97, v97
	v_exp_f32_e32 v98, v98
	v_exp_f32_e32 v99, v99
	v_exp_f32_e32 v100, v100
	v_exp_f32_e32 v101, v101
	v_exp_f32_e32 v102, v102
	v_exp_f32_e32 v103, v103
	v_add_f32_e32 v96, 1.0, v96
	v_add_f32_e32 v97, 1.0, v97
	v_add_f32_e32 v98, 1.0, v98
	v_add_f32_e32 v99, 1.0, v99
	v_add_f32_e32 v100, 1.0, v100
	v_add_f32_e32 v101, 1.0, v101
	v_add_f32_e32 v102, 1.0, v102
	v_add_f32_e32 v103, 1.0, v103
	v_rcp_f32_e32 v96, v96
	v_rcp_f32_e32 v97, v97
	v_rcp_f32_e32 v98, v98
	v_rcp_f32_e32 v99, v99
	v_rcp_f32_e32 v100, v100
	v_rcp_f32_e32 v101, v101
	v_rcp_f32_e32 v102, v102
	v_rcp_f32_e32 v103, v103
	v_pk_mul_f32 v[88:89], v[88:89], v[96:97]
	v_pk_mul_f32 v[90:91], v[90:91], v[98:99]
	v_pk_mul_f32 v[92:93], v[92:93], v[100:101]
	v_pk_mul_f32 v[94:95], v[94:95], v[102:103]
	v_cvt_pk_bf16_f32 v88, v88, v89
	v_cvt_pk_bf16_f32 v89, v90, v91
	v_cvt_pk_bf16_f32 v90, v92, v93
	v_cvt_pk_bf16_f32 v91, v94, v95
	global_store_dwordx4 v[112:113], v[88:91], off
	global_load_dwordx4 v[90:93], v[104:105], off offset:512
	s_nop 0
	global_load_dwordx4 v[94:97], v152, s[0:1]
	global_load_dwordx4 v[98:101], v152, s[0:1] offset:16
	v_add_u32_e32 v102, s2, v149
	v_ashrrev_i32_e32 v103, 31, v102
	v_lshl_add_u64 v[88:89], s[40:41], 0, v[102:103]
	v_mad_u64_u32 v[104:105], s[66:67], v88, s46, v[142:143]
	v_lshl_add_u64 v[106:107], v[110:111], 0, v[136:137]
	v_mad_i32_i24 v105, v89, s46, v105
	v_lshl_add_u64 v[106:107], v[106:107], 0, s[38:39]
	v_lshl_add_u64 v[88:89], v[104:105], 0, v[138:139]
	v_lshl_add_u64 v[104:105], v[106:107], 0, v[132:133]
	s_waitcnt vmcnt(2)
; DI float bflo(unsigned w) { return __uint_as_float(w << 16); }
; DI float bfhi(unsigned w) { return __uint_as_float(w & 0xffff0000u); }
; DI float gelu_tanh(float y) { const float u = 0.7978845608028654f * (y + 0.044715f * y * y * y); return y * __builtin_amdgcn_rcpf(1.0f + __builtin_amdgcn_exp2f(-2.0f * 1.4426950408889634f * u)); }
; #define EPI_ROWS(...) _Pragma("unroll") for (int ai = 0; ai < 2; ++ai) _Pragma("unroll") for (int m = 0; m < 4; ++m) { const int rr = ai * 128 + wr * 64 + m * 16 + fr; __VA_ARGS__ }
; #define EPI_COLS8(...) _Pragma("unroll") for (int bj = 0; bj < 2; ++bj) { const int cc = bj * 128 + wc * 32 + 8 * fq; const f32x4 v0 = acc[ai][bj][m][0], v1 = acc[ai][bj][m][1]; __VA_ARGS__ }
;     DI void operator()(const Acc& acc, int wr, int wc, int fr, int fq) const {
;         EPI_ROWS(const int chunk = row0 + rr; const bf16_t* ap = Ap + ((size_t)g * 2048 + chunk) * 384 + 128;
;             EPI_COLS8(const int r = cc >> 4, i = cc & 15; const u32x4 uw = *(const u32x4*)(ap + cc); const f32x4 d0 = *(const f32x4*)(dskip + g * 16 + i), d1 = *(const f32x4*)(dskip + g * 16 + i + 4);
;                 const float y0 = v0[0] + d0[0] * bflo(uw.x), y1 = v0[1] + d0[1] * bfhi(uw.x), y2 = v0[2] + d0[2] * bflo(uw.y), y3 = v0[3] + d0[3] * bfhi(uw.y);
;                 const float y4 = v1[0] + d1[0] * bflo(uw.z), y5 = v1[1] + d1[1] * bfhi(uw.z), y6 = v1[2] + d1[2] * bflo(uw.w), y7 = v1[3] + d1[3] * bfhi(uw.w);
;                 u32x4 w; w.x = pk2(gelu_tanh(y0), gelu_tanh(y1)); w.y = pk2(gelu_tanh(y2), gelu_tanh(y3)); w.z = pk2(gelu_tanh(y4), gelu_tanh(y5)); w.w = pk2(gelu_tanh(y6), gelu_tanh(y7));
;                 *(u32x4*)(z + ((size_t)chunk * 16 + r) * 512 + g * 16 + i) = w;))
	v_lshlrev_b32_e32 v106, 16, v90
	v_and_b32_e32 v107, 0xffff0000, v90
	v_lshlrev_b32_e32 v90, 16, v91
	v_and_b32_e32 v91, 0xffff0000, v91
	v_lshlrev_b32_e32 v108, 16, v92
	v_and_b32_e32 v109, 0xffff0000, v92
	v_lshlrev_b32_e32 v92, 16, v93
	v_and_b32_e32 v93, 0xffff0000, v93
	s_waitcnt vmcnt(1)
	v_pk_fma_f32 v[80:81], v[94:95], v[106:107], v[80:81]
	v_pk_fma_f32 v[82:83], v[96:97], v[90:91], v[82:83]
	s_waitcnt vmcnt(0)
	v_pk_fma_f32 v[84:85], v[98:99], v[108:109], v[84:85]
	v_pk_fma_f32 v[86:87], v[100:101], v[92:93], v[86:87]
	v_mul_f32_e32 v90, 0x3d372713, v80
	v_mul_f32_e32 v91, 0x3d372713, v81
	v_mul_f32_e32 v92, 0x3d372713, v82
	v_mul_f32_e32 v93, 0x3d372713, v83
	v_mul_f32_e32 v94, 0x3d372713, v84
	v_mul_f32_e32 v95, 0x3d372713, v85
	v_mul_f32_e32 v96, 0x3d372713, v86
	v_mul_f32_e32 v97, 0x3d372713, v87
	v_mul_f32_e32 v90, v80, v90
	v_mul_f32_e32 v91, v81, v91
	v_mul_f32_e32 v92, v82, v92
	v_mul_f32_e32 v93, v83, v93
	v_mul_f32_e32 v94, v84, v94
	v_mul_f32_e32 v95, v85, v95
	v_mul_f32_e32 v96, v86, v96
	v_mul_f32_e32 v97, v87, v97
	v_fma_f32 v90, v80, v90, v80
	v_fma_f32 v91, v81, v91, v81
	v_fma_f32 v92, v82, v92, v82
	v_fma_f32 v93, v83, v93, v83
	v_fma_f32 v94, v84, v94, v84
	v_fma_f32 v95, v85, v95, v85
	v_fma_f32 v96, v86, v96, v86
	v_fma_f32 v97, v87, v97, v87
	v_mul_f32_e32 v90, 0xc0135761, v90
	v_mul_f32_e32 v91, 0xc0135761, v91
	v_mul_f32_e32 v92, 0xc0135761, v92
	v_mul_f32_e32 v93, 0xc0135761, v93
	v_mul_f32_e32 v94, 0xc0135761, v94
	v_mul_f32_e32 v95, 0xc0135761, v95
	v_mul_f32_e32 v96, 0xc0135761, v96
	v_mul_f32_e32 v97, 0xc0135761, v97
	v_exp_f32_e32 v90, v90
	v_exp_f32_e32 v91, v91
	v_exp_f32_e32 v92, v92
	v_exp_f32_e32 v93, v93
	v_exp_f32_e32 v94, v94
	v_exp_f32_e32 v95, v95
	v_exp_f32_e32 v96, v96
	v_exp_f32_e32 v97, v97
	v_add_f32_e32 v90, 1.0, v90
	v_add_f32_e32 v91, 1.0, v91
	v_add_f32_e32 v92, 1.0, v92
	v_add_f32_e32 v93, 1.0, v93
	v_add_f32_e32 v94, 1.0, v94
	v_add_f32_e32 v95, 1.0, v95
	v_add_f32_e32 v96, 1.0, v96
	v_add_f32_e32 v97, 1.0, v97
	v_rcp_f32_e32 v90, v90
	v_rcp_f32_e32 v91, v91
	v_rcp_f32_e32 v92, v92
	v_rcp_f32_e32 v93, v93
	v_rcp_f32_e32 v94, v94
	v_rcp_f32_e32 v95, v95
	v_rcp_f32_e32 v96, v96
	v_rcp_f32_e32 v97, v97
	v_pk_mul_f32 v[80:81], v[80:81], v[90:91]
	v_pk_mul_f32 v[82:83], v[82:83], v[92:93]
	v_pk_mul_f32 v[84:85], v[84:85], v[94:95]
	v_pk_mul_f32 v[86:87], v[86:87], v[96:97]
	v_cvt_pk_bf16_f32 v80, v80, v81
	v_cvt_pk_bf16_f32 v81, v82, v83
	v_cvt_pk_bf16_f32 v82, v84, v85
	v_cvt_pk_bf16_f32 v83, v86, v87
	global_store_dwordx4 v[104:105], v[80:83], off
	global_load_dwordx4 v[80:83], v[88:89], off offset:256
	s_nop 0
	global_load_dwordx4 v[84:87], v152, s[0:1]
	global_load_dwordx4 v[90:93], v152, s[0:1] offset:16
	v_lshlrev_b64 v[94:95], 14, v[102:103]
	v_lshl_add_u64 v[94:95], s[26:27], 0, v[94:95]
	v_lshl_add_u64 v[96:97], v[94:95], 0, v[134:135]
	v_lshl_add_u64 v[96:97], v[96:97], 0, s[38:39]
	v_lshl_add_u64 v[96:97], v[96:97], 0, v[132:133]
	s_waitcnt vmcnt(2)
	v_lshlrev_b32_e32 v98, 16, v80
	v_and_b32_e32 v99, 0xffff0000, v80
	v_lshlrev_b32_e32 v80, 16, v81
	v_and_b32_e32 v81, 0xffff0000, v81
	v_lshlrev_b32_e32 v100, 16, v82
	v_and_b32_e32 v101, 0xffff0000, v82
	v_lshlrev_b32_e32 v82, 16, v83
	v_and_b32_e32 v83, 0xffff0000, v83
	s_waitcnt vmcnt(1)
	v_pk_fma_f32 v[72:73], v[84:85], v[98:99], v[72:73]
	v_pk_fma_f32 v[74:75], v[86:87], v[80:81], v[74:75]
	s_waitcnt vmcnt(0)
	v_pk_fma_f32 v[76:77], v[90:91], v[100:101], v[76:77]
	v_pk_fma_f32 v[78:79], v[92:93], v[82:83], v[78:79]
	v_mul_f32_e32 v80, 0x3d372713, v72
	v_mul_f32_e32 v81, 0x3d372713, v73
	v_mul_f32_e32 v82, 0x3d372713, v74
	v_mul_f32_e32 v83, 0x3d372713, v75
	v_mul_f32_e32 v84, 0x3d372713, v76
	v_mul_f32_e32 v85, 0x3d372713, v77
	v_mul_f32_e32 v86, 0x3d372713, v78
	v_mul_f32_e32 v87, 0x3d372713, v79
	v_mul_f32_e32 v80, v72, v80
	v_mul_f32_e32 v81, v73, v81
	v_mul_f32_e32 v82, v74, v82
	v_mul_f32_e32 v83, v75, v83
	v_mul_f32_e32 v84, v76, v84
	v_mul_f32_e32 v85, v77, v85
	v_mul_f32_e32 v86, v78, v86
	v_mul_f32_e32 v87, v79, v87
	v_fma_f32 v80, v72, v80, v72
	v_fma_f32 v81, v73, v81, v73
	v_fma_f32 v82, v74, v82, v74
	v_fma_f32 v83, v75, v83, v75
	v_fma_f32 v84, v76, v84, v76
	v_fma_f32 v85, v77, v85, v77
	v_fma_f32 v86, v78, v86, v78
	v_fma_f32 v87, v79, v87, v79
	v_mul_f32_e32 v80, 0xc0135761, v80
	v_mul_f32_e32 v81, 0xc0135761, v81
	v_mul_f32_e32 v82, 0xc0135761, v82
	v_mul_f32_e32 v83, 0xc0135761, v83
	v_mul_f32_e32 v84, 0xc0135761, v84
	v_mul_f32_e32 v85, 0xc0135761, v85
	v_mul_f32_e32 v86, 0xc0135761, v86
	v_mul_f32_e32 v87, 0xc0135761, v87
	v_exp_f32_e32 v80, v80
	v_exp_f32_e32 v81, v81
	v_exp_f32_e32 v82, v82
	v_exp_f32_e32 v83, v83
	v_exp_f32_e32 v84, v84
	v_exp_f32_e32 v85, v85
	v_exp_f32_e32 v86, v86
	v_exp_f32_e32 v87, v87
	v_add_f32_e32 v80, 1.0, v80
	v_add_f32_e32 v81, 1.0, v81
	v_add_f32_e32 v82, 1.0, v82
	v_add_f32_e32 v83, 1.0, v83
	v_add_f32_e32 v84, 1.0, v84
	v_add_f32_e32 v85, 1.0, v85
	v_add_f32_e32 v86, 1.0, v86
	v_add_f32_e32 v87, 1.0, v87
	v_rcp_f32_e32 v80, v80
	v_rcp_f32_e32 v81, v81
	v_rcp_f32_e32 v82, v82
	v_rcp_f32_e32 v83, v83
	v_rcp_f32_e32 v84, v84
	v_rcp_f32_e32 v85, v85
	v_rcp_f32_e32 v86, v86
	v_rcp_f32_e32 v87, v87
	v_pk_mul_f32 v[72:73], v[72:73], v[80:81]
	v_pk_mul_f32 v[74:75], v[74:75], v[82:83]
	v_pk_mul_f32 v[76:77], v[76:77], v[84:85]
	v_pk_mul_f32 v[78:79], v[78:79], v[86:87]
	v_cvt_pk_bf16_f32 v72, v72, v73
	v_cvt_pk_bf16_f32 v73, v74, v75
	v_cvt_pk_bf16_f32 v74, v76, v77
	v_cvt_pk_bf16_f32 v75, v78, v79
	global_store_dwordx4 v[96:97], v[72:75], off
	global_load_dwordx4 v[74:77], v[88:89], off offset:512
	s_nop 0
	global_load_dwordx4 v[78:81], v152, s[0:1]
	global_load_dwordx4 v[82:85], v152, s[0:1] offset:16
	v_add_u32_e32 v86, 0x80, v140
	v_ashrrev_i32_e32 v87, 31, v86
	v_lshl_add_u64 v[72:73], s[40:41], 0, v[86:87]
	v_mad_u64_u32 v[90:91], s[66:67], v72, s46, v[142:143]
	v_mad_i32_i24 v91, v73, s46, v91
	v_lshl_add_u64 v[72:73], v[90:91], 0, v[138:139]
	v_lshl_add_u64 v[88:89], v[94:95], 0, v[136:137]
	v_lshl_add_u64 v[88:89], v[88:89], 0, s[38:39]
	v_lshl_add_u64 v[88:89], v[88:89], 0, v[132:133]
	s_waitcnt vmcnt(2)
; DI float bflo(unsigned w) { return __uint_as_float(w << 16); }
; DI float bfhi(unsigned w) { return __uint_as_float(w & 0xffff0000u); }
; DI float gelu_tanh(float y) { const float u = 0.7978845608028654f * (y + 0.044715f * y * y * y); return y * __builtin_amdgcn_rcpf(1.0f + __builtin_amdgcn_exp2f(-2.0f * 1.4426950408889634f * u)); }
; #define EPI_ROWS(...) _Pragma("unroll") for (int ai = 0; ai < 2; ++ai) _Pragma("unroll") for (int m = 0; m < 4; ++m) { const int rr = ai * 128 + wr * 64 + m * 16 + fr; __VA_ARGS__ }
; #define EPI_COLS8(...) _Pragma("unroll") for (int bj = 0; bj < 2; ++bj) { const int cc = bj * 128 + wc * 32 + 8 * fq; const f32x4 v0 = acc[ai][bj][m][0], v1 = acc[ai][bj][m][1]; __VA_ARGS__ }
;     DI void operator()(const Acc& acc, int wr, int wc, int fr, int fq) const {
;         EPI_ROWS(const int chunk = row0 + rr; const bf16_t* ap = Ap + ((size_t)g * 2048 + chunk) * 384 + 128;
;             EPI_COLS8(const int r = cc >> 4, i = cc & 15; const u32x4 uw = *(const u32x4*)(ap + cc); const f32x4 d0 = *(const f32x4*)(dskip + g * 16 + i), d1 = *(const f32x4*)(dskip + g * 16 + i + 4);
;                 const float y0 = v0[0] + d0[0] * bflo(uw.x), y1 = v0[1] + d0[1] * bfhi(uw.x), y2 = v0[2] + d0[2] * bflo(uw.y), y3 = v0[3] + d0[3] * bfhi(uw.y);
;                 const float y4 = v1[0] + d1[0] * bflo(uw.z), y5 = v1[1] + d1[1] * bfhi(uw.z), y6 = v1[2] + d1[2] * bflo(uw.w), y7 = v1[3] + d1[3] * bfhi(uw.w);
;                 u32x4 w; w.x = pk2(gelu_tanh(y0), gelu_tanh(y1)); w.y = pk2(gelu_tanh(y2), gelu_tanh(y3)); w.z = pk2(gelu_tanh(y4), gelu_tanh(y5)); w.w = pk2(gelu_tanh(y6), gelu_tanh(y7));
;                 *(u32x4*)(z + ((size_t)chunk * 16 + r) * 512 + g * 16 + i) = w;))
	v_lshlrev_b32_e32 v90, 16, v74
	v_and_b32_e32 v91, 0xffff0000, v74
	v_lshlrev_b32_e32 v74, 16, v75
	v_and_b32_e32 v75, 0xffff0000, v75
	v_lshlrev_b32_e32 v92, 16, v76
	v_and_b32_e32 v93, 0xffff0000, v76
	v_lshlrev_b32_e32 v76, 16, v77
	v_and_b32_e32 v77, 0xffff0000, v77
	s_waitcnt vmcnt(1)
	v_pk_fma_f32 v[64:65], v[78:79], v[90:91], v[64:65]
	v_pk_fma_f32 v[66:67], v[80:81], v[74:75], v[66:67]
	s_waitcnt vmcnt(0)
	v_pk_fma_f32 v[68:69], v[82:83], v[92:93], v[68:69]
	v_pk_fma_f32 v[70:71], v[84:85], v[76:77], v[70:71]
	v_mul_f32_e32 v74, 0x3d372713, v64
	v_mul_f32_e32 v75, 0x3d372713, v65
	v_mul_f32_e32 v76, 0x3d372713, v66
	v_mul_f32_e32 v77, 0x3d372713, v67
	v_mul_f32_e32 v78, 0x3d372713, v68
	v_mul_f32_e32 v79, 0x3d372713, v69
	v_mul_f32_e32 v80, 0x3d372713, v70
	v_mul_f32_e32 v81, 0x3d372713, v71
	v_mul_f32_e32 v74, v64, v74
	v_mul_f32_e32 v75, v65, v75
	v_mul_f32_e32 v76, v66, v76
	v_mul_f32_e32 v77, v67, v77
	v_mul_f32_e32 v78, v68, v78
	v_mul_f32_e32 v79, v69, v79
	v_mul_f32_e32 v80, v70, v80
	v_mul_f32_e32 v81, v71, v81
	v_fma_f32 v74, v64, v74, v64
	v_fma_f32 v75, v65, v75, v65
	v_fma_f32 v76, v66, v76, v66
	v_fma_f32 v77, v67, v77, v67
	v_fma_f32 v78, v68, v78, v68
	v_fma_f32 v79, v69, v79, v69
	v_fma_f32 v80, v70, v80, v70
	v_fma_f32 v81, v71, v81, v71
	v_mul_f32_e32 v74, 0xc0135761, v74
	v_mul_f32_e32 v75, 0xc0135761, v75
	v_mul_f32_e32 v76, 0xc0135761, v76
	v_mul_f32_e32 v77, 0xc0135761, v77
	v_mul_f32_e32 v78, 0xc0135761, v78
	v_mul_f32_e32 v79, 0xc0135761, v79
	v_mul_f32_e32 v80, 0xc0135761, v80
	v_mul_f32_e32 v81, 0xc0135761, v81
	v_exp_f32_e32 v74, v74
	v_exp_f32_e32 v75, v75
	v_exp_f32_e32 v76, v76
	v_exp_f32_e32 v77, v77
	v_exp_f32_e32 v78, v78
	v_exp_f32_e32 v79, v79
	v_exp_f32_e32 v80, v80
	v_exp_f32_e32 v81, v81
	v_add_f32_e32 v74, 1.0, v74
	v_add_f32_e32 v75, 1.0, v75
	v_add_f32_e32 v76, 1.0, v76
	v_add_f32_e32 v77, 1.0, v77
	v_add_f32_e32 v78, 1.0, v78
	v_add_f32_e32 v79, 1.0, v79
	v_add_f32_e32 v80, 1.0, v80
	v_add_f32_e32 v81, 1.0, v81
	v_rcp_f32_e32 v74, v74
	v_rcp_f32_e32 v75, v75
	v_rcp_f32_e32 v76, v76
	v_rcp_f32_e32 v77, v77
	v_rcp_f32_e32 v78, v78
	v_rcp_f32_e32 v79, v79
	v_rcp_f32_e32 v80, v80
	v_rcp_f32_e32 v81, v81
	v_pk_mul_f32 v[64:65], v[64:65], v[74:75]
	v_pk_mul_f32 v[66:67], v[66:67], v[76:77]
	v_pk_mul_f32 v[68:69], v[68:69], v[78:79]
	v_pk_mul_f32 v[70:71], v[70:71], v[80:81]
	v_cvt_pk_bf16_f32 v64, v64, v65
	v_cvt_pk_bf16_f32 v65, v66, v67
	v_cvt_pk_bf16_f32 v66, v68, v69
	v_cvt_pk_bf16_f32 v67, v70, v71
	global_store_dwordx4 v[88:89], v[64:67], off
	global_load_dwordx4 v[64:67], v[72:73], off offset:256
	s_nop 0
	global_load_dwordx4 v[68:71], v152, s[0:1]
	global_load_dwordx4 v[74:77], v152, s[0:1] offset:16
	v_lshlrev_b64 v[78:79], 14, v[86:87]
	v_lshl_add_u64 v[78:79], s[26:27], 0, v[78:79]
	v_lshl_add_u64 v[80:81], v[78:79], 0, v[134:135]
	v_lshl_add_u64 v[80:81], v[80:81], 0, s[38:39]
	v_lshl_add_u64 v[80:81], v[80:81], 0, v[132:133]
	s_waitcnt vmcnt(2)
	v_lshlrev_b32_e32 v82, 16, v64
	v_and_b32_e32 v83, 0xffff0000, v64
	v_lshlrev_b32_e32 v64, 16, v65
	v_and_b32_e32 v65, 0xffff0000, v65
	v_lshlrev_b32_e32 v84, 16, v66
	v_and_b32_e32 v85, 0xffff0000, v66
	v_lshlrev_b32_e32 v66, 16, v67
	v_and_b32_e32 v67, 0xffff0000, v67
	s_waitcnt vmcnt(1)
	v_pk_fma_f32 v[56:57], v[68:69], v[82:83], v[56:57]
	v_pk_fma_f32 v[58:59], v[70:71], v[64:65], v[58:59]
	s_waitcnt vmcnt(0)
	v_pk_fma_f32 v[60:61], v[74:75], v[84:85], v[60:61]
	v_pk_fma_f32 v[62:63], v[76:77], v[66:67], v[62:63]
	v_mul_f32_e32 v64, 0x3d372713, v56
	v_mul_f32_e32 v65, 0x3d372713, v57
	v_mul_f32_e32 v66, 0x3d372713, v58
	v_mul_f32_e32 v67, 0x3d372713, v59
	v_mul_f32_e32 v68, 0x3d372713, v60
	v_mul_f32_e32 v69, 0x3d372713, v61
	v_mul_f32_e32 v70, 0x3d372713, v62
	v_mul_f32_e32 v71, 0x3d372713, v63
	v_mul_f32_e32 v64, v56, v64
	v_mul_f32_e32 v65, v57, v65
	v_mul_f32_e32 v66, v58, v66
	v_mul_f32_e32 v67, v59, v67
	v_mul_f32_e32 v68, v60, v68
	v_mul_f32_e32 v69, v61, v69
	v_mul_f32_e32 v70, v62, v70
	v_mul_f32_e32 v71, v63, v71
	v_fma_f32 v64, v56, v64, v56
	v_fma_f32 v65, v57, v65, v57
	v_fma_f32 v66, v58, v66, v58
	v_fma_f32 v67, v59, v67, v59
	v_fma_f32 v68, v60, v68, v60
	v_fma_f32 v69, v61, v69, v61
	v_fma_f32 v70, v62, v70, v62
	v_fma_f32 v71, v63, v71, v63
	v_mul_f32_e32 v64, 0xc0135761, v64
	v_mul_f32_e32 v65, 0xc0135761, v65
	v_mul_f32_e32 v66, 0xc0135761, v66
	v_mul_f32_e32 v67, 0xc0135761, v67
	v_mul_f32_e32 v68, 0xc0135761, v68
	v_mul_f32_e32 v69, 0xc0135761, v69
	v_mul_f32_e32 v70, 0xc0135761, v70
	v_mul_f32_e32 v71, 0xc0135761, v71
	v_exp_f32_e32 v64, v64
	v_exp_f32_e32 v65, v65
	v_exp_f32_e32 v66, v66
	v_exp_f32_e32 v67, v67
	v_exp_f32_e32 v68, v68
	v_exp_f32_e32 v69, v69
	v_exp_f32_e32 v70, v70
	v_exp_f32_e32 v71, v71
	v_add_f32_e32 v64, 1.0, v64
	v_add_f32_e32 v65, 1.0, v65
	v_add_f32_e32 v66, 1.0, v66
	v_add_f32_e32 v67, 1.0, v67
	v_add_f32_e32 v68, 1.0, v68
	v_add_f32_e32 v69, 1.0, v69
	v_add_f32_e32 v70, 1.0, v70
	v_add_f32_e32 v71, 1.0, v71
	v_rcp_f32_e32 v64, v64
	v_rcp_f32_e32 v65, v65
	v_rcp_f32_e32 v66, v66
	v_rcp_f32_e32 v67, v67
	v_rcp_f32_e32 v68, v68
	v_rcp_f32_e32 v69, v69
	v_rcp_f32_e32 v70, v70
	v_rcp_f32_e32 v71, v71
	v_pk_mul_f32 v[56:57], v[56:57], v[64:65]
	v_pk_mul_f32 v[58:59], v[58:59], v[66:67]
	v_pk_mul_f32 v[60:61], v[60:61], v[68:69]
	v_pk_mul_f32 v[62:63], v[62:63], v[70:71]
	v_cvt_pk_bf16_f32 v56, v56, v57
	v_cvt_pk_bf16_f32 v57, v58, v59
	v_cvt_pk_bf16_f32 v58, v60, v61
	v_cvt_pk_bf16_f32 v59, v62, v63
	global_store_dwordx4 v[80:81], v[56:59], off
	global_load_dwordx4 v[58:61], v[72:73], off offset:512
	s_nop 0
	global_load_dwordx4 v[62:65], v152, s[0:1]
	global_load_dwordx4 v[66:69], v152, s[0:1] offset:16
	v_add_u32_e32 v70, 0x90, v140
	v_ashrrev_i32_e32 v71, 31, v70
	v_lshl_add_u64 v[56:57], s[40:41], 0, v[70:71]
	v_mad_u64_u32 v[72:73], s[66:67], v56, s46, v[142:143]
	v_lshl_add_u64 v[74:75], v[78:79], 0, v[136:137]
	v_mad_i32_i24 v73, v57, s46, v73
	v_lshl_add_u64 v[74:75], v[74:75], 0, s[38:39]
	v_lshl_add_u64 v[56:57], v[72:73], 0, v[138:139]
	v_lshl_add_u64 v[72:73], v[74:75], 0, v[132:133]
	s_waitcnt vmcnt(2)
; DI float bflo(unsigned w) { return __uint_as_float(w << 16); }
; DI float bfhi(unsigned w) { return __uint_as_float(w & 0xffff0000u); }
; DI float gelu_tanh(float y) { const float u = 0.7978845608028654f * (y + 0.044715f * y * y * y); return y * __builtin_amdgcn_rcpf(1.0f + __builtin_amdgcn_exp2f(-2.0f * 1.4426950408889634f * u)); }
; #define EPI_ROWS(...) _Pragma("unroll") for (int ai = 0; ai < 2; ++ai) _Pragma("unroll") for (int m = 0; m < 4; ++m) { const int rr = ai * 128 + wr * 64 + m * 16 + fr; __VA_ARGS__ }
; #define EPI_COLS8(...) _Pragma("unroll") for (int bj = 0; bj < 2; ++bj) { const int cc = bj * 128 + wc * 32 + 8 * fq; const f32x4 v0 = acc[ai][bj][m][0], v1 = acc[ai][bj][m][1]; __VA_ARGS__ }
;     DI void operator()(const Acc& acc, int wr, int wc, int fr, int fq) const {
;         EPI_ROWS(const int chunk = row0 + rr; const bf16_t* ap = Ap + ((size_t)g * 2048 + chunk) * 384 + 128;
;             EPI_COLS8(const int r = cc >> 4, i = cc & 15; const u32x4 uw = *(const u32x4*)(ap + cc); const f32x4 d0 = *(const f32x4*)(dskip + g * 16 + i), d1 = *(const f32x4*)(dskip + g * 16 + i + 4);
;                 const float y0 = v0[0] + d0[0] * bflo(uw.x), y1 = v0[1] + d0[1] * bfhi(uw.x), y2 = v0[2] + d0[2] * bflo(uw.y), y3 = v0[3] + d0[3] * bfhi(uw.y);
;                 const float y4 = v1[0] + d1[0] * bflo(uw.z), y5 = v1[1] + d1[1] * bfhi(uw.z), y6 = v1[2] + d1[2] * bflo(uw.w), y7 = v1[3] + d1[3] * bfhi(uw.w);
;                 u32x4 w; w.x = pk2(gelu_tanh(y0), gelu_tanh(y1)); w.y = pk2(gelu_tanh(y2), gelu_tanh(y3)); w.z = pk2(gelu_tanh(y4), gelu_tanh(y5)); w.w = pk2(gelu_tanh(y6), gelu_tanh(y7));
;                 *(u32x4*)(z + ((size_t)chunk * 16 + r) * 512 + g * 16 + i) = w;))
	v_lshlrev_b32_e32 v74, 16, v58
	v_and_b32_e32 v75, 0xffff0000, v58
	v_lshlrev_b32_e32 v58, 16, v59
	v_and_b32_e32 v59, 0xffff0000, v59
	v_lshlrev_b32_e32 v76, 16, v60
	v_and_b32_e32 v77, 0xffff0000, v60
	v_lshlrev_b32_e32 v60, 16, v61
	v_and_b32_e32 v61, 0xffff0000, v61
	s_waitcnt vmcnt(1)
	v_pk_fma_f32 v[48:49], v[62:63], v[74:75], v[48:49]
	v_pk_fma_f32 v[50:51], v[64:65], v[58:59], v[50:51]
	s_waitcnt vmcnt(0)
	v_pk_fma_f32 v[52:53], v[66:67], v[76:77], v[52:53]
	v_pk_fma_f32 v[54:55], v[68:69], v[60:61], v[54:55]
	v_mul_f32_e32 v58, 0x3d372713, v48
	v_mul_f32_e32 v59, 0x3d372713, v49
	v_mul_f32_e32 v60, 0x3d372713, v50
	v_mul_f32_e32 v61, 0x3d372713, v51
	v_mul_f32_e32 v62, 0x3d372713, v52
	v_mul_f32_e32 v63, 0x3d372713, v53
	v_mul_f32_e32 v64, 0x3d372713, v54
	v_mul_f32_e32 v65, 0x3d372713, v55
	v_mul_f32_e32 v58, v48, v58
	v_mul_f32_e32 v59, v49, v59
	v_mul_f32_e32 v60, v50, v60
	v_mul_f32_e32 v61, v51, v61
	v_mul_f32_e32 v62, v52, v62
	v_mul_f32_e32 v63, v53, v63
	v_mul_f32_e32 v64, v54, v64
	v_mul_f32_e32 v65, v55, v65
	v_fma_f32 v58, v48, v58, v48
	v_fma_f32 v59, v49, v59, v49
	v_fma_f32 v60, v50, v60, v50
	v_fma_f32 v61, v51, v61, v51
	v_fma_f32 v62, v52, v62, v52
	v_fma_f32 v63, v53, v63, v53
	v_fma_f32 v64, v54, v64, v54
	v_fma_f32 v65, v55, v65, v55
	v_mul_f32_e32 v58, 0xc0135761, v58
	v_mul_f32_e32 v59, 0xc0135761, v59
	v_mul_f32_e32 v60, 0xc0135761, v60
	v_mul_f32_e32 v61, 0xc0135761, v61
	v_mul_f32_e32 v62, 0xc0135761, v62
	v_mul_f32_e32 v63, 0xc0135761, v63
	v_mul_f32_e32 v64, 0xc0135761, v64
	v_mul_f32_e32 v65, 0xc0135761, v65
	v_exp_f32_e32 v58, v58
	v_exp_f32_e32 v59, v59
	v_exp_f32_e32 v60, v60
	v_exp_f32_e32 v61, v61
	v_exp_f32_e32 v62, v62
	v_exp_f32_e32 v63, v63
	v_exp_f32_e32 v64, v64
	v_exp_f32_e32 v65, v65
	v_add_f32_e32 v58, 1.0, v58
	v_add_f32_e32 v59, 1.0, v59
	v_add_f32_e32 v60, 1.0, v60
	v_add_f32_e32 v61, 1.0, v61
	v_add_f32_e32 v62, 1.0, v62
	v_add_f32_e32 v63, 1.0, v63
	v_add_f32_e32 v64, 1.0, v64
	v_add_f32_e32 v65, 1.0, v65
	v_rcp_f32_e32 v58, v58
	v_rcp_f32_e32 v59, v59
	v_rcp_f32_e32 v60, v60
	v_rcp_f32_e32 v61, v61
	v_rcp_f32_e32 v62, v62
	v_rcp_f32_e32 v63, v63
	v_rcp_f32_e32 v64, v64
	v_rcp_f32_e32 v65, v65
	v_pk_mul_f32 v[48:49], v[48:49], v[58:59]
	v_pk_mul_f32 v[50:51], v[50:51], v[60:61]
	v_pk_mul_f32 v[52:53], v[52:53], v[62:63]
	v_pk_mul_f32 v[54:55], v[54:55], v[64:65]
	v_cvt_pk_bf16_f32 v48, v48, v49
	v_cvt_pk_bf16_f32 v49, v50, v51
	v_cvt_pk_bf16_f32 v50, v52, v53
	v_cvt_pk_bf16_f32 v51, v54, v55
	global_store_dwordx4 v[72:73], v[48:51], off
	global_load_dwordx4 v[48:51], v[56:57], off offset:256
	s_nop 0
	global_load_dwordx4 v[52:55], v152, s[0:1]
	global_load_dwordx4 v[58:61], v152, s[0:1] offset:16
	v_lshlrev_b64 v[62:63], 14, v[70:71]
	v_lshl_add_u64 v[62:63], s[26:27], 0, v[62:63]
	v_lshl_add_u64 v[64:65], v[62:63], 0, v[134:135]
	v_lshl_add_u64 v[64:65], v[64:65], 0, s[38:39]
	v_lshl_add_u64 v[64:65], v[64:65], 0, v[132:133]
	s_waitcnt vmcnt(2)
	v_lshlrev_b32_e32 v66, 16, v48
	v_and_b32_e32 v67, 0xffff0000, v48
	v_lshlrev_b32_e32 v48, 16, v49
	v_and_b32_e32 v49, 0xffff0000, v49
	v_lshlrev_b32_e32 v68, 16, v50
	v_and_b32_e32 v69, 0xffff0000, v50
	v_lshlrev_b32_e32 v50, 16, v51
	v_and_b32_e32 v51, 0xffff0000, v51
	s_waitcnt vmcnt(1)
	v_pk_fma_f32 v[40:41], v[52:53], v[66:67], v[40:41]
	v_pk_fma_f32 v[42:43], v[54:55], v[48:49], v[42:43]
	s_waitcnt vmcnt(0)
	v_pk_fma_f32 v[44:45], v[58:59], v[68:69], v[44:45]
	v_pk_fma_f32 v[46:47], v[60:61], v[50:51], v[46:47]
	v_mul_f32_e32 v48, 0x3d372713, v40
	v_mul_f32_e32 v49, 0x3d372713, v41
	v_mul_f32_e32 v50, 0x3d372713, v42
	v_mul_f32_e32 v51, 0x3d372713, v43
	v_mul_f32_e32 v52, 0x3d372713, v44
	v_mul_f32_e32 v53, 0x3d372713, v45
	v_mul_f32_e32 v54, 0x3d372713, v46
	v_mul_f32_e32 v55, 0x3d372713, v47
	v_mul_f32_e32 v48, v40, v48
	v_mul_f32_e32 v49, v41, v49
	v_mul_f32_e32 v50, v42, v50
	v_mul_f32_e32 v51, v43, v51
	v_mul_f32_e32 v52, v44, v52
	v_mul_f32_e32 v53, v45, v53
	v_mul_f32_e32 v54, v46, v54
	v_mul_f32_e32 v55, v47, v55
	v_fma_f32 v48, v40, v48, v40
	v_fma_f32 v49, v41, v49, v41
	v_fma_f32 v50, v42, v50, v42
	v_fma_f32 v51, v43, v51, v43
	v_fma_f32 v52, v44, v52, v44
	v_fma_f32 v53, v45, v53, v45
	v_fma_f32 v54, v46, v54, v46
	v_fma_f32 v55, v47, v55, v47
	v_mul_f32_e32 v48, 0xc0135761, v48
	v_mul_f32_e32 v49, 0xc0135761, v49
	v_mul_f32_e32 v50, 0xc0135761, v50
	v_mul_f32_e32 v51, 0xc0135761, v51
	v_mul_f32_e32 v52, 0xc0135761, v52
	v_mul_f32_e32 v53, 0xc0135761, v53
	v_mul_f32_e32 v54, 0xc0135761, v54
	v_mul_f32_e32 v55, 0xc0135761, v55
	v_exp_f32_e32 v48, v48
	v_exp_f32_e32 v49, v49
	v_exp_f32_e32 v50, v50
	v_exp_f32_e32 v51, v51
	v_exp_f32_e32 v52, v52
	v_exp_f32_e32 v53, v53
	v_exp_f32_e32 v54, v54
	v_exp_f32_e32 v55, v55
	v_add_f32_e32 v48, 1.0, v48
	v_add_f32_e32 v49, 1.0, v49
	v_add_f32_e32 v50, 1.0, v50
	v_add_f32_e32 v51, 1.0, v51
	v_add_f32_e32 v52, 1.0, v52
	v_add_f32_e32 v53, 1.0, v53
	v_add_f32_e32 v54, 1.0, v54
	v_add_f32_e32 v55, 1.0, v55
	v_rcp_f32_e32 v48, v48
	v_rcp_f32_e32 v49, v49
	v_rcp_f32_e32 v50, v50
	v_rcp_f32_e32 v51, v51
	v_rcp_f32_e32 v52, v52
	v_rcp_f32_e32 v53, v53
	v_rcp_f32_e32 v54, v54
	v_rcp_f32_e32 v55, v55
	v_pk_mul_f32 v[40:41], v[40:41], v[48:49]
	v_pk_mul_f32 v[42:43], v[42:43], v[50:51]
	v_pk_mul_f32 v[44:45], v[44:45], v[52:53]
	v_pk_mul_f32 v[46:47], v[46:47], v[54:55]
	v_cvt_pk_bf16_f32 v40, v40, v41
	v_cvt_pk_bf16_f32 v41, v42, v43
	v_cvt_pk_bf16_f32 v42, v44, v45
	v_cvt_pk_bf16_f32 v43, v46, v47
	global_store_dwordx4 v[64:65], v[40:43], off
	global_load_dwordx4 v[42:45], v[56:57], off offset:512
	s_nop 0
	global_load_dwordx4 v[46:49], v152, s[0:1]
	global_load_dwordx4 v[50:53], v152, s[0:1] offset:16
	v_add_u32_e32 v54, 0xa0, v140
	v_ashrrev_i32_e32 v55, 31, v54
	v_lshl_add_u64 v[40:41], s[40:41], 0, v[54:55]
	v_mad_u64_u32 v[56:57], s[66:67], v40, s46, v[142:143]
	v_lshl_add_u64 v[58:59], v[62:63], 0, v[136:137]
	v_mad_i32_i24 v57, v41, s46, v57
	v_lshl_add_u64 v[58:59], v[58:59], 0, s[38:39]
	v_lshl_add_u64 v[40:41], v[56:57], 0, v[138:139]
	v_lshl_add_u64 v[56:57], v[58:59], 0, v[132:133]
	s_waitcnt vmcnt(2)
; DI float bflo(unsigned w) { return __uint_as_float(w << 16); }
; DI float bfhi(unsigned w) { return __uint_as_float(w & 0xffff0000u); }
; DI float gelu_tanh(float y) { const float u = 0.7978845608028654f * (y + 0.044715f * y * y * y); return y * __builtin_amdgcn_rcpf(1.0f + __builtin_amdgcn_exp2f(-2.0f * 1.4426950408889634f * u)); }
; #define EPI_ROWS(...) _Pragma("unroll") for (int ai = 0; ai < 2; ++ai) _Pragma("unroll") for (int m = 0; m < 4; ++m) { const int rr = ai * 128 + wr * 64 + m * 16 + fr; __VA_ARGS__ }
; #define EPI_COLS8(...) _Pragma("unroll") for (int bj = 0; bj < 2; ++bj) { const int cc = bj * 128 + wc * 32 + 8 * fq; const f32x4 v0 = acc[ai][bj][m][0], v1 = acc[ai][bj][m][1]; __VA_ARGS__ }
;     DI void operator()(const Acc& acc, int wr, int wc, int fr, int fq) const {
;         EPI_ROWS(const int chunk = row0 + rr; const bf16_t* ap = Ap + ((size_t)g * 2048 + chunk) * 384 + 128;
;             EPI_COLS8(const int r = cc >> 4, i = cc & 15; const u32x4 uw = *(const u32x4*)(ap + cc); const f32x4 d0 = *(const f32x4*)(dskip + g * 16 + i), d1 = *(const f32x4*)(dskip + g * 16 + i + 4);
;                 const float y0 = v0[0] + d0[0] * bflo(uw.x), y1 = v0[1] + d0[1] * bfhi(uw.x), y2 = v0[2] + d0[2] * bflo(uw.y), y3 = v0[3] + d0[3] * bfhi(uw.y);
;                 const float y4 = v1[0] + d1[0] * bflo(uw.z), y5 = v1[1] + d1[1] * bfhi(uw.z), y6 = v1[2] + d1[2] * bflo(uw.w), y7 = v1[3] + d1[3] * bfhi(uw.w);
;                 u32x4 w; w.x = pk2(gelu_tanh(y0), gelu_tanh(y1)); w.y = pk2(gelu_tanh(y2), gelu_tanh(y3)); w.z = pk2(gelu_tanh(y4), gelu_tanh(y5)); w.w = pk2(gelu_tanh(y6), gelu_tanh(y7));
;                 *(u32x4*)(z + ((size_t)chunk * 16 + r) * 512 + g * 16 + i) = w;))
	v_lshlrev_b32_e32 v58, 16, v42
	v_and_b32_e32 v59, 0xffff0000, v42
	v_lshlrev_b32_e32 v42, 16, v43
	v_and_b32_e32 v43, 0xffff0000, v43
	v_lshlrev_b32_e32 v60, 16, v44
	v_and_b32_e32 v61, 0xffff0000, v44
	v_lshlrev_b32_e32 v44, 16, v45
	v_and_b32_e32 v45, 0xffff0000, v45
	s_waitcnt vmcnt(1)
	v_pk_fma_f32 v[32:33], v[46:47], v[58:59], v[32:33]
	v_pk_fma_f32 v[34:35], v[48:49], v[42:43], v[34:35]
	s_waitcnt vmcnt(0)
	v_pk_fma_f32 v[36:37], v[50:51], v[60:61], v[36:37]
	v_pk_fma_f32 v[38:39], v[52:53], v[44:45], v[38:39]
	v_mul_f32_e32 v42, 0x3d372713, v32
	v_mul_f32_e32 v43, 0x3d372713, v33
	v_mul_f32_e32 v44, 0x3d372713, v34
	v_mul_f32_e32 v45, 0x3d372713, v35
	v_mul_f32_e32 v46, 0x3d372713, v36
	v_mul_f32_e32 v47, 0x3d372713, v37
	v_mul_f32_e32 v48, 0x3d372713, v38
	v_mul_f32_e32 v49, 0x3d372713, v39
	v_mul_f32_e32 v42, v32, v42
	v_mul_f32_e32 v43, v33, v43
	v_mul_f32_e32 v44, v34, v44
	v_mul_f32_e32 v45, v35, v45
	v_mul_f32_e32 v46, v36, v46
	v_mul_f32_e32 v47, v37, v47
	v_mul_f32_e32 v48, v38, v48
	v_mul_f32_e32 v49, v39, v49
	v_fma_f32 v42, v32, v42, v32
	v_fma_f32 v43, v33, v43, v33
	v_fma_f32 v44, v34, v44, v34
	v_fma_f32 v45, v35, v45, v35
	v_fma_f32 v46, v36, v46, v36
	v_fma_f32 v47, v37, v47, v37
	v_fma_f32 v48, v38, v48, v38
	v_fma_f32 v49, v39, v49, v39
	v_mul_f32_e32 v42, 0xc0135761, v42
	v_mul_f32_e32 v43, 0xc0135761, v43
	v_mul_f32_e32 v44, 0xc0135761, v44
	v_mul_f32_e32 v45, 0xc0135761, v45
	v_mul_f32_e32 v46, 0xc0135761, v46
	v_mul_f32_e32 v47, 0xc0135761, v47
	v_mul_f32_e32 v48, 0xc0135761, v48
	v_mul_f32_e32 v49, 0xc0135761, v49
	v_exp_f32_e32 v42, v42
	v_exp_f32_e32 v43, v43
	v_exp_f32_e32 v44, v44
	v_exp_f32_e32 v45, v45
	v_exp_f32_e32 v46, v46
	v_exp_f32_e32 v47, v47
	v_exp_f32_e32 v48, v48
	v_exp_f32_e32 v49, v49
	v_add_f32_e32 v42, 1.0, v42
	v_add_f32_e32 v43, 1.0, v43
	v_add_f32_e32 v44, 1.0, v44
	v_add_f32_e32 v45, 1.0, v45
	v_add_f32_e32 v46, 1.0, v46
	v_add_f32_e32 v47, 1.0, v47
	v_add_f32_e32 v48, 1.0, v48
	v_add_f32_e32 v49, 1.0, v49
	v_rcp_f32_e32 v42, v42
	v_rcp_f32_e32 v43, v43
	v_rcp_f32_e32 v44, v44
	v_rcp_f32_e32 v45, v45
	v_rcp_f32_e32 v46, v46
	v_rcp_f32_e32 v47, v47
	v_rcp_f32_e32 v48, v48
	v_rcp_f32_e32 v49, v49
	v_pk_mul_f32 v[32:33], v[32:33], v[42:43]
	v_pk_mul_f32 v[34:35], v[34:35], v[44:45]
	v_pk_mul_f32 v[36:37], v[36:37], v[46:47]
	v_pk_mul_f32 v[38:39], v[38:39], v[48:49]
	v_cvt_pk_bf16_f32 v32, v32, v33
	v_cvt_pk_bf16_f32 v33, v34, v35
	v_cvt_pk_bf16_f32 v34, v36, v37
	v_cvt_pk_bf16_f32 v35, v38, v39
	global_store_dwordx4 v[56:57], v[32:35], off
	global_load_dwordx4 v[32:35], v[40:41], off offset:256
	s_nop 0
	global_load_dwordx4 v[36:39], v152, s[0:1]
	global_load_dwordx4 v[42:45], v152, s[0:1] offset:16
	v_lshlrev_b64 v[46:47], 14, v[54:55]
	v_lshl_add_u64 v[46:47], s[26:27], 0, v[46:47]
	v_lshl_add_u64 v[48:49], v[46:47], 0, v[134:135]
	v_lshl_add_u64 v[48:49], v[48:49], 0, s[38:39]
	v_lshl_add_u64 v[48:49], v[48:49], 0, v[132:133]
	s_waitcnt vmcnt(2)
	v_lshlrev_b32_e32 v50, 16, v32
	v_and_b32_e32 v51, 0xffff0000, v32
	v_lshlrev_b32_e32 v32, 16, v33
	v_and_b32_e32 v33, 0xffff0000, v33
	v_lshlrev_b32_e32 v52, 16, v34
	v_and_b32_e32 v53, 0xffff0000, v34
	v_lshlrev_b32_e32 v34, 16, v35
	v_and_b32_e32 v35, 0xffff0000, v35
	s_waitcnt vmcnt(1)
	v_pk_fma_f32 v[24:25], v[36:37], v[50:51], v[24:25]
	v_pk_fma_f32 v[26:27], v[38:39], v[32:33], v[26:27]
	s_waitcnt vmcnt(0)
	v_pk_fma_f32 v[28:29], v[42:43], v[52:53], v[28:29]
	v_pk_fma_f32 v[30:31], v[44:45], v[34:35], v[30:31]
	v_mul_f32_e32 v32, 0x3d372713, v24
	v_mul_f32_e32 v33, 0x3d372713, v25
	v_mul_f32_e32 v34, 0x3d372713, v26
	v_mul_f32_e32 v35, 0x3d372713, v27
	v_mul_f32_e32 v36, 0x3d372713, v28
	v_mul_f32_e32 v37, 0x3d372713, v29
	v_mul_f32_e32 v38, 0x3d372713, v30
	v_mul_f32_e32 v39, 0x3d372713, v31
	v_mul_f32_e32 v32, v24, v32
	v_mul_f32_e32 v33, v25, v33
	v_mul_f32_e32 v34, v26, v34
	v_mul_f32_e32 v35, v27, v35
	v_mul_f32_e32 v36, v28, v36
	v_mul_f32_e32 v37, v29, v37
	v_mul_f32_e32 v38, v30, v38
	v_mul_f32_e32 v39, v31, v39
	v_fma_f32 v32, v24, v32, v24
	v_fma_f32 v33, v25, v33, v25
	v_fma_f32 v34, v26, v34, v26
	v_fma_f32 v35, v27, v35, v27
	v_fma_f32 v36, v28, v36, v28
	v_fma_f32 v37, v29, v37, v29
	v_fma_f32 v38, v30, v38, v30
	v_fma_f32 v39, v31, v39, v31
	v_mul_f32_e32 v32, 0xc0135761, v32
	v_mul_f32_e32 v33, 0xc0135761, v33
	v_mul_f32_e32 v34, 0xc0135761, v34
	v_mul_f32_e32 v35, 0xc0135761, v35
	v_mul_f32_e32 v36, 0xc0135761, v36
	v_mul_f32_e32 v37, 0xc0135761, v37
	v_mul_f32_e32 v38, 0xc0135761, v38
	v_mul_f32_e32 v39, 0xc0135761, v39
	v_exp_f32_e32 v32, v32
	v_exp_f32_e32 v33, v33
	v_exp_f32_e32 v34, v34
	v_exp_f32_e32 v35, v35
	v_exp_f32_e32 v36, v36
	v_exp_f32_e32 v37, v37
	v_exp_f32_e32 v38, v38
	v_exp_f32_e32 v39, v39
	v_add_f32_e32 v32, 1.0, v32
	v_add_f32_e32 v33, 1.0, v33
	v_add_f32_e32 v34, 1.0, v34
	v_add_f32_e32 v35, 1.0, v35
	v_add_f32_e32 v36, 1.0, v36
	v_add_f32_e32 v37, 1.0, v37
	v_add_f32_e32 v38, 1.0, v38
	v_add_f32_e32 v39, 1.0, v39
	v_rcp_f32_e32 v32, v32
	v_rcp_f32_e32 v33, v33
	v_rcp_f32_e32 v34, v34
	v_rcp_f32_e32 v35, v35
	v_rcp_f32_e32 v36, v36
	v_rcp_f32_e32 v37, v37
	v_rcp_f32_e32 v38, v38
	v_rcp_f32_e32 v39, v39
	v_pk_mul_f32 v[24:25], v[24:25], v[32:33]
	v_pk_mul_f32 v[26:27], v[26:27], v[34:35]
	v_pk_mul_f32 v[28:29], v[28:29], v[36:37]
	v_pk_mul_f32 v[30:31], v[30:31], v[38:39]
	v_cvt_pk_bf16_f32 v24, v24, v25
	v_cvt_pk_bf16_f32 v25, v26, v27
	v_cvt_pk_bf16_f32 v26, v28, v29
	v_cvt_pk_bf16_f32 v27, v30, v31
	global_store_dwordx4 v[48:49], v[24:27], off
	global_load_dwordx4 v[26:29], v[40:41], off offset:512
	s_nop 0
	global_load_dwordx4 v[30:33], v152, s[0:1]
	global_load_dwordx4 v[34:37], v152, s[0:1] offset:16
	v_add_u32_e32 v38, 0xb0, v140
	v_ashrrev_i32_e32 v39, 31, v38
	v_lshl_add_u64 v[24:25], s[40:41], 0, v[38:39]
	v_mad_u64_u32 v[40:41], s[40:41], v24, s46, v[142:143]
	v_lshl_add_u64 v[42:43], v[46:47], 0, v[136:137]
	v_mad_i32_i24 v41, v25, s46, v41
	v_lshl_add_u64 v[42:43], v[42:43], 0, s[38:39]
	v_lshl_add_u64 v[24:25], v[40:41], 0, v[138:139]
	v_lshl_add_u64 v[40:41], v[42:43], 0, v[132:133]
	s_waitcnt vmcnt(2)
; DI float bflo(unsigned w) { return __uint_as_float(w << 16); }
; DI float bfhi(unsigned w) { return __uint_as_float(w & 0xffff0000u); }
; DI float gelu_tanh(float y) { const float u = 0.7978845608028654f * (y + 0.044715f * y * y * y); return y * __builtin_amdgcn_rcpf(1.0f + __builtin_amdgcn_exp2f(-2.0f * 1.4426950408889634f * u)); }
; #define EPI_ROWS(...) _Pragma("unroll") for (int ai = 0; ai < 2; ++ai) _Pragma("unroll") for (int m = 0; m < 4; ++m) { const int rr = ai * 128 + wr * 64 + m * 16 + fr; __VA_ARGS__ }
; #define EPI_COLS8(...) _Pragma("unroll") for (int bj = 0; bj < 2; ++bj) { const int cc = bj * 128 + wc * 32 + 8 * fq; const f32x4 v0 = acc[ai][bj][m][0], v1 = acc[ai][bj][m][1]; __VA_ARGS__ }
;     DI void operator()(const Acc& acc, int wr, int wc, int fr, int fq) const {
;         EPI_ROWS(const int chunk = row0 + rr; const bf16_t* ap = Ap + ((size_t)g * 2048 + chunk) * 384 + 128;
;             EPI_COLS8(const int r = cc >> 4, i = cc & 15; const u32x4 uw = *(const u32x4*)(ap + cc); const f32x4 d0 = *(const f32x4*)(dskip + g * 16 + i), d1 = *(const f32x4*)(dskip + g * 16 + i + 4);
;                 const float y0 = v0[0] + d0[0] * bflo(uw.x), y1 = v0[1] + d0[1] * bfhi(uw.x), y2 = v0[2] + d0[2] * bflo(uw.y), y3 = v0[3] + d0[3] * bfhi(uw.y);
;                 const float y4 = v1[0] + d1[0] * bflo(uw.z), y5 = v1[1] + d1[1] * bfhi(uw.z), y6 = v1[2] + d1[2] * bflo(uw.w), y7 = v1[3] + d1[3] * bfhi(uw.w);
;                 u32x4 w; w.x = pk2(gelu_tanh(y0), gelu_tanh(y1)); w.y = pk2(gelu_tanh(y2), gelu_tanh(y3)); w.z = pk2(gelu_tanh(y4), gelu_tanh(y5)); w.w = pk2(gelu_tanh(y6), gelu_tanh(y7));
;                 *(u32x4*)(z + ((size_t)chunk * 16 + r) * 512 + g * 16 + i) = w;))
	v_lshlrev_b32_e32 v42, 16, v26
	v_and_b32_e32 v43, 0xffff0000, v26
	v_lshlrev_b32_e32 v26, 16, v27
	v_and_b32_e32 v27, 0xffff0000, v27
	v_lshlrev_b32_e32 v44, 16, v28
	v_and_b32_e32 v45, 0xffff0000, v28
	v_lshlrev_b32_e32 v28, 16, v29
	v_and_b32_e32 v29, 0xffff0000, v29
	s_waitcnt vmcnt(1)
	v_pk_fma_f32 v[16:17], v[30:31], v[42:43], v[16:17]
	v_pk_fma_f32 v[18:19], v[32:33], v[26:27], v[18:19]
	s_waitcnt vmcnt(0)
	v_pk_fma_f32 v[20:21], v[34:35], v[44:45], v[20:21]
	v_pk_fma_f32 v[22:23], v[36:37], v[28:29], v[22:23]
	v_mul_f32_e32 v26, 0x3d372713, v16
	v_mul_f32_e32 v27, 0x3d372713, v17
	v_mul_f32_e32 v28, 0x3d372713, v18
	v_mul_f32_e32 v29, 0x3d372713, v19
	v_mul_f32_e32 v30, 0x3d372713, v20
	v_mul_f32_e32 v31, 0x3d372713, v21
	v_mul_f32_e32 v32, 0x3d372713, v22
	v_mul_f32_e32 v33, 0x3d372713, v23
	v_mul_f32_e32 v26, v16, v26
	v_mul_f32_e32 v27, v17, v27
	v_mul_f32_e32 v28, v18, v28
	v_mul_f32_e32 v29, v19, v29
	v_mul_f32_e32 v30, v20, v30
	v_mul_f32_e32 v31, v21, v31
	v_mul_f32_e32 v32, v22, v32
	v_mul_f32_e32 v33, v23, v33
	v_fma_f32 v26, v16, v26, v16
	v_fma_f32 v27, v17, v27, v17
	v_fma_f32 v28, v18, v28, v18
	v_fma_f32 v29, v19, v29, v19
	v_fma_f32 v30, v20, v30, v20
	v_fma_f32 v31, v21, v31, v21
	v_fma_f32 v32, v22, v32, v22
	v_fma_f32 v33, v23, v33, v23
	v_mul_f32_e32 v26, 0xc0135761, v26
	v_mul_f32_e32 v27, 0xc0135761, v27
	v_mul_f32_e32 v28, 0xc0135761, v28
	v_mul_f32_e32 v29, 0xc0135761, v29
	v_mul_f32_e32 v30, 0xc0135761, v30
	v_mul_f32_e32 v31, 0xc0135761, v31
	v_mul_f32_e32 v32, 0xc0135761, v32
	v_mul_f32_e32 v33, 0xc0135761, v33
	v_exp_f32_e32 v26, v26
	v_exp_f32_e32 v27, v27
	v_exp_f32_e32 v28, v28
	v_exp_f32_e32 v29, v29
	v_exp_f32_e32 v30, v30
	v_exp_f32_e32 v31, v31
	v_exp_f32_e32 v32, v32
	v_exp_f32_e32 v33, v33
	v_add_f32_e32 v26, 1.0, v26
	v_add_f32_e32 v27, 1.0, v27
	v_add_f32_e32 v28, 1.0, v28
	v_add_f32_e32 v29, 1.0, v29
	v_add_f32_e32 v30, 1.0, v30
	v_add_f32_e32 v31, 1.0, v31
	v_add_f32_e32 v32, 1.0, v32
	v_add_f32_e32 v33, 1.0, v33
	v_rcp_f32_e32 v26, v26
	v_rcp_f32_e32 v27, v27
	v_rcp_f32_e32 v28, v28
	v_rcp_f32_e32 v29, v29
	v_rcp_f32_e32 v30, v30
	v_rcp_f32_e32 v31, v31
	v_rcp_f32_e32 v32, v32
	v_rcp_f32_e32 v33, v33
	v_pk_mul_f32 v[16:17], v[16:17], v[26:27]
	v_pk_mul_f32 v[18:19], v[18:19], v[28:29]
	v_pk_mul_f32 v[20:21], v[20:21], v[30:31]
	v_pk_mul_f32 v[22:23], v[22:23], v[32:33]
	v_cvt_pk_bf16_f32 v16, v16, v17
	v_cvt_pk_bf16_f32 v17, v18, v19
	v_cvt_pk_bf16_f32 v18, v20, v21
	v_cvt_pk_bf16_f32 v19, v22, v23
	global_store_dwordx4 v[40:41], v[16:19], off
	global_load_dwordx4 v[16:19], v[24:25], off offset:256
	s_nop 0
	global_load_dwordx4 v[20:23], v152, s[0:1]
	global_load_dwordx4 v[26:29], v152, s[0:1] offset:16
	v_lshlrev_b64 v[30:31], 14, v[38:39]
	v_lshl_add_u64 v[30:31], s[26:27], 0, v[30:31]
	v_lshl_add_u64 v[32:33], v[30:31], 0, v[134:135]
	v_lshl_add_u64 v[32:33], v[32:33], 0, s[38:39]
	v_lshl_add_u64 v[32:33], v[32:33], 0, v[132:133]
	s_waitcnt vmcnt(2)
	v_lshlrev_b32_e32 v34, 16, v16
	v_and_b32_e32 v35, 0xffff0000, v16
	v_lshlrev_b32_e32 v16, 16, v17
	v_and_b32_e32 v17, 0xffff0000, v17
	v_lshlrev_b32_e32 v36, 16, v18
	v_and_b32_e32 v37, 0xffff0000, v18
	v_lshlrev_b32_e32 v18, 16, v19
	v_and_b32_e32 v19, 0xffff0000, v19
	s_waitcnt vmcnt(1)
	v_pk_fma_f32 v[8:9], v[20:21], v[34:35], v[8:9]
	v_pk_fma_f32 v[10:11], v[22:23], v[16:17], v[10:11]
	s_waitcnt vmcnt(0)
; DI float bflo(unsigned w) { return __uint_as_float(w << 16); }
; DI float bfhi(unsigned w) { return __uint_as_float(w & 0xffff0000u); }
; DI float gelu_tanh(float y) { const float u = 0.7978845608028654f * (y + 0.044715f * y * y * y); return y * __builtin_amdgcn_rcpf(1.0f + __builtin_amdgcn_exp2f(-2.0f * 1.4426950408889634f * u)); }
; #define EPI_ROWS(...) _Pragma("unroll") for (int ai = 0; ai < 2; ++ai) _Pragma("unroll") for (int m = 0; m < 4; ++m) { const int rr = ai * 128 + wr * 64 + m * 16 + fr; __VA_ARGS__ }
; #define EPI_COLS8(...) _Pragma("unroll") for (int bj = 0; bj < 2; ++bj) { const int cc = bj * 128 + wc * 32 + 8 * fq; const f32x4 v0 = acc[ai][bj][m][0], v1 = acc[ai][bj][m][1]; __VA_ARGS__ }
;     DI void operator()(const Acc& acc, int wr, int wc, int fr, int fq) const {
;         EPI_ROWS(const int chunk = row0 + rr; const bf16_t* ap = Ap + ((size_t)g * 2048 + chunk) * 384 + 128;
;             EPI_COLS8(const int r = cc >> 4, i = cc & 15; const u32x4 uw = *(const u32x4*)(ap + cc); const f32x4 d0 = *(const f32x4*)(dskip + g * 16 + i), d1 = *(const f32x4*)(dskip + g * 16 + i + 4);
;                 const float y0 = v0[0] + d0[0] * bflo(uw.x), y1 = v0[1] + d0[1] * bfhi(uw.x), y2 = v0[2] + d0[2] * bflo(uw.y), y3 = v0[3] + d0[3] * bfhi(uw.y);
;                 const float y4 = v1[0] + d1[0] * bflo(uw.z), y5 = v1[1] + d1[1] * bfhi(uw.z), y6 = v1[2] + d1[2] * bflo(uw.w), y7 = v1[3] + d1[3] * bfhi(uw.w);
;                 u32x4 w; w.x = pk2(gelu_tanh(y0), gelu_tanh(y1)); w.y = pk2(gelu_tanh(y2), gelu_tanh(y3)); w.z = pk2(gelu_tanh(y4), gelu_tanh(y5)); w.w = pk2(gelu_tanh(y6), gelu_tanh(y7));
;                 *(u32x4*)(z + ((size_t)chunk * 16 + r) * 512 + g * 16 + i) = w;))
	v_pk_fma_f32 v[12:13], v[26:27], v[36:37], v[12:13]
	v_pk_fma_f32 v[14:15], v[28:29], v[18:19], v[14:15]
	v_mul_f32_e32 v16, 0x3d372713, v8
	v_mul_f32_e32 v17, 0x3d372713, v9
	v_mul_f32_e32 v18, 0x3d372713, v10
	v_mul_f32_e32 v19, 0x3d372713, v11
	v_mul_f32_e32 v20, 0x3d372713, v12
	v_mul_f32_e32 v21, 0x3d372713, v13
	v_mul_f32_e32 v22, 0x3d372713, v14
	v_mul_f32_e32 v23, 0x3d372713, v15
	v_mul_f32_e32 v16, v8, v16
	v_mul_f32_e32 v17, v9, v17
	v_mul_f32_e32 v18, v10, v18
	v_mul_f32_e32 v19, v11, v19
	v_mul_f32_e32 v20, v12, v20
	v_mul_f32_e32 v21, v13, v21
	v_mul_f32_e32 v22, v14, v22
	v_mul_f32_e32 v23, v15, v23
	v_fma_f32 v16, v8, v16, v8
	v_fma_f32 v17, v9, v17, v9
	v_fma_f32 v18, v10, v18, v10
	v_fma_f32 v19, v11, v19, v11
	v_fma_f32 v20, v12, v20, v12
	v_fma_f32 v21, v13, v21, v13
	v_fma_f32 v22, v14, v22, v14
	v_fma_f32 v23, v15, v23, v15
	v_mul_f32_e32 v16, 0xc0135761, v16
	v_mul_f32_e32 v17, 0xc0135761, v17
	v_mul_f32_e32 v18, 0xc0135761, v18
	v_mul_f32_e32 v19, 0xc0135761, v19
	v_mul_f32_e32 v20, 0xc0135761, v20
	v_mul_f32_e32 v21, 0xc0135761, v21
	v_mul_f32_e32 v22, 0xc0135761, v22
	v_mul_f32_e32 v23, 0xc0135761, v23
	v_exp_f32_e32 v16, v16
	v_exp_f32_e32 v17, v17
	v_exp_f32_e32 v18, v18
	v_exp_f32_e32 v19, v19
	v_exp_f32_e32 v20, v20
	v_exp_f32_e32 v21, v21
	v_exp_f32_e32 v22, v22
	v_exp_f32_e32 v23, v23
	v_add_f32_e32 v16, 1.0, v16
	v_add_f32_e32 v17, 1.0, v17
	v_add_f32_e32 v18, 1.0, v18
	v_add_f32_e32 v19, 1.0, v19
	v_add_f32_e32 v20, 1.0, v20
	v_add_f32_e32 v21, 1.0, v21
	v_add_f32_e32 v22, 1.0, v22
	v_add_f32_e32 v23, 1.0, v23
	v_rcp_f32_e32 v16, v16
	v_rcp_f32_e32 v17, v17
	v_rcp_f32_e32 v18, v18
	v_rcp_f32_e32 v19, v19
	v_rcp_f32_e32 v20, v20
	v_rcp_f32_e32 v21, v21
	v_rcp_f32_e32 v22, v22
	v_rcp_f32_e32 v23, v23
	v_pk_mul_f32 v[8:9], v[8:9], v[16:17]
	v_pk_mul_f32 v[10:11], v[10:11], v[18:19]
	v_pk_mul_f32 v[12:13], v[12:13], v[20:21]
	v_pk_mul_f32 v[14:15], v[14:15], v[22:23]
	v_cvt_pk_bf16_f32 v8, v8, v9
	v_cvt_pk_bf16_f32 v9, v10, v11
	v_cvt_pk_bf16_f32 v10, v12, v13
	v_cvt_pk_bf16_f32 v11, v14, v15
	global_store_dwordx4 v[32:33], v[8:11], off
	global_load_dwordx4 v[8:11], v[24:25], off offset:512
	s_nop 0
	global_load_dwordx4 v[12:15], v152, s[0:1]
	global_load_dwordx4 v[16:19], v152, s[0:1] offset:16
	v_lshl_add_u64 v[20:21], v[30:31], 0, v[136:137]
	v_lshl_add_u64 v[20:21], v[20:21], 0, s[38:39]
	v_lshl_add_u64 v[20:21], v[20:21], 0, v[132:133]
	s_mov_b64 s[0:1], -1
	s_waitcnt vmcnt(2)
	v_lshlrev_b32_e32 v22, 16, v8
	v_and_b32_e32 v23, 0xffff0000, v8
	v_lshlrev_b32_e32 v8, 16, v9
	v_and_b32_e32 v9, 0xffff0000, v9
	v_lshlrev_b32_e32 v24, 16, v10
	v_and_b32_e32 v25, 0xffff0000, v10
	v_lshlrev_b32_e32 v10, 16, v11
	v_and_b32_e32 v11, 0xffff0000, v11
	s_waitcnt vmcnt(1)
	v_pk_fma_f32 v[0:1], v[12:13], v[22:23], v[0:1]
	v_pk_fma_f32 v[2:3], v[14:15], v[8:9], v[2:3]
	s_waitcnt vmcnt(0)
	v_pk_fma_f32 v[4:5], v[16:17], v[24:25], v[4:5]
	v_pk_fma_f32 v[6:7], v[18:19], v[10:11], v[6:7]
	v_mul_f32_e32 v8, 0x3d372713, v0
	v_mul_f32_e32 v9, 0x3d372713, v1
	v_mul_f32_e32 v10, 0x3d372713, v2
	v_mul_f32_e32 v11, 0x3d372713, v3
	v_mul_f32_e32 v12, 0x3d372713, v4
	v_mul_f32_e32 v13, 0x3d372713, v5
	v_mul_f32_e32 v14, 0x3d372713, v6
	v_mul_f32_e32 v15, 0x3d372713, v7
	v_mul_f32_e32 v8, v0, v8
	v_mul_f32_e32 v9, v1, v9
	v_mul_f32_e32 v10, v2, v10
	v_mul_f32_e32 v11, v3, v11
	v_mul_f32_e32 v12, v4, v12
	v_mul_f32_e32 v13, v5, v13
	v_mul_f32_e32 v14, v6, v14
	v_mul_f32_e32 v15, v7, v15
	v_fma_f32 v8, v0, v8, v0
	v_fma_f32 v9, v1, v9, v1
	v_fma_f32 v10, v2, v10, v2
	v_fma_f32 v11, v3, v11, v3
	v_fma_f32 v12, v4, v12, v4
	v_fma_f32 v13, v5, v13, v5
	v_fma_f32 v14, v6, v14, v6
	v_fma_f32 v15, v7, v15, v7
	v_mul_f32_e32 v8, 0xc0135761, v8
	v_mul_f32_e32 v9, 0xc0135761, v9
	v_mul_f32_e32 v10, 0xc0135761, v10
	v_mul_f32_e32 v11, 0xc0135761, v11
	v_mul_f32_e32 v12, 0xc0135761, v12
	v_mul_f32_e32 v13, 0xc0135761, v13
	v_mul_f32_e32 v14, 0xc0135761, v14
	v_mul_f32_e32 v15, 0xc0135761, v15
	v_exp_f32_e32 v8, v8
	v_exp_f32_e32 v9, v9
	v_exp_f32_e32 v10, v10
	v_exp_f32_e32 v11, v11
	v_exp_f32_e32 v12, v12
	v_exp_f32_e32 v13, v13
	v_exp_f32_e32 v14, v14
	v_exp_f32_e32 v15, v15
	v_add_f32_e32 v8, 1.0, v8
	v_add_f32_e32 v9, 1.0, v9
	v_add_f32_e32 v10, 1.0, v10
	v_add_f32_e32 v11, 1.0, v11
	v_add_f32_e32 v12, 1.0, v12
	v_add_f32_e32 v13, 1.0, v13
	v_add_f32_e32 v14, 1.0, v14
	v_add_f32_e32 v15, 1.0, v15
	v_rcp_f32_e32 v8, v8
	v_rcp_f32_e32 v9, v9
	v_rcp_f32_e32 v10, v10
	v_rcp_f32_e32 v11, v11
	v_rcp_f32_e32 v12, v12
	v_rcp_f32_e32 v13, v13
	v_rcp_f32_e32 v14, v14
	v_rcp_f32_e32 v15, v15
	v_pk_mul_f32 v[0:1], v[0:1], v[8:9]
	v_pk_mul_f32 v[2:3], v[2:3], v[10:11]
	v_pk_mul_f32 v[4:5], v[4:5], v[12:13]
	v_pk_mul_f32 v[6:7], v[6:7], v[14:15]
	v_cvt_pk_bf16_f32 v0, v0, v1
	v_cvt_pk_bf16_f32 v1, v2, v3
	v_cvt_pk_bf16_f32 v2, v4, v5
	v_cvt_pk_bf16_f32 v3, v6, v7
	global_store_dwordx4 v[20:21], v[0:3], off
	s_cbranch_vccnz .LBB0_758
	s_and_b64 vcc, exec, s[6:7]
	s_cbranch_vccnz .LBB0_757
	s_barrier
	s_branch .LBB0_757

; DI float bflo(unsigned w) { return __uint_as_float(w << 16); }
; DI float bfhi(unsigned w) { return __uint_as_float(w & 0xffff0000u); }
; DI float gelu_tanh(float y) { const float u = 0.7978845608028654f * (y + 0.044715f * y * y * y); return y * __builtin_amdgcn_rcpf(1.0f + __builtin_amdgcn_exp2f(-2.0f * 1.4426950408889634f * u)); }
; #define EPI_ROWS(...) _Pragma("unroll") for (int ai = 0; ai < 2; ++ai) _Pragma("unroll") for (int m = 0; m < 4; ++m) { const int rr = ai * 128 + wr * 64 + m * 16 + fr; __VA_ARGS__ }
; #define EPI_COLS8(...) _Pragma("unroll") for (int bj = 0; bj < 2; ++bj) { const int cc = bj * 128 + wc * 32 + 8 * fq; const f32x4 v0 = acc[ai][bj][m][0], v1 = acc[ai][bj][m][1]; __VA_ARGS__ }
;     DI void operator()(const Acc& acc, int wr, int wc, int fr, int fq) const {
;         EPI_ROWS(const int chunk = row0 + rr; const bf16_t* ap = Ap + ((size_t)g * 2048 + chunk) * 384 + 128;
;             EPI_COLS8(const int r = cc >> 4, i = cc & 15; const u32x4 uw = *(const u32x4*)(ap + cc); const f32x4 d0 = *(const f32x4*)(dskip + g * 16 + i), d1 = *(const f32x4*)(dskip + g * 16 + i + 4);
;                 const float y0 = v0[0] + d0[0] * bflo(uw.x), y1 = v0[1] + d0[1] * bfhi(uw.x), y2 = v0[2] + d0[2] * bflo(uw.y), y3 = v0[3] + d0[3] * bfhi(uw.y);
;                 const float y4 = v1[0] + d1[0] * bflo(uw.z), y5 = v1[1] + d1[1] * bfhi(uw.z), y6 = v1[2] + d1[2] * bflo(uw.w), y7 = v1[3] + d1[3] * bfhi(uw.w);
;                 u32x4 w; w.x = pk2(gelu_tanh(y0), gelu_tanh(y1)); w.y = pk2(gelu_tanh(y2), gelu_tanh(y3)); w.z = pk2(gelu_tanh(y4), gelu_tanh(y5)); w.w = pk2(gelu_tanh(y6), gelu_tanh(y7));
;                 *(u32x4*)(z + ((size_t)chunk * 16 + r) * 512 + g * 16 + i) = w;))
.LBB0_793:
	v_add_u32_e32 v140, s51, v144
	s_ashr_i32 s11, s10, 31
	s_lshl_b64 s[36:37], s[10:11], 11
	v_ashrrev_i32_e32 v141, 31, v140
	v_lshl_add_u64 v[154:155], s[36:37], 0, v[140:141]
	v_mov_b64_e32 v[142:143], s[22:23]
	s_lshl_b32 s34, s10, 4
	v_mad_u64_u32 v[156:157], s[0:1], v154, s42, v[142:143]
	s_ashr_i32 s35, s34, 31
	v_mad_i32_i24 v157, v155, s42, v157
	s_lshl_b64 s[0:1], s[34:35], 2
	v_lshl_add_u64 v[166:167], v[156:157], 0, v[138:139]
	s_add_u32 s0, s20, s0
	s_addc_u32 s1, s21, s1
	v_lshlrev_b32_e32 v153, 2, v130
	v_mov_b64_e32 v[250:251], v[166:167]
	s_mov_b32 s99, 0
	global_load_dwordx4 v[238:241], v153, s[0:1]
	global_load_dwordx4 v[242:245], v153, s[0:1] offset:16
	global_load_dwordx4 v[182:185], v[250:251], off offset:256
	global_load_dwordx4 v[194:197], v[250:251], off offset:512
	s_mov_b32 s98, 0x3000
	v_lshl_add_u64 v[252:253], v[250:251], 0, s[98:99]
	global_load_dwordx4 v[198:201], v[252:253], off offset:256
	s_mov_b32 s98, 0x3000
	v_lshl_add_u64 v[252:253], v[250:251], 0, s[98:99]
	global_load_dwordx4 v[202:205], v[252:253], off offset:512
	s_mov_b32 s98, 0x6000
	v_lshl_add_u64 v[252:253], v[250:251], 0, s[98:99]
	global_load_dwordx4 v[246:249], v[252:253], off offset:256
	v_lshlrev_b64 v[168:169], 14, v[140:141]
	s_lshl_b64 s[34:35], s[34:35], 1
	s_and_b64 vcc, exec, s[8:9]
	s_waitcnt vmcnt(4)
	v_lshlrev_b32_e32 v170, 16, v182
	v_and_b32_e32 v171, 0xffff0000, v182
	v_lshlrev_b32_e32 v172, 16, v184
	v_and_b32_e32 v173, 0xffff0000, v184
	v_lshlrev_b32_e32 v154, 16, v183
	v_and_b32_e32 v155, 0xffff0000, v183
	v_lshlrev_b32_e32 v156, 16, v185
	v_and_b32_e32 v157, 0xffff0000, v185
	v_pk_fma_f32 v[124:125], v[238:239], v[170:171], v[124:125]
	v_pk_fma_f32 v[120:121], v[242:243], v[172:173], v[120:121]
	v_pk_fma_f32 v[126:127], v[240:241], v[154:155], v[126:127]
	v_pk_fma_f32 v[122:123], v[244:245], v[156:157], v[122:123]
	v_mul_f32_e32 v132, 0x3d372713, v124
	v_mul_f32_e32 v141, 0x3d372713, v125
	v_mul_f32_e32 v156, 0x3d372713, v120
	v_mul_f32_e32 v157, 0x3d372713, v121
	v_mul_f32_e32 v154, 0x3d372713, v126
	v_mul_f32_e32 v155, 0x3d372713, v127
	v_mul_f32_e32 v158, 0x3d372713, v122
	v_mul_f32_e32 v159, 0x3d372713, v123
	v_mul_f32_e32 v132, v124, v132
	v_mul_f32_e32 v141, v125, v141
	v_mul_f32_e32 v156, v120, v156
	v_mul_f32_e32 v157, v121, v157
	v_mul_f32_e32 v154, v126, v154
	v_mul_f32_e32 v155, v127, v155
	v_mul_f32_e32 v158, v122, v158
	v_mul_f32_e32 v159, v123, v159
	v_fma_f32 v132, v124, v132, v124
	v_fma_f32 v141, v125, v141, v125
	v_fma_f32 v156, v120, v156, v120
	v_fma_f32 v157, v121, v157, v121
	v_fma_f32 v154, v126, v154, v126
	v_fma_f32 v155, v127, v155, v127
	v_fma_f32 v158, v122, v158, v122
	v_fma_f32 v159, v123, v159, v123
	v_mul_f32_e32 v132, 0xc0135761, v132
	v_mul_f32_e32 v141, 0xc0135761, v141
	v_mul_f32_e32 v156, 0xc0135761, v156
	v_mul_f32_e32 v157, 0xc0135761, v157
	v_mul_f32_e32 v154, 0xc0135761, v154
	v_mul_f32_e32 v155, 0xc0135761, v155
	v_mul_f32_e32 v158, 0xc0135761, v158
	v_mul_f32_e32 v159, 0xc0135761, v159
	v_exp_f32_e32 v132, v132
	v_exp_f32_e32 v141, v141
	v_exp_f32_e32 v156, v156
	v_exp_f32_e32 v157, v157
	v_exp_f32_e32 v154, v154
	v_exp_f32_e32 v155, v155
	v_exp_f32_e32 v158, v158
	v_exp_f32_e32 v159, v159
	v_add_f32_e32 v132, 1.0, v132
	v_add_f32_e32 v141, 1.0, v141
	v_add_f32_e32 v162, 1.0, v156
	v_add_f32_e32 v163, 1.0, v157
	v_add_f32_e32 v160, 1.0, v154
	v_add_f32_e32 v161, 1.0, v155
	v_add_f32_e32 v164, 1.0, v158
	v_add_f32_e32 v165, 1.0, v159
	v_rcp_f32_e32 v154, v132
	v_rcp_f32_e32 v155, v141
	v_rcp_f32_e32 v158, v162
	v_rcp_f32_e32 v159, v163
	v_rcp_f32_e32 v156, v160
	v_rcp_f32_e32 v157, v161
	v_rcp_f32_e32 v160, v164
	v_rcp_f32_e32 v161, v165
	v_pk_mul_f32 v[124:125], v[124:125], v[154:155]
	v_pk_mul_f32 v[154:155], v[120:121], v[158:159]
	v_lshl_add_u64 v[158:159], s[26:27], 0, v[168:169]
	v_cvt_pk_bf16_f32 v120, v124, v125
	v_lshl_add_u64 v[124:125], v[158:159], 0, v[134:135]
	v_pk_mul_f32 v[126:127], v[126:127], v[156:157]
	v_pk_mul_f32 v[156:157], v[122:123], v[160:161]
	v_lshl_add_u64 v[124:125], v[124:125], 0, s[34:35]
	v_lshlrev_b32_e32 v132, 1, v130
	v_cvt_pk_bf16_f32 v121, v126, v127
	v_cvt_pk_bf16_f32 v122, v154, v155
	v_cvt_pk_bf16_f32 v123, v156, v157
	v_lshl_add_u64 v[124:125], v[124:125], 0, v[132:133]
	global_store_dwordx4 v[124:125], v[120:123], off
	s_mov_b32 s98, 0x6000
	v_lshl_add_u64 v[252:253], v[250:251], 0, s[98:99]
	global_load_dwordx4 v[182:185], v[252:253], off offset:512
	v_lshl_add_u64 v[158:159], v[158:159], 0, v[136:137]
	v_add_u32_e32 v160, s51, v147
	v_lshl_add_u64 v[158:159], v[158:159], 0, s[34:35]
	v_ashrrev_i32_e32 v161, 31, v160
	v_lshl_add_u64 v[158:159], v[158:159], 0, v[132:133]
	s_waitcnt vmcnt(5)
; DI float bflo(unsigned w) { return __uint_as_float(w << 16); }
; DI float bfhi(unsigned w) { return __uint_as_float(w & 0xffff0000u); }
; DI float gelu_tanh(float y) { const float u = 0.7978845608028654f * (y + 0.044715f * y * y * y); return y * __builtin_amdgcn_rcpf(1.0f + __builtin_amdgcn_exp2f(-2.0f * 1.4426950408889634f * u)); }
; #define EPI_ROWS(...) _Pragma("unroll") for (int ai = 0; ai < 2; ++ai) _Pragma("unroll") for (int m = 0; m < 4; ++m) { const int rr = ai * 128 + wr * 64 + m * 16 + fr; __VA_ARGS__ }
; #define EPI_COLS8(...) _Pragma("unroll") for (int bj = 0; bj < 2; ++bj) { const int cc = bj * 128 + wc * 32 + 8 * fq; const f32x4 v0 = acc[ai][bj][m][0], v1 = acc[ai][bj][m][1]; __VA_ARGS__ }
;     DI void operator()(const Acc& acc, int wr, int wc, int fr, int fq) const {
;         EPI_ROWS(const int chunk = row0 + rr; const bf16_t* ap = Ap + ((size_t)g * 2048 + chunk) * 384 + 128;
;             EPI_COLS8(const int r = cc >> 4, i = cc & 15; const u32x4 uw = *(const u32x4*)(ap + cc); const f32x4 d0 = *(const f32x4*)(dskip + g * 16 + i), d1 = *(const f32x4*)(dskip + g * 16 + i + 4);
;                 const float y0 = v0[0] + d0[0] * bflo(uw.x), y1 = v0[1] + d0[1] * bfhi(uw.x), y2 = v0[2] + d0[2] * bflo(uw.y), y3 = v0[3] + d0[3] * bfhi(uw.y);
;                 const float y4 = v1[0] + d1[0] * bflo(uw.z), y5 = v1[1] + d1[1] * bfhi(uw.z), y6 = v1[2] + d1[2] * bflo(uw.w), y7 = v1[3] + d1[3] * bfhi(uw.w);
;                 u32x4 w; w.x = pk2(gelu_tanh(y0), gelu_tanh(y1)); w.y = pk2(gelu_tanh(y2), gelu_tanh(y3)); w.z = pk2(gelu_tanh(y4), gelu_tanh(y5)); w.w = pk2(gelu_tanh(y6), gelu_tanh(y7));
;                 *(u32x4*)(z + ((size_t)chunk * 16 + r) * 512 + g * 16 + i) = w;))
	v_lshlrev_b32_e32 v162, 16, v194
	v_and_b32_e32 v163, 0xffff0000, v194
	v_lshlrev_b32_e32 v120, 16, v195
	v_and_b32_e32 v121, 0xffff0000, v195
	v_lshlrev_b32_e32 v164, 16, v196
	v_and_b32_e32 v165, 0xffff0000, v196
	v_lshlrev_b32_e32 v122, 16, v197
	v_and_b32_e32 v123, 0xffff0000, v197
	v_pk_fma_f32 v[112:113], v[238:239], v[162:163], v[112:113]
	v_pk_fma_f32 v[114:115], v[240:241], v[120:121], v[114:115]
	v_pk_fma_f32 v[116:117], v[242:243], v[164:165], v[116:117]
	v_pk_fma_f32 v[118:119], v[244:245], v[122:123], v[118:119]
	v_mul_f32_e32 v120, 0x3d372713, v112
	v_mul_f32_e32 v121, 0x3d372713, v113
	v_mul_f32_e32 v122, 0x3d372713, v114
	v_mul_f32_e32 v123, 0x3d372713, v115
	v_mul_f32_e32 v124, 0x3d372713, v116
	v_mul_f32_e32 v125, 0x3d372713, v117
	v_mul_f32_e32 v126, 0x3d372713, v118
	v_mul_f32_e32 v127, 0x3d372713, v119
	v_mul_f32_e32 v120, v112, v120
	v_mul_f32_e32 v121, v113, v121
	v_mul_f32_e32 v122, v114, v122
	v_mul_f32_e32 v123, v115, v123
	v_mul_f32_e32 v124, v116, v124
	v_mul_f32_e32 v125, v117, v125
	v_mul_f32_e32 v126, v118, v126
	v_mul_f32_e32 v127, v119, v127
	v_fma_f32 v120, v112, v120, v112
	v_fma_f32 v121, v113, v121, v113
	v_fma_f32 v122, v114, v122, v114
	v_fma_f32 v123, v115, v123, v115
	v_fma_f32 v124, v116, v124, v116
	v_fma_f32 v125, v117, v125, v117
	v_fma_f32 v126, v118, v126, v118
	v_fma_f32 v127, v119, v127, v119
	v_mul_f32_e32 v120, 0xc0135761, v120
	v_mul_f32_e32 v121, 0xc0135761, v121
	v_mul_f32_e32 v122, 0xc0135761, v122
	v_mul_f32_e32 v123, 0xc0135761, v123
	v_mul_f32_e32 v124, 0xc0135761, v124
	v_mul_f32_e32 v125, 0xc0135761, v125
	v_mul_f32_e32 v126, 0xc0135761, v126
	v_mul_f32_e32 v127, 0xc0135761, v127
	v_exp_f32_e32 v120, v120
	v_exp_f32_e32 v121, v121
	v_exp_f32_e32 v122, v122
	v_exp_f32_e32 v123, v123
	v_exp_f32_e32 v124, v124
	v_exp_f32_e32 v125, v125
	v_exp_f32_e32 v126, v126
	v_exp_f32_e32 v127, v127
	v_add_f32_e32 v120, 1.0, v120
	v_add_f32_e32 v121, 1.0, v121
	v_add_f32_e32 v122, 1.0, v122
	v_add_f32_e32 v123, 1.0, v123
	v_add_f32_e32 v124, 1.0, v124
	v_add_f32_e32 v125, 1.0, v125
	v_add_f32_e32 v126, 1.0, v126
	v_add_f32_e32 v127, 1.0, v127
	v_rcp_f32_e32 v120, v120
	v_rcp_f32_e32 v121, v121
	v_rcp_f32_e32 v122, v122
	v_rcp_f32_e32 v123, v123
	v_rcp_f32_e32 v124, v124
	v_rcp_f32_e32 v125, v125
	v_rcp_f32_e32 v126, v126
	v_rcp_f32_e32 v127, v127
	v_pk_mul_f32 v[112:113], v[112:113], v[120:121]
	v_pk_mul_f32 v[114:115], v[114:115], v[122:123]
	v_pk_mul_f32 v[116:117], v[116:117], v[124:125]
	v_pk_mul_f32 v[118:119], v[118:119], v[126:127]
	v_cvt_pk_bf16_f32 v112, v112, v113
	v_cvt_pk_bf16_f32 v113, v114, v115
	v_cvt_pk_bf16_f32 v114, v116, v117
	v_cvt_pk_bf16_f32 v115, v118, v119
	global_store_dwordx4 v[158:159], v[112:115], off
	s_mov_b32 s98, 0x9000
	v_lshl_add_u64 v[252:253], v[250:251], 0, s[98:99]
	global_load_dwordx4 v[194:197], v[252:253], off offset:256
	v_lshlrev_b64 v[126:127], 14, v[160:161]
	v_lshl_add_u64 v[126:127], s[26:27], 0, v[126:127]
	v_lshl_add_u64 v[112:113], s[36:37], 0, v[160:161]
	v_mad_u64_u32 v[114:115], s[56:57], v112, s42, v[142:143]
	v_mad_i32_i24 v115, v113, s42, v115
	v_lshl_add_u64 v[124:125], v[114:115], 0, v[138:139]
	v_lshl_add_u64 v[154:155], v[126:127], 0, v[134:135]
	v_lshl_add_u64 v[154:155], v[154:155], 0, s[34:35]
	v_lshl_add_u64 v[154:155], v[154:155], 0, v[132:133]
	s_waitcnt vmcnt(6)
	v_lshlrev_b32_e32 v156, 16, v198
	v_and_b32_e32 v157, 0xffff0000, v198
	v_lshlrev_b32_e32 v112, 16, v199
	v_and_b32_e32 v113, 0xffff0000, v199
	v_lshlrev_b32_e32 v158, 16, v200
	v_and_b32_e32 v159, 0xffff0000, v200
	v_lshlrev_b32_e32 v114, 16, v201
	v_and_b32_e32 v115, 0xffff0000, v201
	v_pk_fma_f32 v[104:105], v[238:239], v[156:157], v[104:105]
	v_pk_fma_f32 v[106:107], v[240:241], v[112:113], v[106:107]
	v_pk_fma_f32 v[108:109], v[242:243], v[158:159], v[108:109]
	v_pk_fma_f32 v[110:111], v[244:245], v[114:115], v[110:111]
	v_mul_f32_e32 v112, 0x3d372713, v104
	v_mul_f32_e32 v113, 0x3d372713, v105
	v_mul_f32_e32 v114, 0x3d372713, v106
	v_mul_f32_e32 v115, 0x3d372713, v107
	v_mul_f32_e32 v116, 0x3d372713, v108
	v_mul_f32_e32 v117, 0x3d372713, v109
	v_mul_f32_e32 v118, 0x3d372713, v110
	v_mul_f32_e32 v119, 0x3d372713, v111
	v_mul_f32_e32 v112, v104, v112
	v_mul_f32_e32 v113, v105, v113
	v_mul_f32_e32 v114, v106, v114
	v_mul_f32_e32 v115, v107, v115
	v_mul_f32_e32 v116, v108, v116
	v_mul_f32_e32 v117, v109, v117
	v_mul_f32_e32 v118, v110, v118
	v_mul_f32_e32 v119, v111, v119
	v_fma_f32 v112, v104, v112, v104
	v_fma_f32 v113, v105, v113, v105
	v_fma_f32 v114, v106, v114, v106
	v_fma_f32 v115, v107, v115, v107
	v_fma_f32 v116, v108, v116, v108
	v_fma_f32 v117, v109, v117, v109
	v_fma_f32 v118, v110, v118, v110
	v_fma_f32 v119, v111, v119, v111
	v_mul_f32_e32 v112, 0xc0135761, v112
	v_mul_f32_e32 v113, 0xc0135761, v113
	v_mul_f32_e32 v114, 0xc0135761, v114
	v_mul_f32_e32 v115, 0xc0135761, v115
	v_mul_f32_e32 v116, 0xc0135761, v116
	v_mul_f32_e32 v117, 0xc0135761, v117
	v_mul_f32_e32 v118, 0xc0135761, v118
	v_mul_f32_e32 v119, 0xc0135761, v119
	v_exp_f32_e32 v112, v112
	v_exp_f32_e32 v113, v113
	v_exp_f32_e32 v114, v114
	v_exp_f32_e32 v115, v115
	v_exp_f32_e32 v116, v116
	v_exp_f32_e32 v117, v117
	v_exp_f32_e32 v118, v118
	v_exp_f32_e32 v119, v119
	v_add_f32_e32 v112, 1.0, v112
	v_add_f32_e32 v113, 1.0, v113
	v_add_f32_e32 v114, 1.0, v114
	v_add_f32_e32 v115, 1.0, v115
	v_add_f32_e32 v116, 1.0, v116
	v_add_f32_e32 v117, 1.0, v117
	v_add_f32_e32 v118, 1.0, v118
	v_add_f32_e32 v119, 1.0, v119
	v_rcp_f32_e32 v112, v112
	v_rcp_f32_e32 v113, v113
	v_rcp_f32_e32 v114, v114
	v_rcp_f32_e32 v115, v115
	v_rcp_f32_e32 v116, v116
	v_rcp_f32_e32 v117, v117
	v_rcp_f32_e32 v118, v118
	v_rcp_f32_e32 v119, v119
	v_pk_mul_f32 v[104:105], v[104:105], v[112:113]
	v_pk_mul_f32 v[106:107], v[106:107], v[114:115]
	v_pk_mul_f32 v[108:109], v[108:109], v[116:117]
	v_pk_mul_f32 v[110:111], v[110:111], v[118:119]
	v_cvt_pk_bf16_f32 v104, v104, v105
	v_cvt_pk_bf16_f32 v105, v106, v107
	v_cvt_pk_bf16_f32 v106, v108, v109
	v_cvt_pk_bf16_f32 v107, v110, v111
	global_store_dwordx4 v[154:155], v[104:107], off
	s_mov_b32 s98, 0x9000
	v_lshl_add_u64 v[252:253], v[250:251], 0, s[98:99]
	global_load_dwordx4 v[198:201], v[252:253], off offset:512
	v_add_u32_e32 v118, s51, v148
	v_ashrrev_i32_e32 v119, 31, v118
	v_lshl_add_u64 v[104:105], s[36:37], 0, v[118:119]
	v_mad_u64_u32 v[120:121], s[56:57], v104, s42, v[142:143]
	v_lshl_add_u64 v[122:123], v[126:127], 0, v[136:137]
	v_mad_i32_i24 v121, v105, s42, v121
	v_lshl_add_u64 v[122:123], v[122:123], 0, s[34:35]
	v_lshl_add_u64 v[104:105], v[120:121], 0, v[138:139]
	v_lshl_add_u64 v[120:121], v[122:123], 0, v[132:133]
	s_waitcnt vmcnt(7)
; DI float bflo(unsigned w) { return __uint_as_float(w << 16); }
; DI float bfhi(unsigned w) { return __uint_as_float(w & 0xffff0000u); }
; DI float gelu_tanh(float y) { const float u = 0.7978845608028654f * (y + 0.044715f * y * y * y); return y * __builtin_amdgcn_rcpf(1.0f + __builtin_amdgcn_exp2f(-2.0f * 1.4426950408889634f * u)); }
; #define EPI_ROWS(...) _Pragma("unroll") for (int ai = 0; ai < 2; ++ai) _Pragma("unroll") for (int m = 0; m < 4; ++m) { const int rr = ai * 128 + wr * 64 + m * 16 + fr; __VA_ARGS__ }
; #define EPI_COLS8(...) _Pragma("unroll") for (int bj = 0; bj < 2; ++bj) { const int cc = bj * 128 + wc * 32 + 8 * fq; const f32x4 v0 = acc[ai][bj][m][0], v1 = acc[ai][bj][m][1]; __VA_ARGS__ }
;     DI void operator()(const Acc& acc, int wr, int wc, int fr, int fq) const {
;         EPI_ROWS(const int chunk = row0 + rr; const bf16_t* ap = Ap + ((size_t)g * 2048 + chunk) * 384 + 128;
;             EPI_COLS8(const int r = cc >> 4, i = cc & 15; const u32x4 uw = *(const u32x4*)(ap + cc); const f32x4 d0 = *(const f32x4*)(dskip + g * 16 + i), d1 = *(const f32x4*)(dskip + g * 16 + i + 4);
;                 const float y0 = v0[0] + d0[0] * bflo(uw.x), y1 = v0[1] + d0[1] * bfhi(uw.x), y2 = v0[2] + d0[2] * bflo(uw.y), y3 = v0[3] + d0[3] * bfhi(uw.y);
;                 const float y4 = v1[0] + d1[0] * bflo(uw.z), y5 = v1[1] + d1[1] * bfhi(uw.z), y6 = v1[2] + d1[2] * bflo(uw.w), y7 = v1[3] + d1[3] * bfhi(uw.w);
;                 u32x4 w; w.x = pk2(gelu_tanh(y0), gelu_tanh(y1)); w.y = pk2(gelu_tanh(y2), gelu_tanh(y3)); w.z = pk2(gelu_tanh(y4), gelu_tanh(y5)); w.w = pk2(gelu_tanh(y6), gelu_tanh(y7));
;                 *(u32x4*)(z + ((size_t)chunk * 16 + r) * 512 + g * 16 + i) = w;))
	v_lshlrev_b32_e32 v122, 16, v202
	v_and_b32_e32 v123, 0xffff0000, v202
	v_lshlrev_b32_e32 v106, 16, v203
	v_and_b32_e32 v107, 0xffff0000, v203
	v_lshlrev_b32_e32 v124, 16, v204
	v_and_b32_e32 v125, 0xffff0000, v204
	v_lshlrev_b32_e32 v108, 16, v205
	v_and_b32_e32 v109, 0xffff0000, v205
	v_pk_fma_f32 v[96:97], v[238:239], v[122:123], v[96:97]
	v_pk_fma_f32 v[98:99], v[240:241], v[106:107], v[98:99]
	v_pk_fma_f32 v[100:101], v[242:243], v[124:125], v[100:101]
	v_pk_fma_f32 v[102:103], v[244:245], v[108:109], v[102:103]
	v_mul_f32_e32 v106, 0x3d372713, v96
	v_mul_f32_e32 v107, 0x3d372713, v97
	v_mul_f32_e32 v108, 0x3d372713, v98
	v_mul_f32_e32 v109, 0x3d372713, v99
	v_mul_f32_e32 v110, 0x3d372713, v100
	v_mul_f32_e32 v111, 0x3d372713, v101
	v_mul_f32_e32 v112, 0x3d372713, v102
	v_mul_f32_e32 v113, 0x3d372713, v103
	v_mul_f32_e32 v106, v96, v106
	v_mul_f32_e32 v107, v97, v107
	v_mul_f32_e32 v108, v98, v108
	v_mul_f32_e32 v109, v99, v109
	v_mul_f32_e32 v110, v100, v110
	v_mul_f32_e32 v111, v101, v111
	v_mul_f32_e32 v112, v102, v112
	v_mul_f32_e32 v113, v103, v113
	v_fma_f32 v106, v96, v106, v96
	v_fma_f32 v107, v97, v107, v97
	v_fma_f32 v108, v98, v108, v98
	v_fma_f32 v109, v99, v109, v99
	v_fma_f32 v110, v100, v110, v100
	v_fma_f32 v111, v101, v111, v101
	v_fma_f32 v112, v102, v112, v102
	v_fma_f32 v113, v103, v113, v103
	v_mul_f32_e32 v106, 0xc0135761, v106
	v_mul_f32_e32 v107, 0xc0135761, v107
	v_mul_f32_e32 v108, 0xc0135761, v108
	v_mul_f32_e32 v109, 0xc0135761, v109
	v_mul_f32_e32 v110, 0xc0135761, v110
	v_mul_f32_e32 v111, 0xc0135761, v111
	v_mul_f32_e32 v112, 0xc0135761, v112
	v_mul_f32_e32 v113, 0xc0135761, v113
	v_exp_f32_e32 v106, v106
	v_exp_f32_e32 v107, v107
	v_exp_f32_e32 v108, v108
	v_exp_f32_e32 v109, v109
	v_exp_f32_e32 v110, v110
	v_exp_f32_e32 v111, v111
	v_exp_f32_e32 v112, v112
	v_exp_f32_e32 v113, v113
	v_add_f32_e32 v106, 1.0, v106
	v_add_f32_e32 v107, 1.0, v107
	v_add_f32_e32 v108, 1.0, v108
	v_add_f32_e32 v109, 1.0, v109
	v_add_f32_e32 v110, 1.0, v110
	v_add_f32_e32 v111, 1.0, v111
	v_add_f32_e32 v112, 1.0, v112
	v_add_f32_e32 v113, 1.0, v113
	v_rcp_f32_e32 v106, v106
	v_rcp_f32_e32 v107, v107
	v_rcp_f32_e32 v108, v108
	v_rcp_f32_e32 v109, v109
	v_rcp_f32_e32 v110, v110
	v_rcp_f32_e32 v111, v111
	v_rcp_f32_e32 v112, v112
	v_rcp_f32_e32 v113, v113
	v_pk_mul_f32 v[96:97], v[96:97], v[106:107]
	v_pk_mul_f32 v[98:99], v[98:99], v[108:109]
	v_pk_mul_f32 v[100:101], v[100:101], v[110:111]
	v_pk_mul_f32 v[102:103], v[102:103], v[112:113]
	v_cvt_pk_bf16_f32 v96, v96, v97
	v_cvt_pk_bf16_f32 v97, v98, v99
	v_cvt_pk_bf16_f32 v98, v100, v101
	v_cvt_pk_bf16_f32 v99, v102, v103
	global_store_dwordx4 v[120:121], v[96:99], off
	s_mov_b32 s98, 0x18000
	v_lshl_add_u64 v[252:253], v[250:251], 0, s[98:99]
	global_load_dwordx4 v[202:205], v[252:253], off offset:256
	v_lshlrev_b64 v[110:111], 14, v[118:119]
	v_lshl_add_u64 v[110:111], s[26:27], 0, v[110:111]
	v_lshl_add_u64 v[112:113], v[110:111], 0, v[134:135]
	v_lshl_add_u64 v[112:113], v[112:113], 0, s[34:35]
	v_lshl_add_u64 v[112:113], v[112:113], 0, v[132:133]
	s_waitcnt vmcnt(8)
	v_lshlrev_b32_e32 v114, 16, v246
	v_and_b32_e32 v115, 0xffff0000, v246
	v_lshlrev_b32_e32 v96, 16, v247
	v_and_b32_e32 v97, 0xffff0000, v247
	v_lshlrev_b32_e32 v116, 16, v248
	v_and_b32_e32 v117, 0xffff0000, v248
	v_lshlrev_b32_e32 v98, 16, v249
	v_and_b32_e32 v99, 0xffff0000, v249
	v_pk_fma_f32 v[88:89], v[238:239], v[114:115], v[88:89]
	v_pk_fma_f32 v[90:91], v[240:241], v[96:97], v[90:91]
	v_pk_fma_f32 v[92:93], v[242:243], v[116:117], v[92:93]
	v_pk_fma_f32 v[94:95], v[244:245], v[98:99], v[94:95]
	v_mul_f32_e32 v96, 0x3d372713, v88
	v_mul_f32_e32 v97, 0x3d372713, v89
	v_mul_f32_e32 v98, 0x3d372713, v90
	v_mul_f32_e32 v99, 0x3d372713, v91
	v_mul_f32_e32 v100, 0x3d372713, v92
	v_mul_f32_e32 v101, 0x3d372713, v93
	v_mul_f32_e32 v102, 0x3d372713, v94
	v_mul_f32_e32 v103, 0x3d372713, v95
	v_mul_f32_e32 v96, v88, v96
	v_mul_f32_e32 v97, v89, v97
	v_mul_f32_e32 v98, v90, v98
	v_mul_f32_e32 v99, v91, v99
	v_mul_f32_e32 v100, v92, v100
	v_mul_f32_e32 v101, v93, v101
	v_mul_f32_e32 v102, v94, v102
	v_mul_f32_e32 v103, v95, v103
	v_fma_f32 v96, v88, v96, v88
	v_fma_f32 v97, v89, v97, v89
	v_fma_f32 v98, v90, v98, v90
	v_fma_f32 v99, v91, v99, v91
	v_fma_f32 v100, v92, v100, v92
	v_fma_f32 v101, v93, v101, v93
	v_fma_f32 v102, v94, v102, v94
	v_fma_f32 v103, v95, v103, v95
	v_mul_f32_e32 v96, 0xc0135761, v96
	v_mul_f32_e32 v97, 0xc0135761, v97
	v_mul_f32_e32 v98, 0xc0135761, v98
	v_mul_f32_e32 v99, 0xc0135761, v99
	v_mul_f32_e32 v100, 0xc0135761, v100
	v_mul_f32_e32 v101, 0xc0135761, v101
	v_mul_f32_e32 v102, 0xc0135761, v102
	v_mul_f32_e32 v103, 0xc0135761, v103
	v_exp_f32_e32 v96, v96
	v_exp_f32_e32 v97, v97
	v_exp_f32_e32 v98, v98
	v_exp_f32_e32 v99, v99
	v_exp_f32_e32 v100, v100
	v_exp_f32_e32 v101, v101
	v_exp_f32_e32 v102, v102
	v_exp_f32_e32 v103, v103
	v_add_f32_e32 v96, 1.0, v96
	v_add_f32_e32 v97, 1.0, v97
	v_add_f32_e32 v98, 1.0, v98
	v_add_f32_e32 v99, 1.0, v99
	v_add_f32_e32 v100, 1.0, v100
	v_add_f32_e32 v101, 1.0, v101
	v_add_f32_e32 v102, 1.0, v102
	v_add_f32_e32 v103, 1.0, v103
	v_rcp_f32_e32 v96, v96
	v_rcp_f32_e32 v97, v97
	v_rcp_f32_e32 v98, v98
	v_rcp_f32_e32 v99, v99
	v_rcp_f32_e32 v100, v100
	v_rcp_f32_e32 v101, v101
	v_rcp_f32_e32 v102, v102
	v_rcp_f32_e32 v103, v103
	v_pk_mul_f32 v[88:89], v[88:89], v[96:97]
	v_pk_mul_f32 v[90:91], v[90:91], v[98:99]
	v_pk_mul_f32 v[92:93], v[92:93], v[100:101]
	v_pk_mul_f32 v[94:95], v[94:95], v[102:103]
	v_cvt_pk_bf16_f32 v88, v88, v89
	v_cvt_pk_bf16_f32 v89, v90, v91
	v_cvt_pk_bf16_f32 v90, v92, v93
	v_cvt_pk_bf16_f32 v91, v94, v95
	global_store_dwordx4 v[112:113], v[88:91], off
	s_mov_b32 s98, 0x18000
	v_lshl_add_u64 v[252:253], v[250:251], 0, s[98:99]
	global_load_dwordx4 v[246:249], v[252:253], off offset:512
	v_add_u32_e32 v102, s51, v149
	v_ashrrev_i32_e32 v103, 31, v102
	v_lshl_add_u64 v[88:89], s[36:37], 0, v[102:103]
	v_mad_u64_u32 v[104:105], s[56:57], v88, s42, v[142:143]
	v_lshl_add_u64 v[106:107], v[110:111], 0, v[136:137]
	v_mad_i32_i24 v105, v89, s42, v105
	v_lshl_add_u64 v[106:107], v[106:107], 0, s[34:35]
	v_lshl_add_u64 v[88:89], v[104:105], 0, v[138:139]
	v_lshl_add_u64 v[104:105], v[106:107], 0, v[132:133]
	s_waitcnt vmcnt(8)
; DI float bflo(unsigned w) { return __uint_as_float(w << 16); }
; DI float bfhi(unsigned w) { return __uint_as_float(w & 0xffff0000u); }
; DI float gelu_tanh(float y) { const float u = 0.7978845608028654f * (y + 0.044715f * y * y * y); return y * __builtin_amdgcn_rcpf(1.0f + __builtin_amdgcn_exp2f(-2.0f * 1.4426950408889634f * u)); }
; #define EPI_ROWS(...) _Pragma("unroll") for (int ai = 0; ai < 2; ++ai) _Pragma("unroll") for (int m = 0; m < 4; ++m) { const int rr = ai * 128 + wr * 64 + m * 16 + fr; __VA_ARGS__ }
; #define EPI_COLS8(...) _Pragma("unroll") for (int bj = 0; bj < 2; ++bj) { const int cc = bj * 128 + wc * 32 + 8 * fq; const f32x4 v0 = acc[ai][bj][m][0], v1 = acc[ai][bj][m][1]; __VA_ARGS__ }
;     DI void operator()(const Acc& acc, int wr, int wc, int fr, int fq) const {
;         EPI_ROWS(const int chunk = row0 + rr; const bf16_t* ap = Ap + ((size_t)g * 2048 + chunk) * 384 + 128;
;             EPI_COLS8(const int r = cc >> 4, i = cc & 15; const u32x4 uw = *(const u32x4*)(ap + cc); const f32x4 d0 = *(const f32x4*)(dskip + g * 16 + i), d1 = *(const f32x4*)(dskip + g * 16 + i + 4);
;                 const float y0 = v0[0] + d0[0] * bflo(uw.x), y1 = v0[1] + d0[1] * bfhi(uw.x), y2 = v0[2] + d0[2] * bflo(uw.y), y3 = v0[3] + d0[3] * bfhi(uw.y);
;                 const float y4 = v1[0] + d1[0] * bflo(uw.z), y5 = v1[1] + d1[1] * bfhi(uw.z), y6 = v1[2] + d1[2] * bflo(uw.w), y7 = v1[3] + d1[3] * bfhi(uw.w);
;                 u32x4 w; w.x = pk2(gelu_tanh(y0), gelu_tanh(y1)); w.y = pk2(gelu_tanh(y2), gelu_tanh(y3)); w.z = pk2(gelu_tanh(y4), gelu_tanh(y5)); w.w = pk2(gelu_tanh(y6), gelu_tanh(y7));
;                 *(u32x4*)(z + ((size_t)chunk * 16 + r) * 512 + g * 16 + i) = w;))
	v_lshlrev_b32_e32 v106, 16, v182
	v_and_b32_e32 v107, 0xffff0000, v182
	v_lshlrev_b32_e32 v90, 16, v183
	v_and_b32_e32 v91, 0xffff0000, v183
	v_lshlrev_b32_e32 v108, 16, v184
	v_and_b32_e32 v109, 0xffff0000, v184
	v_lshlrev_b32_e32 v92, 16, v185
	v_and_b32_e32 v93, 0xffff0000, v185
	v_pk_fma_f32 v[80:81], v[238:239], v[106:107], v[80:81]
	v_pk_fma_f32 v[82:83], v[240:241], v[90:91], v[82:83]
	v_pk_fma_f32 v[84:85], v[242:243], v[108:109], v[84:85]
	v_pk_fma_f32 v[86:87], v[244:245], v[92:93], v[86:87]
	v_mul_f32_e32 v90, 0x3d372713, v80
	v_mul_f32_e32 v91, 0x3d372713, v81
	v_mul_f32_e32 v92, 0x3d372713, v82
	v_mul_f32_e32 v93, 0x3d372713, v83
	v_mul_f32_e32 v94, 0x3d372713, v84
	v_mul_f32_e32 v95, 0x3d372713, v85
	v_mul_f32_e32 v96, 0x3d372713, v86
	v_mul_f32_e32 v97, 0x3d372713, v87
	v_mul_f32_e32 v90, v80, v90
	v_mul_f32_e32 v91, v81, v91
	v_mul_f32_e32 v92, v82, v92
	v_mul_f32_e32 v93, v83, v93
	v_mul_f32_e32 v94, v84, v94
	v_mul_f32_e32 v95, v85, v95
	v_mul_f32_e32 v96, v86, v96
	v_mul_f32_e32 v97, v87, v97
	v_fma_f32 v90, v80, v90, v80
	v_fma_f32 v91, v81, v91, v81
	v_fma_f32 v92, v82, v92, v82
	v_fma_f32 v93, v83, v93, v83
	v_fma_f32 v94, v84, v94, v84
	v_fma_f32 v95, v85, v95, v85
	v_fma_f32 v96, v86, v96, v86
	v_fma_f32 v97, v87, v97, v87
	v_mul_f32_e32 v90, 0xc0135761, v90
	v_mul_f32_e32 v91, 0xc0135761, v91
	v_mul_f32_e32 v92, 0xc0135761, v92
	v_mul_f32_e32 v93, 0xc0135761, v93
	v_mul_f32_e32 v94, 0xc0135761, v94
	v_mul_f32_e32 v95, 0xc0135761, v95
	v_mul_f32_e32 v96, 0xc0135761, v96
	v_mul_f32_e32 v97, 0xc0135761, v97
	v_exp_f32_e32 v90, v90
	v_exp_f32_e32 v91, v91
	v_exp_f32_e32 v92, v92
	v_exp_f32_e32 v93, v93
	v_exp_f32_e32 v94, v94
	v_exp_f32_e32 v95, v95
	v_exp_f32_e32 v96, v96
	v_exp_f32_e32 v97, v97
	v_add_f32_e32 v90, 1.0, v90
	v_add_f32_e32 v91, 1.0, v91
	v_add_f32_e32 v92, 1.0, v92
	v_add_f32_e32 v93, 1.0, v93
	v_add_f32_e32 v94, 1.0, v94
	v_add_f32_e32 v95, 1.0, v95
	v_add_f32_e32 v96, 1.0, v96
	v_add_f32_e32 v97, 1.0, v97
	v_rcp_f32_e32 v90, v90
	v_rcp_f32_e32 v91, v91
	v_rcp_f32_e32 v92, v92
	v_rcp_f32_e32 v93, v93
	v_rcp_f32_e32 v94, v94
	v_rcp_f32_e32 v95, v95
	v_rcp_f32_e32 v96, v96
	v_rcp_f32_e32 v97, v97
	v_pk_mul_f32 v[80:81], v[80:81], v[90:91]
	v_pk_mul_f32 v[82:83], v[82:83], v[92:93]
	v_pk_mul_f32 v[84:85], v[84:85], v[94:95]
	v_pk_mul_f32 v[86:87], v[86:87], v[96:97]
	v_cvt_pk_bf16_f32 v80, v80, v81
	v_cvt_pk_bf16_f32 v81, v82, v83
	v_cvt_pk_bf16_f32 v82, v84, v85
	v_cvt_pk_bf16_f32 v83, v86, v87
	global_store_dwordx4 v[104:105], v[80:83], off
	s_mov_b32 s98, 0x1b000
	v_lshl_add_u64 v[252:253], v[250:251], 0, s[98:99]
	global_load_dwordx4 v[182:185], v[252:253], off offset:256
	v_lshlrev_b64 v[94:95], 14, v[102:103]
	v_lshl_add_u64 v[94:95], s[26:27], 0, v[94:95]
	v_lshl_add_u64 v[96:97], v[94:95], 0, v[134:135]
	v_lshl_add_u64 v[96:97], v[96:97], 0, s[34:35]
	v_lshl_add_u64 v[96:97], v[96:97], 0, v[132:133]
	s_waitcnt vmcnt(8)
	v_lshlrev_b32_e32 v98, 16, v194
	v_and_b32_e32 v99, 0xffff0000, v194
	v_lshlrev_b32_e32 v80, 16, v195
	v_and_b32_e32 v81, 0xffff0000, v195
	v_lshlrev_b32_e32 v100, 16, v196
	v_and_b32_e32 v101, 0xffff0000, v196
	v_lshlrev_b32_e32 v82, 16, v197
	v_and_b32_e32 v83, 0xffff0000, v197
	v_pk_fma_f32 v[72:73], v[238:239], v[98:99], v[72:73]
	v_pk_fma_f32 v[74:75], v[240:241], v[80:81], v[74:75]
	v_pk_fma_f32 v[76:77], v[242:243], v[100:101], v[76:77]
	v_pk_fma_f32 v[78:79], v[244:245], v[82:83], v[78:79]
	v_mul_f32_e32 v80, 0x3d372713, v72
	v_mul_f32_e32 v81, 0x3d372713, v73
	v_mul_f32_e32 v82, 0x3d372713, v74
	v_mul_f32_e32 v83, 0x3d372713, v75
	v_mul_f32_e32 v84, 0x3d372713, v76
	v_mul_f32_e32 v85, 0x3d372713, v77
	v_mul_f32_e32 v86, 0x3d372713, v78
	v_mul_f32_e32 v87, 0x3d372713, v79
	v_mul_f32_e32 v80, v72, v80
	v_mul_f32_e32 v81, v73, v81
	v_mul_f32_e32 v82, v74, v82
	v_mul_f32_e32 v83, v75, v83
	v_mul_f32_e32 v84, v76, v84
	v_mul_f32_e32 v85, v77, v85
	v_mul_f32_e32 v86, v78, v86
	v_mul_f32_e32 v87, v79, v87
	v_fma_f32 v80, v72, v80, v72
	v_fma_f32 v81, v73, v81, v73
	v_fma_f32 v82, v74, v82, v74
	v_fma_f32 v83, v75, v83, v75
	v_fma_f32 v84, v76, v84, v76
	v_fma_f32 v85, v77, v85, v77
	v_fma_f32 v86, v78, v86, v78
	v_fma_f32 v87, v79, v87, v79
	v_mul_f32_e32 v80, 0xc0135761, v80
	v_mul_f32_e32 v81, 0xc0135761, v81
	v_mul_f32_e32 v82, 0xc0135761, v82
	v_mul_f32_e32 v83, 0xc0135761, v83
	v_mul_f32_e32 v84, 0xc0135761, v84
	v_mul_f32_e32 v85, 0xc0135761, v85
	v_mul_f32_e32 v86, 0xc0135761, v86
	v_mul_f32_e32 v87, 0xc0135761, v87
	v_exp_f32_e32 v80, v80
	v_exp_f32_e32 v81, v81
	v_exp_f32_e32 v82, v82
	v_exp_f32_e32 v83, v83
	v_exp_f32_e32 v84, v84
	v_exp_f32_e32 v85, v85
	v_exp_f32_e32 v86, v86
	v_exp_f32_e32 v87, v87
	v_add_f32_e32 v80, 1.0, v80
	v_add_f32_e32 v81, 1.0, v81
	v_add_f32_e32 v82, 1.0, v82
	v_add_f32_e32 v83, 1.0, v83
	v_add_f32_e32 v84, 1.0, v84
	v_add_f32_e32 v85, 1.0, v85
	v_add_f32_e32 v86, 1.0, v86
	v_add_f32_e32 v87, 1.0, v87
	v_rcp_f32_e32 v80, v80
	v_rcp_f32_e32 v81, v81
	v_rcp_f32_e32 v82, v82
	v_rcp_f32_e32 v83, v83
	v_rcp_f32_e32 v84, v84
	v_rcp_f32_e32 v85, v85
	v_rcp_f32_e32 v86, v86
	v_rcp_f32_e32 v87, v87
	v_pk_mul_f32 v[72:73], v[72:73], v[80:81]
	v_pk_mul_f32 v[74:75], v[74:75], v[82:83]
	v_pk_mul_f32 v[76:77], v[76:77], v[84:85]
	v_pk_mul_f32 v[78:79], v[78:79], v[86:87]
	v_cvt_pk_bf16_f32 v72, v72, v73
	v_cvt_pk_bf16_f32 v73, v74, v75
	v_cvt_pk_bf16_f32 v74, v76, v77
	v_cvt_pk_bf16_f32 v75, v78, v79
	global_store_dwordx4 v[96:97], v[72:75], off
	s_mov_b32 s98, 0x1b000
	v_lshl_add_u64 v[252:253], v[250:251], 0, s[98:99]
	global_load_dwordx4 v[194:197], v[252:253], off offset:512
	v_add_u32_e32 v86, 0x80, v140
	v_ashrrev_i32_e32 v87, 31, v86
	v_lshl_add_u64 v[72:73], s[36:37], 0, v[86:87]
	v_mad_u64_u32 v[90:91], s[56:57], v72, s42, v[142:143]
	v_mad_i32_i24 v91, v73, s42, v91
	v_lshl_add_u64 v[72:73], v[90:91], 0, v[138:139]
	v_lshl_add_u64 v[88:89], v[94:95], 0, v[136:137]
	v_lshl_add_u64 v[88:89], v[88:89], 0, s[34:35]
	v_lshl_add_u64 v[88:89], v[88:89], 0, v[132:133]
	s_waitcnt vmcnt(8)
; DI float bflo(unsigned w) { return __uint_as_float(w << 16); }
; DI float bfhi(unsigned w) { return __uint_as_float(w & 0xffff0000u); }
; DI float gelu_tanh(float y) { const float u = 0.7978845608028654f * (y + 0.044715f * y * y * y); return y * __builtin_amdgcn_rcpf(1.0f + __builtin_amdgcn_exp2f(-2.0f * 1.4426950408889634f * u)); }
; #define EPI_ROWS(...) _Pragma("unroll") for (int ai = 0; ai < 2; ++ai) _Pragma("unroll") for (int m = 0; m < 4; ++m) { const int rr = ai * 128 + wr * 64 + m * 16 + fr; __VA_ARGS__ }
; #define EPI_COLS8(...) _Pragma("unroll") for (int bj = 0; bj < 2; ++bj) { const int cc = bj * 128 + wc * 32 + 8 * fq; const f32x4 v0 = acc[ai][bj][m][0], v1 = acc[ai][bj][m][1]; __VA_ARGS__ }
;     DI void operator()(const Acc& acc, int wr, int wc, int fr, int fq) const {
;         EPI_ROWS(const int chunk = row0 + rr; const bf16_t* ap = Ap + ((size_t)g * 2048 + chunk) * 384 + 128;
;             EPI_COLS8(const int r = cc >> 4, i = cc & 15; const u32x4 uw = *(const u32x4*)(ap + cc); const f32x4 d0 = *(const f32x4*)(dskip + g * 16 + i), d1 = *(const f32x4*)(dskip + g * 16 + i + 4);
;                 const float y0 = v0[0] + d0[0] * bflo(uw.x), y1 = v0[1] + d0[1] * bfhi(uw.x), y2 = v0[2] + d0[2] * bflo(uw.y), y3 = v0[3] + d0[3] * bfhi(uw.y);
;                 const float y4 = v1[0] + d1[0] * bflo(uw.z), y5 = v1[1] + d1[1] * bfhi(uw.z), y6 = v1[2] + d1[2] * bflo(uw.w), y7 = v1[3] + d1[3] * bfhi(uw.w);
;                 u32x4 w; w.x = pk2(gelu_tanh(y0), gelu_tanh(y1)); w.y = pk2(gelu_tanh(y2), gelu_tanh(y3)); w.z = pk2(gelu_tanh(y4), gelu_tanh(y5)); w.w = pk2(gelu_tanh(y6), gelu_tanh(y7));
;                 *(u32x4*)(z + ((size_t)chunk * 16 + r) * 512 + g * 16 + i) = w;))
	v_lshlrev_b32_e32 v90, 16, v198
	v_and_b32_e32 v91, 0xffff0000, v198
	v_lshlrev_b32_e32 v74, 16, v199
	v_and_b32_e32 v75, 0xffff0000, v199
	v_lshlrev_b32_e32 v92, 16, v200
	v_and_b32_e32 v93, 0xffff0000, v200
	v_lshlrev_b32_e32 v76, 16, v201
	v_and_b32_e32 v77, 0xffff0000, v201
	v_pk_fma_f32 v[64:65], v[238:239], v[90:91], v[64:65]
	v_pk_fma_f32 v[66:67], v[240:241], v[74:75], v[66:67]
	v_pk_fma_f32 v[68:69], v[242:243], v[92:93], v[68:69]
	v_pk_fma_f32 v[70:71], v[244:245], v[76:77], v[70:71]
	v_mul_f32_e32 v74, 0x3d372713, v64
	v_mul_f32_e32 v75, 0x3d372713, v65
	v_mul_f32_e32 v76, 0x3d372713, v66
	v_mul_f32_e32 v77, 0x3d372713, v67
	v_mul_f32_e32 v78, 0x3d372713, v68
	v_mul_f32_e32 v79, 0x3d372713, v69
	v_mul_f32_e32 v80, 0x3d372713, v70
	v_mul_f32_e32 v81, 0x3d372713, v71
	v_mul_f32_e32 v74, v64, v74
	v_mul_f32_e32 v75, v65, v75
	v_mul_f32_e32 v76, v66, v76
	v_mul_f32_e32 v77, v67, v77
	v_mul_f32_e32 v78, v68, v78
	v_mul_f32_e32 v79, v69, v79
	v_mul_f32_e32 v80, v70, v80
	v_mul_f32_e32 v81, v71, v81
	v_fma_f32 v74, v64, v74, v64
	v_fma_f32 v75, v65, v75, v65
	v_fma_f32 v76, v66, v76, v66
	v_fma_f32 v77, v67, v77, v67
	v_fma_f32 v78, v68, v78, v68
	v_fma_f32 v79, v69, v79, v69
	v_fma_f32 v80, v70, v80, v70
	v_fma_f32 v81, v71, v81, v71
	v_mul_f32_e32 v74, 0xc0135761, v74
	v_mul_f32_e32 v75, 0xc0135761, v75
	v_mul_f32_e32 v76, 0xc0135761, v76
	v_mul_f32_e32 v77, 0xc0135761, v77
	v_mul_f32_e32 v78, 0xc0135761, v78
	v_mul_f32_e32 v79, 0xc0135761, v79
	v_mul_f32_e32 v80, 0xc0135761, v80
	v_mul_f32_e32 v81, 0xc0135761, v81
	v_exp_f32_e32 v74, v74
	v_exp_f32_e32 v75, v75
	v_exp_f32_e32 v76, v76
	v_exp_f32_e32 v77, v77
	v_exp_f32_e32 v78, v78
	v_exp_f32_e32 v79, v79
	v_exp_f32_e32 v80, v80
	v_exp_f32_e32 v81, v81
	v_add_f32_e32 v74, 1.0, v74
	v_add_f32_e32 v75, 1.0, v75
	v_add_f32_e32 v76, 1.0, v76
	v_add_f32_e32 v77, 1.0, v77
	v_add_f32_e32 v78, 1.0, v78
	v_add_f32_e32 v79, 1.0, v79
	v_add_f32_e32 v80, 1.0, v80
	v_add_f32_e32 v81, 1.0, v81
	v_rcp_f32_e32 v74, v74
	v_rcp_f32_e32 v75, v75
	v_rcp_f32_e32 v76, v76
	v_rcp_f32_e32 v77, v77
	v_rcp_f32_e32 v78, v78
	v_rcp_f32_e32 v79, v79
	v_rcp_f32_e32 v80, v80
	v_rcp_f32_e32 v81, v81
	v_pk_mul_f32 v[64:65], v[64:65], v[74:75]
	v_pk_mul_f32 v[66:67], v[66:67], v[76:77]
	v_pk_mul_f32 v[68:69], v[68:69], v[78:79]
	v_pk_mul_f32 v[70:71], v[70:71], v[80:81]
	v_cvt_pk_bf16_f32 v64, v64, v65
	v_cvt_pk_bf16_f32 v65, v66, v67
	v_cvt_pk_bf16_f32 v66, v68, v69
	v_cvt_pk_bf16_f32 v67, v70, v71
	global_store_dwordx4 v[88:89], v[64:67], off
	s_mov_b32 s98, 0x1e000
	v_lshl_add_u64 v[252:253], v[250:251], 0, s[98:99]
	global_load_dwordx4 v[198:201], v[252:253], off offset:256
	v_lshlrev_b64 v[78:79], 14, v[86:87]
	v_lshl_add_u64 v[78:79], s[26:27], 0, v[78:79]
	v_lshl_add_u64 v[80:81], v[78:79], 0, v[134:135]
	v_lshl_add_u64 v[80:81], v[80:81], 0, s[34:35]
	v_lshl_add_u64 v[80:81], v[80:81], 0, v[132:133]
	s_waitcnt vmcnt(8)
	v_lshlrev_b32_e32 v82, 16, v202
	v_and_b32_e32 v83, 0xffff0000, v202
	v_lshlrev_b32_e32 v64, 16, v203
	v_and_b32_e32 v65, 0xffff0000, v203
	v_lshlrev_b32_e32 v84, 16, v204
	v_and_b32_e32 v85, 0xffff0000, v204
	v_lshlrev_b32_e32 v66, 16, v205
	v_and_b32_e32 v67, 0xffff0000, v205
	v_pk_fma_f32 v[56:57], v[238:239], v[82:83], v[56:57]
	v_pk_fma_f32 v[58:59], v[240:241], v[64:65], v[58:59]
	v_pk_fma_f32 v[60:61], v[242:243], v[84:85], v[60:61]
	v_pk_fma_f32 v[62:63], v[244:245], v[66:67], v[62:63]
	v_mul_f32_e32 v64, 0x3d372713, v56
	v_mul_f32_e32 v65, 0x3d372713, v57
	v_mul_f32_e32 v66, 0x3d372713, v58
	v_mul_f32_e32 v67, 0x3d372713, v59
	v_mul_f32_e32 v68, 0x3d372713, v60
	v_mul_f32_e32 v69, 0x3d372713, v61
	v_mul_f32_e32 v70, 0x3d372713, v62
	v_mul_f32_e32 v71, 0x3d372713, v63
	v_mul_f32_e32 v64, v56, v64
	v_mul_f32_e32 v65, v57, v65
	v_mul_f32_e32 v66, v58, v66
	v_mul_f32_e32 v67, v59, v67
	v_mul_f32_e32 v68, v60, v68
	v_mul_f32_e32 v69, v61, v69
	v_mul_f32_e32 v70, v62, v70
	v_mul_f32_e32 v71, v63, v71
	v_fma_f32 v64, v56, v64, v56
	v_fma_f32 v65, v57, v65, v57
	v_fma_f32 v66, v58, v66, v58
	v_fma_f32 v67, v59, v67, v59
	v_fma_f32 v68, v60, v68, v60
	v_fma_f32 v69, v61, v69, v61
	v_fma_f32 v70, v62, v70, v62
	v_fma_f32 v71, v63, v71, v63
	v_mul_f32_e32 v64, 0xc0135761, v64
	v_mul_f32_e32 v65, 0xc0135761, v65
	v_mul_f32_e32 v66, 0xc0135761, v66
	v_mul_f32_e32 v67, 0xc0135761, v67
	v_mul_f32_e32 v68, 0xc0135761, v68
	v_mul_f32_e32 v69, 0xc0135761, v69
	v_mul_f32_e32 v70, 0xc0135761, v70
	v_mul_f32_e32 v71, 0xc0135761, v71
	v_exp_f32_e32 v64, v64
	v_exp_f32_e32 v65, v65
	v_exp_f32_e32 v66, v66
	v_exp_f32_e32 v67, v67
	v_exp_f32_e32 v68, v68
	v_exp_f32_e32 v69, v69
	v_exp_f32_e32 v70, v70
	v_exp_f32_e32 v71, v71
	v_add_f32_e32 v64, 1.0, v64
	v_add_f32_e32 v65, 1.0, v65
	v_add_f32_e32 v66, 1.0, v66
	v_add_f32_e32 v67, 1.0, v67
	v_add_f32_e32 v68, 1.0, v68
	v_add_f32_e32 v69, 1.0, v69
	v_add_f32_e32 v70, 1.0, v70
	v_add_f32_e32 v71, 1.0, v71
	v_rcp_f32_e32 v64, v64
	v_rcp_f32_e32 v65, v65
	v_rcp_f32_e32 v66, v66
	v_rcp_f32_e32 v67, v67
	v_rcp_f32_e32 v68, v68
	v_rcp_f32_e32 v69, v69
	v_rcp_f32_e32 v70, v70
	v_rcp_f32_e32 v71, v71
	v_pk_mul_f32 v[56:57], v[56:57], v[64:65]
	v_pk_mul_f32 v[58:59], v[58:59], v[66:67]
	v_pk_mul_f32 v[60:61], v[60:61], v[68:69]
	v_pk_mul_f32 v[62:63], v[62:63], v[70:71]
	v_cvt_pk_bf16_f32 v56, v56, v57
	v_cvt_pk_bf16_f32 v57, v58, v59
	v_cvt_pk_bf16_f32 v58, v60, v61
	v_cvt_pk_bf16_f32 v59, v62, v63
	global_store_dwordx4 v[80:81], v[56:59], off
	s_mov_b32 s98, 0x1e000
	v_lshl_add_u64 v[252:253], v[250:251], 0, s[98:99]
	global_load_dwordx4 v[202:205], v[252:253], off offset:512
	v_add_u32_e32 v70, 0x90, v140
	v_ashrrev_i32_e32 v71, 31, v70
	v_lshl_add_u64 v[56:57], s[36:37], 0, v[70:71]
	v_mad_u64_u32 v[72:73], s[56:57], v56, s42, v[142:143]
	v_lshl_add_u64 v[74:75], v[78:79], 0, v[136:137]
	v_mad_i32_i24 v73, v57, s42, v73
	v_lshl_add_u64 v[74:75], v[74:75], 0, s[34:35]
	v_lshl_add_u64 v[56:57], v[72:73], 0, v[138:139]
	v_lshl_add_u64 v[72:73], v[74:75], 0, v[132:133]
	s_waitcnt vmcnt(8)
; DI float bflo(unsigned w) { return __uint_as_float(w << 16); }
; DI float bfhi(unsigned w) { return __uint_as_float(w & 0xffff0000u); }
; DI float gelu_tanh(float y) { const float u = 0.7978845608028654f * (y + 0.044715f * y * y * y); return y * __builtin_amdgcn_rcpf(1.0f + __builtin_amdgcn_exp2f(-2.0f * 1.4426950408889634f * u)); }
; #define EPI_ROWS(...) _Pragma("unroll") for (int ai = 0; ai < 2; ++ai) _Pragma("unroll") for (int m = 0; m < 4; ++m) { const int rr = ai * 128 + wr * 64 + m * 16 + fr; __VA_ARGS__ }
; #define EPI_COLS8(...) _Pragma("unroll") for (int bj = 0; bj < 2; ++bj) { const int cc = bj * 128 + wc * 32 + 8 * fq; const f32x4 v0 = acc[ai][bj][m][0], v1 = acc[ai][bj][m][1]; __VA_ARGS__ }
;     DI void operator()(const Acc& acc, int wr, int wc, int fr, int fq) const {
;         EPI_ROWS(const int chunk = row0 + rr; const bf16_t* ap = Ap + ((size_t)g * 2048 + chunk) * 384 + 128;
;             EPI_COLS8(const int r = cc >> 4, i = cc & 15; const u32x4 uw = *(const u32x4*)(ap + cc); const f32x4 d0 = *(const f32x4*)(dskip + g * 16 + i), d1 = *(const f32x4*)(dskip + g * 16 + i + 4);
;                 const float y0 = v0[0] + d0[0] * bflo(uw.x), y1 = v0[1] + d0[1] * bfhi(uw.x), y2 = v0[2] + d0[2] * bflo(uw.y), y3 = v0[3] + d0[3] * bfhi(uw.y);
;                 const float y4 = v1[0] + d1[0] * bflo(uw.z), y5 = v1[1] + d1[1] * bfhi(uw.z), y6 = v1[2] + d1[2] * bflo(uw.w), y7 = v1[3] + d1[3] * bfhi(uw.w);
;                 u32x4 w; w.x = pk2(gelu_tanh(y0), gelu_tanh(y1)); w.y = pk2(gelu_tanh(y2), gelu_tanh(y3)); w.z = pk2(gelu_tanh(y4), gelu_tanh(y5)); w.w = pk2(gelu_tanh(y6), gelu_tanh(y7));
;                 *(u32x4*)(z + ((size_t)chunk * 16 + r) * 512 + g * 16 + i) = w;))
	v_lshlrev_b32_e32 v74, 16, v246
	v_and_b32_e32 v75, 0xffff0000, v246
	v_lshlrev_b32_e32 v58, 16, v247
	v_and_b32_e32 v59, 0xffff0000, v247
	v_lshlrev_b32_e32 v76, 16, v248
	v_and_b32_e32 v77, 0xffff0000, v248
	v_lshlrev_b32_e32 v60, 16, v249
	v_and_b32_e32 v61, 0xffff0000, v249
	v_pk_fma_f32 v[48:49], v[238:239], v[74:75], v[48:49]
	v_pk_fma_f32 v[50:51], v[240:241], v[58:59], v[50:51]
	v_pk_fma_f32 v[52:53], v[242:243], v[76:77], v[52:53]
	v_pk_fma_f32 v[54:55], v[244:245], v[60:61], v[54:55]
	v_mul_f32_e32 v58, 0x3d372713, v48
	v_mul_f32_e32 v59, 0x3d372713, v49
	v_mul_f32_e32 v60, 0x3d372713, v50
	v_mul_f32_e32 v61, 0x3d372713, v51
	v_mul_f32_e32 v62, 0x3d372713, v52
	v_mul_f32_e32 v63, 0x3d372713, v53
	v_mul_f32_e32 v64, 0x3d372713, v54
	v_mul_f32_e32 v65, 0x3d372713, v55
	v_mul_f32_e32 v58, v48, v58
	v_mul_f32_e32 v59, v49, v59
	v_mul_f32_e32 v60, v50, v60
	v_mul_f32_e32 v61, v51, v61
	v_mul_f32_e32 v62, v52, v62
	v_mul_f32_e32 v63, v53, v63
	v_mul_f32_e32 v64, v54, v64
	v_mul_f32_e32 v65, v55, v65
	v_fma_f32 v58, v48, v58, v48
	v_fma_f32 v59, v49, v59, v49
	v_fma_f32 v60, v50, v60, v50
	v_fma_f32 v61, v51, v61, v51
	v_fma_f32 v62, v52, v62, v52
	v_fma_f32 v63, v53, v63, v53
	v_fma_f32 v64, v54, v64, v54
	v_fma_f32 v65, v55, v65, v55
	v_mul_f32_e32 v58, 0xc0135761, v58
	v_mul_f32_e32 v59, 0xc0135761, v59
	v_mul_f32_e32 v60, 0xc0135761, v60
	v_mul_f32_e32 v61, 0xc0135761, v61
	v_mul_f32_e32 v62, 0xc0135761, v62
	v_mul_f32_e32 v63, 0xc0135761, v63
	v_mul_f32_e32 v64, 0xc0135761, v64
	v_mul_f32_e32 v65, 0xc0135761, v65
	v_exp_f32_e32 v58, v58
	v_exp_f32_e32 v59, v59
	v_exp_f32_e32 v60, v60
	v_exp_f32_e32 v61, v61
	v_exp_f32_e32 v62, v62
	v_exp_f32_e32 v63, v63
	v_exp_f32_e32 v64, v64
	v_exp_f32_e32 v65, v65
	v_add_f32_e32 v58, 1.0, v58
	v_add_f32_e32 v59, 1.0, v59
	v_add_f32_e32 v60, 1.0, v60
	v_add_f32_e32 v61, 1.0, v61
	v_add_f32_e32 v62, 1.0, v62
	v_add_f32_e32 v63, 1.0, v63
	v_add_f32_e32 v64, 1.0, v64
	v_add_f32_e32 v65, 1.0, v65
	v_rcp_f32_e32 v58, v58
	v_rcp_f32_e32 v59, v59
	v_rcp_f32_e32 v60, v60
	v_rcp_f32_e32 v61, v61
	v_rcp_f32_e32 v62, v62
	v_rcp_f32_e32 v63, v63
	v_rcp_f32_e32 v64, v64
	v_rcp_f32_e32 v65, v65
	v_pk_mul_f32 v[48:49], v[48:49], v[58:59]
	v_pk_mul_f32 v[50:51], v[50:51], v[60:61]
	v_pk_mul_f32 v[52:53], v[52:53], v[62:63]
	v_pk_mul_f32 v[54:55], v[54:55], v[64:65]
	v_cvt_pk_bf16_f32 v48, v48, v49
	v_cvt_pk_bf16_f32 v49, v50, v51
	v_cvt_pk_bf16_f32 v50, v52, v53
	v_cvt_pk_bf16_f32 v51, v54, v55
	global_store_dwordx4 v[72:73], v[48:51], off
	s_mov_b32 s98, 0x21000
	v_lshl_add_u64 v[252:253], v[250:251], 0, s[98:99]
	global_load_dwordx4 v[246:249], v[252:253], off offset:256
	v_lshlrev_b64 v[62:63], 14, v[70:71]
	v_lshl_add_u64 v[62:63], s[26:27], 0, v[62:63]
	v_lshl_add_u64 v[64:65], v[62:63], 0, v[134:135]
	v_lshl_add_u64 v[64:65], v[64:65], 0, s[34:35]
	v_lshl_add_u64 v[64:65], v[64:65], 0, v[132:133]
	s_waitcnt vmcnt(8)
	v_lshlrev_b32_e32 v66, 16, v182
	v_and_b32_e32 v67, 0xffff0000, v182
	v_lshlrev_b32_e32 v48, 16, v183
	v_and_b32_e32 v49, 0xffff0000, v183
	v_lshlrev_b32_e32 v68, 16, v184
	v_and_b32_e32 v69, 0xffff0000, v184
	v_lshlrev_b32_e32 v50, 16, v185
	v_and_b32_e32 v51, 0xffff0000, v185
	v_pk_fma_f32 v[40:41], v[238:239], v[66:67], v[40:41]
	v_pk_fma_f32 v[42:43], v[240:241], v[48:49], v[42:43]
	v_pk_fma_f32 v[44:45], v[242:243], v[68:69], v[44:45]
	v_pk_fma_f32 v[46:47], v[244:245], v[50:51], v[46:47]
	v_mul_f32_e32 v48, 0x3d372713, v40
	v_mul_f32_e32 v49, 0x3d372713, v41
	v_mul_f32_e32 v50, 0x3d372713, v42
	v_mul_f32_e32 v51, 0x3d372713, v43
	v_mul_f32_e32 v52, 0x3d372713, v44
	v_mul_f32_e32 v53, 0x3d372713, v45
	v_mul_f32_e32 v54, 0x3d372713, v46
	v_mul_f32_e32 v55, 0x3d372713, v47
	v_mul_f32_e32 v48, v40, v48
	v_mul_f32_e32 v49, v41, v49
	v_mul_f32_e32 v50, v42, v50
	v_mul_f32_e32 v51, v43, v51
	v_mul_f32_e32 v52, v44, v52
	v_mul_f32_e32 v53, v45, v53
	v_mul_f32_e32 v54, v46, v54
	v_mul_f32_e32 v55, v47, v55
	v_fma_f32 v48, v40, v48, v40
	v_fma_f32 v49, v41, v49, v41
	v_fma_f32 v50, v42, v50, v42
	v_fma_f32 v51, v43, v51, v43
	v_fma_f32 v52, v44, v52, v44
	v_fma_f32 v53, v45, v53, v45
	v_fma_f32 v54, v46, v54, v46
	v_fma_f32 v55, v47, v55, v47
	v_mul_f32_e32 v48, 0xc0135761, v48
	v_mul_f32_e32 v49, 0xc0135761, v49
	v_mul_f32_e32 v50, 0xc0135761, v50
	v_mul_f32_e32 v51, 0xc0135761, v51
	v_mul_f32_e32 v52, 0xc0135761, v52
	v_mul_f32_e32 v53, 0xc0135761, v53
	v_mul_f32_e32 v54, 0xc0135761, v54
	v_mul_f32_e32 v55, 0xc0135761, v55
	v_exp_f32_e32 v48, v48
	v_exp_f32_e32 v49, v49
	v_exp_f32_e32 v50, v50
	v_exp_f32_e32 v51, v51
	v_exp_f32_e32 v52, v52
	v_exp_f32_e32 v53, v53
	v_exp_f32_e32 v54, v54
	v_exp_f32_e32 v55, v55
	v_add_f32_e32 v48, 1.0, v48
	v_add_f32_e32 v49, 1.0, v49
	v_add_f32_e32 v50, 1.0, v50
	v_add_f32_e32 v51, 1.0, v51
	v_add_f32_e32 v52, 1.0, v52
	v_add_f32_e32 v53, 1.0, v53
	v_add_f32_e32 v54, 1.0, v54
	v_add_f32_e32 v55, 1.0, v55
	v_rcp_f32_e32 v48, v48
	v_rcp_f32_e32 v49, v49
	v_rcp_f32_e32 v50, v50
	v_rcp_f32_e32 v51, v51
	v_rcp_f32_e32 v52, v52
	v_rcp_f32_e32 v53, v53
	v_rcp_f32_e32 v54, v54
	v_rcp_f32_e32 v55, v55
	v_pk_mul_f32 v[40:41], v[40:41], v[48:49]
	v_pk_mul_f32 v[42:43], v[42:43], v[50:51]
	v_pk_mul_f32 v[44:45], v[44:45], v[52:53]
	v_pk_mul_f32 v[46:47], v[46:47], v[54:55]
	v_cvt_pk_bf16_f32 v40, v40, v41
	v_cvt_pk_bf16_f32 v41, v42, v43
	v_cvt_pk_bf16_f32 v42, v44, v45
	v_cvt_pk_bf16_f32 v43, v46, v47
	global_store_dwordx4 v[64:65], v[40:43], off
	s_mov_b32 s98, 0x21000
	v_lshl_add_u64 v[252:253], v[250:251], 0, s[98:99]
	global_load_dwordx4 v[182:185], v[252:253], off offset:512
	v_add_u32_e32 v54, 0xa0, v140
	v_ashrrev_i32_e32 v55, 31, v54
	v_lshl_add_u64 v[40:41], s[36:37], 0, v[54:55]
	v_mad_u64_u32 v[56:57], s[56:57], v40, s42, v[142:143]
	v_lshl_add_u64 v[58:59], v[62:63], 0, v[136:137]
	v_mad_i32_i24 v57, v41, s42, v57
	v_lshl_add_u64 v[58:59], v[58:59], 0, s[34:35]
	v_lshl_add_u64 v[40:41], v[56:57], 0, v[138:139]
	v_lshl_add_u64 v[56:57], v[58:59], 0, v[132:133]
	s_waitcnt vmcnt(8)
; DI float bflo(unsigned w) { return __uint_as_float(w << 16); }
; DI float bfhi(unsigned w) { return __uint_as_float(w & 0xffff0000u); }
; DI float gelu_tanh(float y) { const float u = 0.7978845608028654f * (y + 0.044715f * y * y * y); return y * __builtin_amdgcn_rcpf(1.0f + __builtin_amdgcn_exp2f(-2.0f * 1.4426950408889634f * u)); }
; #define EPI_ROWS(...) _Pragma("unroll") for (int ai = 0; ai < 2; ++ai) _Pragma("unroll") for (int m = 0; m < 4; ++m) { const int rr = ai * 128 + wr * 64 + m * 16 + fr; __VA_ARGS__ }
; #define EPI_COLS8(...) _Pragma("unroll") for (int bj = 0; bj < 2; ++bj) { const int cc = bj * 128 + wc * 32 + 8 * fq; const f32x4 v0 = acc[ai][bj][m][0], v1 = acc[ai][bj][m][1]; __VA_ARGS__ }
;     DI void operator()(const Acc& acc, int wr, int wc, int fr, int fq) const {
;         EPI_ROWS(const int chunk = row0 + rr; const bf16_t* ap = Ap + ((size_t)g * 2048 + chunk) * 384 + 128;
;             EPI_COLS8(const int r = cc >> 4, i = cc & 15; const u32x4 uw = *(const u32x4*)(ap + cc); const f32x4 d0 = *(const f32x4*)(dskip + g * 16 + i), d1 = *(const f32x4*)(dskip + g * 16 + i + 4);
;                 const float y0 = v0[0] + d0[0] * bflo(uw.x), y1 = v0[1] + d0[1] * bfhi(uw.x), y2 = v0[2] + d0[2] * bflo(uw.y), y3 = v0[3] + d0[3] * bfhi(uw.y);
;                 const float y4 = v1[0] + d1[0] * bflo(uw.z), y5 = v1[1] + d1[1] * bfhi(uw.z), y6 = v1[2] + d1[2] * bflo(uw.w), y7 = v1[3] + d1[3] * bfhi(uw.w);
;                 u32x4 w; w.x = pk2(gelu_tanh(y0), gelu_tanh(y1)); w.y = pk2(gelu_tanh(y2), gelu_tanh(y3)); w.z = pk2(gelu_tanh(y4), gelu_tanh(y5)); w.w = pk2(gelu_tanh(y6), gelu_tanh(y7));
;                 *(u32x4*)(z + ((size_t)chunk * 16 + r) * 512 + g * 16 + i) = w;))
	v_lshlrev_b32_e32 v58, 16, v194
	v_and_b32_e32 v59, 0xffff0000, v194
	v_lshlrev_b32_e32 v42, 16, v195
	v_and_b32_e32 v43, 0xffff0000, v195
	v_lshlrev_b32_e32 v60, 16, v196
	v_and_b32_e32 v61, 0xffff0000, v196
	v_lshlrev_b32_e32 v44, 16, v197
	v_and_b32_e32 v45, 0xffff0000, v197
	v_pk_fma_f32 v[32:33], v[238:239], v[58:59], v[32:33]
	v_pk_fma_f32 v[34:35], v[240:241], v[42:43], v[34:35]
	v_pk_fma_f32 v[36:37], v[242:243], v[60:61], v[36:37]
	v_pk_fma_f32 v[38:39], v[244:245], v[44:45], v[38:39]
	v_mul_f32_e32 v42, 0x3d372713, v32
	v_mul_f32_e32 v43, 0x3d372713, v33
	v_mul_f32_e32 v44, 0x3d372713, v34
	v_mul_f32_e32 v45, 0x3d372713, v35
	v_mul_f32_e32 v46, 0x3d372713, v36
	v_mul_f32_e32 v47, 0x3d372713, v37
	v_mul_f32_e32 v48, 0x3d372713, v38
	v_mul_f32_e32 v49, 0x3d372713, v39
	v_mul_f32_e32 v42, v32, v42
	v_mul_f32_e32 v43, v33, v43
	v_mul_f32_e32 v44, v34, v44
	v_mul_f32_e32 v45, v35, v45
	v_mul_f32_e32 v46, v36, v46
	v_mul_f32_e32 v47, v37, v47
	v_mul_f32_e32 v48, v38, v48
	v_mul_f32_e32 v49, v39, v49
	v_fma_f32 v42, v32, v42, v32
	v_fma_f32 v43, v33, v43, v33
	v_fma_f32 v44, v34, v44, v34
	v_fma_f32 v45, v35, v45, v35
	v_fma_f32 v46, v36, v46, v36
	v_fma_f32 v47, v37, v47, v37
	v_fma_f32 v48, v38, v48, v38
	v_fma_f32 v49, v39, v49, v39
	v_mul_f32_e32 v42, 0xc0135761, v42
	v_mul_f32_e32 v43, 0xc0135761, v43
	v_mul_f32_e32 v44, 0xc0135761, v44
	v_mul_f32_e32 v45, 0xc0135761, v45
	v_mul_f32_e32 v46, 0xc0135761, v46
	v_mul_f32_e32 v47, 0xc0135761, v47
	v_mul_f32_e32 v48, 0xc0135761, v48
	v_mul_f32_e32 v49, 0xc0135761, v49
	v_exp_f32_e32 v42, v42
	v_exp_f32_e32 v43, v43
	v_exp_f32_e32 v44, v44
	v_exp_f32_e32 v45, v45
	v_exp_f32_e32 v46, v46
	v_exp_f32_e32 v47, v47
	v_exp_f32_e32 v48, v48
	v_exp_f32_e32 v49, v49
	v_add_f32_e32 v42, 1.0, v42
	v_add_f32_e32 v43, 1.0, v43
	v_add_f32_e32 v44, 1.0, v44
	v_add_f32_e32 v45, 1.0, v45
	v_add_f32_e32 v46, 1.0, v46
	v_add_f32_e32 v47, 1.0, v47
	v_add_f32_e32 v48, 1.0, v48
	v_add_f32_e32 v49, 1.0, v49
	v_rcp_f32_e32 v42, v42
	v_rcp_f32_e32 v43, v43
	v_rcp_f32_e32 v44, v44
	v_rcp_f32_e32 v45, v45
	v_rcp_f32_e32 v46, v46
	v_rcp_f32_e32 v47, v47
	v_rcp_f32_e32 v48, v48
	v_rcp_f32_e32 v49, v49
	v_pk_mul_f32 v[32:33], v[32:33], v[42:43]
	v_pk_mul_f32 v[34:35], v[34:35], v[44:45]
	v_pk_mul_f32 v[36:37], v[36:37], v[46:47]
	v_pk_mul_f32 v[38:39], v[38:39], v[48:49]
	v_cvt_pk_bf16_f32 v32, v32, v33
	v_cvt_pk_bf16_f32 v33, v34, v35
	v_cvt_pk_bf16_f32 v34, v36, v37
	v_cvt_pk_bf16_f32 v35, v38, v39
	global_store_dwordx4 v[56:57], v[32:35], off
	v_lshlrev_b64 v[46:47], 14, v[54:55]
	v_lshl_add_u64 v[46:47], s[26:27], 0, v[46:47]
	v_lshl_add_u64 v[48:49], v[46:47], 0, v[134:135]
	v_lshl_add_u64 v[48:49], v[48:49], 0, s[34:35]
	v_lshl_add_u64 v[48:49], v[48:49], 0, v[132:133]
	s_waitcnt vmcnt(7)
	v_lshlrev_b32_e32 v50, 16, v198
	v_and_b32_e32 v51, 0xffff0000, v198
	v_lshlrev_b32_e32 v32, 16, v199
	v_and_b32_e32 v33, 0xffff0000, v199
	v_lshlrev_b32_e32 v52, 16, v200
	v_and_b32_e32 v53, 0xffff0000, v200
	v_lshlrev_b32_e32 v34, 16, v201
	v_and_b32_e32 v35, 0xffff0000, v201
	v_pk_fma_f32 v[24:25], v[238:239], v[50:51], v[24:25]
	v_pk_fma_f32 v[26:27], v[240:241], v[32:33], v[26:27]
	v_pk_fma_f32 v[28:29], v[242:243], v[52:53], v[28:29]
	v_pk_fma_f32 v[30:31], v[244:245], v[34:35], v[30:31]
	v_mul_f32_e32 v32, 0x3d372713, v24
	v_mul_f32_e32 v33, 0x3d372713, v25
	v_mul_f32_e32 v34, 0x3d372713, v26
	v_mul_f32_e32 v35, 0x3d372713, v27
	v_mul_f32_e32 v36, 0x3d372713, v28
	v_mul_f32_e32 v37, 0x3d372713, v29
	v_mul_f32_e32 v38, 0x3d372713, v30
	v_mul_f32_e32 v39, 0x3d372713, v31
	v_mul_f32_e32 v32, v24, v32
	v_mul_f32_e32 v33, v25, v33
	v_mul_f32_e32 v34, v26, v34
	v_mul_f32_e32 v35, v27, v35
	v_mul_f32_e32 v36, v28, v36
	v_mul_f32_e32 v37, v29, v37
	v_mul_f32_e32 v38, v30, v38
	v_mul_f32_e32 v39, v31, v39
	v_fma_f32 v32, v24, v32, v24
	v_fma_f32 v33, v25, v33, v25
	v_fma_f32 v34, v26, v34, v26
	v_fma_f32 v35, v27, v35, v27
	v_fma_f32 v36, v28, v36, v28
	v_fma_f32 v37, v29, v37, v29
	v_fma_f32 v38, v30, v38, v30
	v_fma_f32 v39, v31, v39, v31
	v_mul_f32_e32 v32, 0xc0135761, v32
	v_mul_f32_e32 v33, 0xc0135761, v33
	v_mul_f32_e32 v34, 0xc0135761, v34
	v_mul_f32_e32 v35, 0xc0135761, v35
	v_mul_f32_e32 v36, 0xc0135761, v36
	v_mul_f32_e32 v37, 0xc0135761, v37
	v_mul_f32_e32 v38, 0xc0135761, v38
	v_mul_f32_e32 v39, 0xc0135761, v39
	v_exp_f32_e32 v32, v32
	v_exp_f32_e32 v33, v33
	v_exp_f32_e32 v34, v34
	v_exp_f32_e32 v35, v35
	v_exp_f32_e32 v36, v36
	v_exp_f32_e32 v37, v37
	v_exp_f32_e32 v38, v38
	v_exp_f32_e32 v39, v39
	v_add_f32_e32 v32, 1.0, v32
	v_add_f32_e32 v33, 1.0, v33
	v_add_f32_e32 v34, 1.0, v34
	v_add_f32_e32 v35, 1.0, v35
	v_add_f32_e32 v36, 1.0, v36
	v_add_f32_e32 v37, 1.0, v37
	v_add_f32_e32 v38, 1.0, v38
	v_add_f32_e32 v39, 1.0, v39
	v_rcp_f32_e32 v32, v32
	v_rcp_f32_e32 v33, v33
	v_rcp_f32_e32 v34, v34
	v_rcp_f32_e32 v35, v35
	v_rcp_f32_e32 v36, v36
	v_rcp_f32_e32 v37, v37
	v_rcp_f32_e32 v38, v38
	v_rcp_f32_e32 v39, v39
	v_pk_mul_f32 v[24:25], v[24:25], v[32:33]
	v_pk_mul_f32 v[26:27], v[26:27], v[34:35]
	v_pk_mul_f32 v[28:29], v[28:29], v[36:37]
	v_pk_mul_f32 v[30:31], v[30:31], v[38:39]
	v_cvt_pk_bf16_f32 v24, v24, v25
	v_cvt_pk_bf16_f32 v25, v26, v27
	v_cvt_pk_bf16_f32 v26, v28, v29
	v_cvt_pk_bf16_f32 v27, v30, v31
	global_store_dwordx4 v[48:49], v[24:27], off
	v_add_u32_e32 v38, 0xb0, v140
	v_ashrrev_i32_e32 v39, 31, v38
	v_lshl_add_u64 v[24:25], s[36:37], 0, v[38:39]
	v_mad_u64_u32 v[40:41], s[36:37], v24, s42, v[142:143]
	v_lshl_add_u64 v[42:43], v[46:47], 0, v[136:137]
	v_mad_i32_i24 v41, v25, s42, v41
	v_lshl_add_u64 v[42:43], v[42:43], 0, s[34:35]
	v_lshl_add_u64 v[24:25], v[40:41], 0, v[138:139]
	v_lshl_add_u64 v[40:41], v[42:43], 0, v[132:133]
	s_waitcnt vmcnt(6)
; DI float bflo(unsigned w) { return __uint_as_float(w << 16); }
; DI float bfhi(unsigned w) { return __uint_as_float(w & 0xffff0000u); }
; DI float gelu_tanh(float y) { const float u = 0.7978845608028654f * (y + 0.044715f * y * y * y); return y * __builtin_amdgcn_rcpf(1.0f + __builtin_amdgcn_exp2f(-2.0f * 1.4426950408889634f * u)); }
; #define EPI_ROWS(...) _Pragma("unroll") for (int ai = 0; ai < 2; ++ai) _Pragma("unroll") for (int m = 0; m < 4; ++m) { const int rr = ai * 128 + wr * 64 + m * 16 + fr; __VA_ARGS__ }
; #define EPI_COLS8(...) _Pragma("unroll") for (int bj = 0; bj < 2; ++bj) { const int cc = bj * 128 + wc * 32 + 8 * fq; const f32x4 v0 = acc[ai][bj][m][0], v1 = acc[ai][bj][m][1]; __VA_ARGS__ }
;     DI void operator()(const Acc& acc, int wr, int wc, int fr, int fq) const {
;         EPI_ROWS(const int chunk = row0 + rr; const bf16_t* ap = Ap + ((size_t)g * 2048 + chunk) * 384 + 128;
;             EPI_COLS8(const int r = cc >> 4, i = cc & 15; const u32x4 uw = *(const u32x4*)(ap + cc); const f32x4 d0 = *(const f32x4*)(dskip + g * 16 + i), d1 = *(const f32x4*)(dskip + g * 16 + i + 4);
;                 const float y0 = v0[0] + d0[0] * bflo(uw.x), y1 = v0[1] + d0[1] * bfhi(uw.x), y2 = v0[2] + d0[2] * bflo(uw.y), y3 = v0[3] + d0[3] * bfhi(uw.y);
;                 const float y4 = v1[0] + d1[0] * bflo(uw.z), y5 = v1[1] + d1[1] * bfhi(uw.z), y6 = v1[2] + d1[2] * bflo(uw.w), y7 = v1[3] + d1[3] * bfhi(uw.w);
;                 u32x4 w; w.x = pk2(gelu_tanh(y0), gelu_tanh(y1)); w.y = pk2(gelu_tanh(y2), gelu_tanh(y3)); w.z = pk2(gelu_tanh(y4), gelu_tanh(y5)); w.w = pk2(gelu_tanh(y6), gelu_tanh(y7));
;                 *(u32x4*)(z + ((size_t)chunk * 16 + r) * 512 + g * 16 + i) = w;))
	v_lshlrev_b32_e32 v42, 16, v202
	v_and_b32_e32 v43, 0xffff0000, v202
	v_lshlrev_b32_e32 v26, 16, v203
	v_and_b32_e32 v27, 0xffff0000, v203
	v_lshlrev_b32_e32 v44, 16, v204
	v_and_b32_e32 v45, 0xffff0000, v204
	v_lshlrev_b32_e32 v28, 16, v205
	v_and_b32_e32 v29, 0xffff0000, v205
	v_pk_fma_f32 v[16:17], v[238:239], v[42:43], v[16:17]
	v_pk_fma_f32 v[18:19], v[240:241], v[26:27], v[18:19]
	v_pk_fma_f32 v[20:21], v[242:243], v[44:45], v[20:21]
	v_pk_fma_f32 v[22:23], v[244:245], v[28:29], v[22:23]
	v_mul_f32_e32 v26, 0x3d372713, v16
	v_mul_f32_e32 v27, 0x3d372713, v17
	v_mul_f32_e32 v28, 0x3d372713, v18
	v_mul_f32_e32 v29, 0x3d372713, v19
	v_mul_f32_e32 v30, 0x3d372713, v20
	v_mul_f32_e32 v31, 0x3d372713, v21
	v_mul_f32_e32 v32, 0x3d372713, v22
	v_mul_f32_e32 v33, 0x3d372713, v23
	v_mul_f32_e32 v26, v16, v26
	v_mul_f32_e32 v27, v17, v27
	v_mul_f32_e32 v28, v18, v28
	v_mul_f32_e32 v29, v19, v29
	v_mul_f32_e32 v30, v20, v30
	v_mul_f32_e32 v31, v21, v31
	v_mul_f32_e32 v32, v22, v32
	v_mul_f32_e32 v33, v23, v33
	v_fma_f32 v26, v16, v26, v16
	v_fma_f32 v27, v17, v27, v17
	v_fma_f32 v28, v18, v28, v18
	v_fma_f32 v29, v19, v29, v19
	v_fma_f32 v30, v20, v30, v20
	v_fma_f32 v31, v21, v31, v21
	v_fma_f32 v32, v22, v32, v22
	v_fma_f32 v33, v23, v33, v23
	v_mul_f32_e32 v26, 0xc0135761, v26
	v_mul_f32_e32 v27, 0xc0135761, v27
	v_mul_f32_e32 v28, 0xc0135761, v28
	v_mul_f32_e32 v29, 0xc0135761, v29
	v_mul_f32_e32 v30, 0xc0135761, v30
	v_mul_f32_e32 v31, 0xc0135761, v31
	v_mul_f32_e32 v32, 0xc0135761, v32
	v_mul_f32_e32 v33, 0xc0135761, v33
	v_exp_f32_e32 v26, v26
	v_exp_f32_e32 v27, v27
	v_exp_f32_e32 v28, v28
	v_exp_f32_e32 v29, v29
	v_exp_f32_e32 v30, v30
	v_exp_f32_e32 v31, v31
	v_exp_f32_e32 v32, v32
	v_exp_f32_e32 v33, v33
	v_add_f32_e32 v26, 1.0, v26
	v_add_f32_e32 v27, 1.0, v27
	v_add_f32_e32 v28, 1.0, v28
	v_add_f32_e32 v29, 1.0, v29
	v_add_f32_e32 v30, 1.0, v30
	v_add_f32_e32 v31, 1.0, v31
	v_add_f32_e32 v32, 1.0, v32
	v_add_f32_e32 v33, 1.0, v33
	v_rcp_f32_e32 v26, v26
	v_rcp_f32_e32 v27, v27
	v_rcp_f32_e32 v28, v28
	v_rcp_f32_e32 v29, v29
	v_rcp_f32_e32 v30, v30
	v_rcp_f32_e32 v31, v31
	v_rcp_f32_e32 v32, v32
	v_rcp_f32_e32 v33, v33
	v_pk_mul_f32 v[16:17], v[16:17], v[26:27]
	v_pk_mul_f32 v[18:19], v[18:19], v[28:29]
	v_pk_mul_f32 v[20:21], v[20:21], v[30:31]
	v_pk_mul_f32 v[22:23], v[22:23], v[32:33]
	v_cvt_pk_bf16_f32 v16, v16, v17
	v_cvt_pk_bf16_f32 v17, v18, v19
	v_cvt_pk_bf16_f32 v18, v20, v21
	v_cvt_pk_bf16_f32 v19, v22, v23
	global_store_dwordx4 v[40:41], v[16:19], off
	v_lshlrev_b64 v[30:31], 14, v[38:39]
	v_lshl_add_u64 v[30:31], s[26:27], 0, v[30:31]
	v_lshl_add_u64 v[32:33], v[30:31], 0, v[134:135]
	v_lshl_add_u64 v[32:33], v[32:33], 0, s[34:35]
	v_lshl_add_u64 v[32:33], v[32:33], 0, v[132:133]
	s_waitcnt vmcnt(5)
; DI float bflo(unsigned w) { return __uint_as_float(w << 16); }
; DI float bfhi(unsigned w) { return __uint_as_float(w & 0xffff0000u); }
; DI float gelu_tanh(float y) { const float u = 0.7978845608028654f * (y + 0.044715f * y * y * y); return y * __builtin_amdgcn_rcpf(1.0f + __builtin_amdgcn_exp2f(-2.0f * 1.4426950408889634f * u)); }
; #define EPI_ROWS(...) _Pragma("unroll") for (int ai = 0; ai < 2; ++ai) _Pragma("unroll") for (int m = 0; m < 4; ++m) { const int rr = ai * 128 + wr * 64 + m * 16 + fr; __VA_ARGS__ }
; #define EPI_COLS8(...) _Pragma("unroll") for (int bj = 0; bj < 2; ++bj) { const int cc = bj * 128 + wc * 32 + 8 * fq; const f32x4 v0 = acc[ai][bj][m][0], v1 = acc[ai][bj][m][1]; __VA_ARGS__ }
;     DI void operator()(const Acc& acc, int wr, int wc, int fr, int fq) const {
;         EPI_ROWS(const int chunk = row0 + rr; const bf16_t* ap = Ap + ((size_t)g * 2048 + chunk) * 384 + 128;
;             EPI_COLS8(const int r = cc >> 4, i = cc & 15; const u32x4 uw = *(const u32x4*)(ap + cc); const f32x4 d0 = *(const f32x4*)(dskip + g * 16 + i), d1 = *(const f32x4*)(dskip + g * 16 + i + 4);
;                 const float y0 = v0[0] + d0[0] * bflo(uw.x), y1 = v0[1] + d0[1] * bfhi(uw.x), y2 = v0[2] + d0[2] * bflo(uw.y), y3 = v0[3] + d0[3] * bfhi(uw.y);
;                 const float y4 = v1[0] + d1[0] * bflo(uw.z), y5 = v1[1] + d1[1] * bfhi(uw.z), y6 = v1[2] + d1[2] * bflo(uw.w), y7 = v1[3] + d1[3] * bfhi(uw.w);
;                 u32x4 w; w.x = pk2(gelu_tanh(y0), gelu_tanh(y1)); w.y = pk2(gelu_tanh(y2), gelu_tanh(y3)); w.z = pk2(gelu_tanh(y4), gelu_tanh(y5)); w.w = pk2(gelu_tanh(y6), gelu_tanh(y7));
;                 *(u32x4*)(z + ((size_t)chunk * 16 + r) * 512 + g * 16 + i) = w;))
	v_lshlrev_b32_e32 v34, 16, v246
	v_and_b32_e32 v35, 0xffff0000, v246
	v_lshlrev_b32_e32 v16, 16, v247
	v_and_b32_e32 v17, 0xffff0000, v247
	v_lshlrev_b32_e32 v36, 16, v248
	v_and_b32_e32 v37, 0xffff0000, v248
	v_lshlrev_b32_e32 v18, 16, v249
	v_and_b32_e32 v19, 0xffff0000, v249
	v_pk_fma_f32 v[8:9], v[238:239], v[34:35], v[8:9]
	v_pk_fma_f32 v[10:11], v[240:241], v[16:17], v[10:11]
	v_pk_fma_f32 v[12:13], v[242:243], v[36:37], v[12:13]
	v_pk_fma_f32 v[14:15], v[244:245], v[18:19], v[14:15]
	v_mul_f32_e32 v16, 0x3d372713, v8
	v_mul_f32_e32 v17, 0x3d372713, v9
	v_mul_f32_e32 v18, 0x3d372713, v10
	v_mul_f32_e32 v19, 0x3d372713, v11
	v_mul_f32_e32 v20, 0x3d372713, v12
	v_mul_f32_e32 v21, 0x3d372713, v13
	v_mul_f32_e32 v22, 0x3d372713, v14
	v_mul_f32_e32 v23, 0x3d372713, v15
	v_mul_f32_e32 v16, v8, v16
	v_mul_f32_e32 v17, v9, v17
	v_mul_f32_e32 v18, v10, v18
	v_mul_f32_e32 v19, v11, v19
	v_mul_f32_e32 v20, v12, v20
	v_mul_f32_e32 v21, v13, v21
	v_mul_f32_e32 v22, v14, v22
	v_mul_f32_e32 v23, v15, v23
	v_fma_f32 v16, v8, v16, v8
	v_fma_f32 v17, v9, v17, v9
	v_fma_f32 v18, v10, v18, v10
	v_fma_f32 v19, v11, v19, v11
	v_fma_f32 v20, v12, v20, v12
	v_fma_f32 v21, v13, v21, v13
	v_fma_f32 v22, v14, v22, v14
	v_fma_f32 v23, v15, v23, v15
	v_mul_f32_e32 v16, 0xc0135761, v16
	v_mul_f32_e32 v17, 0xc0135761, v17
	v_mul_f32_e32 v18, 0xc0135761, v18
	v_mul_f32_e32 v19, 0xc0135761, v19
	v_mul_f32_e32 v20, 0xc0135761, v20
	v_mul_f32_e32 v21, 0xc0135761, v21
	v_mul_f32_e32 v22, 0xc0135761, v22
	v_mul_f32_e32 v23, 0xc0135761, v23
	v_exp_f32_e32 v16, v16
	v_exp_f32_e32 v17, v17
	v_exp_f32_e32 v18, v18
	v_exp_f32_e32 v19, v19
	v_exp_f32_e32 v20, v20
	v_exp_f32_e32 v21, v21
	v_exp_f32_e32 v22, v22
	v_exp_f32_e32 v23, v23
	v_add_f32_e32 v16, 1.0, v16
	v_add_f32_e32 v17, 1.0, v17
	v_add_f32_e32 v18, 1.0, v18
	v_add_f32_e32 v19, 1.0, v19
	v_add_f32_e32 v20, 1.0, v20
	v_add_f32_e32 v21, 1.0, v21
	v_add_f32_e32 v22, 1.0, v22
	v_add_f32_e32 v23, 1.0, v23
	v_rcp_f32_e32 v16, v16
	v_rcp_f32_e32 v17, v17
	v_rcp_f32_e32 v18, v18
	v_rcp_f32_e32 v19, v19
	v_rcp_f32_e32 v20, v20
	v_rcp_f32_e32 v21, v21
	v_rcp_f32_e32 v22, v22
	v_rcp_f32_e32 v23, v23
	v_pk_mul_f32 v[8:9], v[8:9], v[16:17]
	v_pk_mul_f32 v[10:11], v[10:11], v[18:19]
	v_pk_mul_f32 v[12:13], v[12:13], v[20:21]
	v_pk_mul_f32 v[14:15], v[14:15], v[22:23]
	v_cvt_pk_bf16_f32 v8, v8, v9
	v_cvt_pk_bf16_f32 v9, v10, v11
	v_cvt_pk_bf16_f32 v10, v12, v13
	v_cvt_pk_bf16_f32 v11, v14, v15
	global_store_dwordx4 v[32:33], v[8:11], off
	v_lshl_add_u64 v[20:21], v[30:31], 0, v[136:137]
	v_lshl_add_u64 v[20:21], v[20:21], 0, s[34:35]
	v_lshl_add_u64 v[20:21], v[20:21], 0, v[132:133]
	s_mov_b64 s[0:1], -1
	s_waitcnt vmcnt(4)
	v_lshlrev_b32_e32 v22, 16, v182
	v_and_b32_e32 v23, 0xffff0000, v182
	v_lshlrev_b32_e32 v8, 16, v183
	v_and_b32_e32 v9, 0xffff0000, v183
	v_lshlrev_b32_e32 v24, 16, v184
	v_and_b32_e32 v25, 0xffff0000, v184
	v_lshlrev_b32_e32 v10, 16, v185
	v_and_b32_e32 v11, 0xffff0000, v185
	v_pk_fma_f32 v[0:1], v[238:239], v[22:23], v[0:1]
	v_pk_fma_f32 v[2:3], v[240:241], v[8:9], v[2:3]
	v_pk_fma_f32 v[4:5], v[242:243], v[24:25], v[4:5]
	v_pk_fma_f32 v[6:7], v[244:245], v[10:11], v[6:7]
	v_mul_f32_e32 v8, 0x3d372713, v0
	v_mul_f32_e32 v9, 0x3d372713, v1
	v_mul_f32_e32 v10, 0x3d372713, v2
	v_mul_f32_e32 v11, 0x3d372713, v3
	v_mul_f32_e32 v12, 0x3d372713, v4
	v_mul_f32_e32 v13, 0x3d372713, v5
	v_mul_f32_e32 v14, 0x3d372713, v6
	v_mul_f32_e32 v15, 0x3d372713, v7
	v_mul_f32_e32 v8, v0, v8
	v_mul_f32_e32 v9, v1, v9
	v_mul_f32_e32 v10, v2, v10
	v_mul_f32_e32 v11, v3, v11
	v_mul_f32_e32 v12, v4, v12
	v_mul_f32_e32 v13, v5, v13
	v_mul_f32_e32 v14, v6, v14
	v_mul_f32_e32 v15, v7, v15
	v_fma_f32 v8, v0, v8, v0
	v_fma_f32 v9, v1, v9, v1
	v_fma_f32 v10, v2, v10, v2
	v_fma_f32 v11, v3, v11, v3
	v_fma_f32 v12, v4, v12, v4
	v_fma_f32 v13, v5, v13, v5
	v_fma_f32 v14, v6, v14, v6
	v_fma_f32 v15, v7, v15, v7
	v_mul_f32_e32 v8, 0xc0135761, v8
	v_mul_f32_e32 v9, 0xc0135761, v9
	v_mul_f32_e32 v10, 0xc0135761, v10
	v_mul_f32_e32 v11, 0xc0135761, v11
	v_mul_f32_e32 v12, 0xc0135761, v12
	v_mul_f32_e32 v13, 0xc0135761, v13
	v_mul_f32_e32 v14, 0xc0135761, v14
	v_mul_f32_e32 v15, 0xc0135761, v15
	v_exp_f32_e32 v8, v8
	v_exp_f32_e32 v9, v9
	v_exp_f32_e32 v10, v10
	v_exp_f32_e32 v11, v11
	v_exp_f32_e32 v12, v12
	v_exp_f32_e32 v13, v13
	v_exp_f32_e32 v14, v14
	v_exp_f32_e32 v15, v15
	v_add_f32_e32 v8, 1.0, v8
	v_add_f32_e32 v9, 1.0, v9
	v_add_f32_e32 v10, 1.0, v10
	v_add_f32_e32 v11, 1.0, v11
	v_add_f32_e32 v12, 1.0, v12
	v_add_f32_e32 v13, 1.0, v13
	v_add_f32_e32 v14, 1.0, v14
	v_add_f32_e32 v15, 1.0, v15
	v_rcp_f32_e32 v8, v8
	v_rcp_f32_e32 v9, v9
	v_rcp_f32_e32 v10, v10
	v_rcp_f32_e32 v11, v11
	v_rcp_f32_e32 v12, v12
	v_rcp_f32_e32 v13, v13
	v_rcp_f32_e32 v14, v14
	v_rcp_f32_e32 v15, v15
	v_pk_mul_f32 v[0:1], v[0:1], v[8:9]
	v_pk_mul_f32 v[2:3], v[2:3], v[10:11]
	v_pk_mul_f32 v[4:5], v[4:5], v[12:13]
	v_pk_mul_f32 v[6:7], v[6:7], v[14:15]
	v_cvt_pk_bf16_f32 v0, v0, v1
	v_cvt_pk_bf16_f32 v1, v2, v3
	v_cvt_pk_bf16_f32 v2, v4, v5
	v_cvt_pk_bf16_f32 v3, v6, v7
	global_store_dwordx4 v[20:21], v[0:3], off
	s_cbranch_vccnz .LBB0_788
	s_and_b64 vcc, exec, s[6:7]
	s_cbranch_vccnz .LBB0_787
	s_barrier
	s_branch .LBB0_787
